# EpiRes row-stat atomics: sum and sum-of-squares merged into one 32-lane atomic per row group (out-proj and FFN-down epilogues)
# baseline (speedup 1.0000x reference)
; #define PG8_LAS __attribute__((address_space(3)))
; __device__ __forceinline__ void ln_row_lds(const PG8_LAS unsigned char* ev, int rl, float& rA, float& rB) {
;     __device__ __forceinline__ void operator()(const f32x4 (&acc)[2][2][4][2], const Unit& u, int wr, int wc, int fr, int fq, int rowmask, const PG8_LAS unsigned char* ev) const {
;     ...
;         const unsigned zoff0 = (unsigned)(row0 * 1024 + gcol0) * 2u;
;         u32x4 zpre[2][4][2];
; #pragma unroll
;         for (int ai = 0; ai < 2; ++ai)
; #pragma unroll
;             for (int m = 0; m < 4; ++m)
; #pragma unroll
;                 for (int bj = 0; bj < 2; ++bj) zpre[ai][m][bj] = ((rowmask >> (ai * 4 + m)) & 1) ? *(const u32x4*)((const char*)Zres + (zoff0 + (unsigned)((ai * HALF + m * 16) * 2048 + bj * HALF * 2))) : (u32x4){0u, 0u, 0u, 0u};
; #pragma unroll
;         for (int ai = 0; ai < 2; ++ai) {
; #pragma unroll
;             for (int m = 0; m < 4; ++m) { if (!((rowmask >> (ai * 4 + m)) & 1)) continue; const int row = row0 + ai * HALF + m * 16; float rA, rB; ln_row_lds(ev, wr * 64 + fr + ai * HALF + m * 16, rA, rB);
;                 float s = 0.f, q = 0.f;
; #pragma unroll
;                 for (int bj = 0; bj < 2; ++bj) { const u32x4 zr = zpre[ai][m][bj];
;                     f32x4 x0 = {bf_lo(zr.x), bf_hi(zr.x), bf_lo(zr.y), bf_hi(zr.y)}, x1 = {bf_lo(zr.z), bf_hi(zr.z), bf_lo(zr.w), bf_hi(zr.w)};
;                     const PG8_LAS f32x4* kp = (const PG8_LAS f32x4*)(ev + 2048 + (wc * 32 + 8 * fq + bj * HALF) * 4);
;                     f32x4 z0 = ((x0 * rA + rB) * kp[0] + kp[64]) * ALPHA_ + acc[ai][bj][m][0], z1 = ((x1 * rA + rB) * kp[1] + kp[65]) * ALPHA_ + acc[ai][bj][m][1];
;                     if (F32OUT) { if (row < MP_ + NSMP_) { float* p = Fout + (size_t)row * 1024 + gcol0 + bj * HALF; *(f32x4*)p = z0; *(f32x4*)(p + 4) = z1; } }
;                     else { const u32x4 w = pack8(z0, z1); st16_sel(Zout + (size_t)row * 1024 + gcol0 + bj * HALF, w, (rowmask & 0x200) != 0);
;                         z0 = (f32x4){bf_lo(w.x), bf_hi(w.x), bf_lo(w.y), bf_hi(w.y)}; z1 = (f32x4){bf_lo(w.z), bf_hi(w.z), bf_lo(w.w), bf_hi(w.w)}; }
;                     s += (z0[0] + z0[1]) + (z0[2] + z0[3]) + (z1[0] + z1[1]) + (z1[2] + z1[3]);
;                     q += (z0[0] * z0[0] + z0[1] * z0[1]) + (z0[2] * z0[2] + z0[3] * z0[3]) + (z1[0] * z1[0] + z1[1] * z1[1]) + (z1[2] * z1[2] + z1[3] * z1[3]); }
.LBB0_985:
	v_lshl_or_b32 v210, s34, 8, v224
	v_lshl_add_u32 v212, s26, 8, v223
	v_lshlrev_b32_e32 v0, 1, v210
	v_lshl_add_u32 v0, v212, 11, v0
	global_load_dwordx4 v[232:235], v0, s[70:71]
	v_or_b32_e32 v50, 0x100, v0
	global_load_dwordx4 v[186:189], v50, s[70:71]
	v_add_u32_e32 v50, 0x8000, v0
	global_load_dwordx4 v[182:185], v50, s[70:71]
	v_add_u32_e32 v50, 0x8100, v0
	global_load_dwordx4 v[178:181], v50, s[70:71]
	v_add_u32_e32 v50, 0x10000, v0
	global_load_dwordx4 v[174:177], v50, s[70:71]
	v_add_u32_e32 v50, 0x10100, v0
	global_load_dwordx4 v[162:165], v50, s[70:71]
	v_add_u32_e32 v50, 0x18000, v0
	global_load_dwordx4 v[158:161], v50, s[70:71]
	v_add_u32_e32 v50, 0x18100, v0
	global_load_dwordx4 v[146:149], v50, s[70:71]
	v_add_u32_e32 v50, 0x40000, v0
	global_load_dwordx4 v[138:141], v50, s[70:71]
	v_add_u32_e32 v50, 0x40100, v0
	global_load_dwordx4 v[122:125], v50, s[70:71]
	v_add_u32_e32 v50, 0x48000, v0
	global_load_dwordx4 v[114:117], v50, s[70:71]
	v_add_u32_e32 v50, 0x48100, v0
	global_load_dwordx4 v[98:101], v50, s[70:71]
	v_add_u32_e32 v50, 0x50000, v0
	global_load_dwordx4 v[90:93], v50, s[70:71]
	v_add_u32_e32 v50, 0x50100, v0
	global_load_dwordx4 v[74:77], v50, s[70:71]
	v_add_u32_e32 v50, 0x58000, v0
	v_add_u32_e32 v0, 0x58100, v0
	global_load_dwordx4 v[62:65], v50, s[70:71]
	s_lshl_b32 s0, s27, 12
	global_load_dwordx4 v[50:53], v0, s[70:71]
	s_and_b32 s0, s0, 0x1000
	s_add_i32 s0, s0, 0
	s_add_i32 s0, s0, 0x20400
	v_add_u32_e32 v230, s0, v225
	ds_read_b64 v[236:237], v230
	v_add_u32_e32 v229, s0, v226
	v_ashrrev_i32_e32 v213, 31, v212
	v_lshlrev_b64 v[244:245], 11, v[212:213]
	v_ashrrev_i32_e32 v211, 31, v210
	s_waitcnt lgkmcnt(0)
	v_pk_mul_f32 v[236:237], v[236:237], s[6:7] op_sel_hi:[1,0]
	s_waitcnt vmcnt(15)
	v_lshlrev_b32_e32 v246, 16, v234
	v_fma_f32 v0, -v236, v236, v237
	v_max_f32_e32 v0, 0, v0
	v_add_f32_e32 v0, 0x3727c5ac, v0
	v_rsq_f32_e32 v0, v0
	v_and_b32_e32 v237, 0xffff0000, v232
	v_and_b32_e32 v247, 0xffff0000, v234
	v_lshlrev_b32_e32 v248, 16, v235
	v_mul_f32_e64 v214, v236, -v0
	v_lshlrev_b32_e32 v236, 16, v232
	v_lshlrev_b32_e32 v232, 16, v233
	v_and_b32_e32 v233, 0xffff0000, v233
	v_and_b32_e32 v249, 0xffff0000, v235
	v_pk_fma_f32 v[216:217], v[0:1], v[232:233], v[214:215] op_sel_hi:[0,1,0]
	v_pk_fma_f32 v[190:191], v[0:1], v[236:237], v[214:215] op_sel_hi:[0,1,0]
	ds_read_b128 v[232:235], v229 offset:2048
	ds_read_b128 v[236:239], v229 offset:2064
	ds_read_b128 v[240:243], v229 offset:3072
	s_waitcnt lgkmcnt(0)
	v_pk_fma_f32 v[190:191], v[232:233], v[190:191], v[240:241]
	v_pk_fma_f32 v[216:217], v[234:235], v[216:217], v[242:243]
	v_pk_fma_f32 v[190:191], v[190:191], s[8:9], v[170:171] op_sel_hi:[1,0,1]
	v_pk_fma_f32 v[216:217], v[216:217], s[8:9], v[172:173] op_sel_hi:[1,0,1]
	ds_read_b128 v[170:173], v229 offset:3088
	v_pk_fma_f32 v[232:233], v[0:1], v[248:249], v[214:215] op_sel_hi:[0,1,0]
	v_pk_fma_f32 v[234:235], v[0:1], v[246:247], v[214:215] op_sel_hi:[0,1,0]
	s_waitcnt lgkmcnt(0)
	v_pk_fma_f32 v[170:171], v[236:237], v[234:235], v[170:171]
	v_pk_fma_f32 v[172:173], v[238:239], v[232:233], v[172:173]
	s_nop 0
	v_pk_fma_f32 v[172:173], v[172:173], s[8:9], v[168:169] op_sel_hi:[1,0,1]
	v_pk_fma_f32 v[168:169], v[170:171], s[8:9], v[166:167] op_sel_hi:[1,0,1]
	v_lshl_add_u64 v[170:171], s[72:73], 0, v[244:245]
	v_cvt_pk_bf16_f32 v166, v190, v191
	v_cvt_pk_bf16_f32 v167, v216, v217
	v_lshl_add_u64 v[170:171], v[210:211], 1, v[170:171]
	v_cvt_pk_bf16_f32 v168, v168, v169
	v_cvt_pk_bf16_f32 v169, v172, v173
	global_store_dwordx4 v[170:171], v[166:169], off
	v_lshlrev_b32_e32 v172, 16, v166
	v_lshlrev_b32_e32 v173, 16, v167
	v_and_b32_e32 v166, 0xffff0000, v166
	v_and_b32_e32 v167, 0xffff0000, v167
	v_add_f32_e32 v216, v172, v166
	v_add_f32_e32 v217, v173, v167
	v_mul_f32_e32 v166, v166, v166
	v_mul_f32_e32 v167, v167, v167
	v_lshlrev_b32_e32 v190, 16, v168
	v_and_b32_e32 v168, 0xffff0000, v168
	v_fmac_f32_e32 v166, v172, v172
	v_fmac_f32_e32 v167, v173, v173
	v_add_f32_e32 v166, v166, v167
	v_mul_f32_e32 v167, v168, v168
	v_lshlrev_b32_e32 v191, 16, v169
	v_and_b32_e32 v169, 0xffff0000, v169
	v_fmac_f32_e32 v167, v190, v190
	v_add_f32_e32 v216, v216, v217
	v_add_f32_e32 v217, v190, v168
	v_add_f32_e32 v166, v166, v167
	v_mul_f32_e32 v167, v169, v169
	v_add_f32_e32 v216, v216, v217
	v_add_f32_e32 v217, v191, v169
	v_fmac_f32_e32 v167, v191, v191
	v_add_f32_e32 v216, v216, v217
	v_add_f32_e32 v238, v166, v167
	s_waitcnt vmcnt(15)
	v_lshlrev_b32_e32 v166, 16, v186
	v_and_b32_e32 v167, 0xffff0000, v186
	v_lshlrev_b32_e32 v168, 16, v187
	v_and_b32_e32 v169, 0xffff0000, v187
	v_add_f32_e32 v231, 0, v216
	v_lshlrev_b32_e32 v172, 16, v188
	v_and_b32_e32 v173, 0xffff0000, v188
	v_lshlrev_b32_e32 v190, 16, v189
	v_and_b32_e32 v191, 0xffff0000, v189
	v_pk_fma_f32 v[216:217], v[0:1], v[168:169], v[214:215] op_sel_hi:[0,1,0]
	v_pk_fma_f32 v[236:237], v[0:1], v[166:167], v[214:215] op_sel_hi:[0,1,0]
	ds_read_b128 v[166:169], v229 offset:2560
	ds_read_b128 v[186:189], v229 offset:2576
	ds_read_b128 v[232:235], v229 offset:3584
	v_pk_fma_f32 v[190:191], v[0:1], v[190:191], v[214:215] op_sel_hi:[0,1,0]
	v_pk_fma_f32 v[172:173], v[0:1], v[172:173], v[214:215] op_sel_hi:[0,1,0]
	s_waitcnt lgkmcnt(0)
	v_pk_fma_f32 v[166:167], v[166:167], v[236:237], v[232:233]
	v_pk_fma_f32 v[168:169], v[168:169], v[216:217], v[234:235]
	v_pk_fma_f32 v[166:167], v[166:167], s[8:9], v[154:155] op_sel_hi:[1,0,1]
	v_pk_fma_f32 v[168:169], v[168:169], s[8:9], v[156:157] op_sel_hi:[1,0,1]
	ds_read_b128 v[154:157], v229 offset:3600
	s_waitcnt lgkmcnt(0)
; #define PG8_LAS __attribute__((address_space(3)))
; __device__ __forceinline__ float bf_lo(unsigned w) { return __uint_as_float(w << 16); }
; __device__ __forceinline__ float bf_hi(unsigned w) { return __uint_as_float(w & 0xffff0000u); }
; __device__ __forceinline__ void st16_sel(void* p, u32x4 v, bool wt) { if (wt) st16_wt_e(p, v); else *(u32x4*)p = v; }
;     __device__ __forceinline__ void operator()(const f32x4 (&acc)[2][2][4][2], const Unit& u, int wr, int wc, int fr, int fq, int rowmask, const PG8_LAS unsigned char* ev) const {
;     ...
;             for (int m = 0; m < 4; ++m) { if (!((rowmask >> (ai * 4 + m)) & 1)) continue; const int row = row0 + ai * HALF + m * 16; float rA, rB; ln_row_lds(ev, wr * 64 + fr + ai * HALF + m * 16, rA, rB);
;                 float s = 0.f, q = 0.f;
; #pragma unroll
;                 for (int bj = 0; bj < 2; ++bj) { const u32x4 zr = zpre[ai][m][bj];
;                     f32x4 x0 = {bf_lo(zr.x), bf_hi(zr.x), bf_lo(zr.y), bf_hi(zr.y)}, x1 = {bf_lo(zr.z), bf_hi(zr.z), bf_lo(zr.w), bf_hi(zr.w)};
;                     const PG8_LAS f32x4* kp = (const PG8_LAS f32x4*)(ev + 2048 + (wc * 32 + 8 * fq + bj * HALF) * 4);
;                     f32x4 z0 = ((x0 * rA + rB) * kp[0] + kp[64]) * ALPHA_ + acc[ai][bj][m][0], z1 = ((x1 * rA + rB) * kp[1] + kp[65]) * ALPHA_ + acc[ai][bj][m][1];
;                     if (F32OUT) { if (row < MP_ + NSMP_) { float* p = Fout + (size_t)row * 1024 + gcol0 + bj * HALF; *(f32x4*)p = z0; *(f32x4*)(p + 4) = z1; } }
;                     else { const u32x4 w = pack8(z0, z1); st16_sel(Zout + (size_t)row * 1024 + gcol0 + bj * HALF, w, (rowmask & 0x200) != 0);
;                         z0 = (f32x4){bf_lo(w.x), bf_hi(w.x), bf_lo(w.y), bf_hi(w.y)}; z1 = (f32x4){bf_lo(w.z), bf_hi(w.z), bf_lo(w.w), bf_hi(w.w)}; }
;                     s += (z0[0] + z0[1]) + (z0[2] + z0[3]) + (z1[0] + z1[1]) + (z1[2] + z1[3]);
;                     q += (z0[0] * z0[0] + z0[1] * z0[1]) + (z0[2] * z0[2] + z0[3] * z0[3]) + (z1[0] * z1[0] + z1[1] * z1[1]) + (z1[2] * z1[2] + z1[3] * z1[3]); }
;                 s += __shfl_xor(s, 16); s += __shfl_xor(s, 32); q += __shfl_xor(q, 16); q += __shfl_xor(q, 32);
;                 if (fq == 0) { atomicAdd(stats_out + 2 * (size_t)row, s); atomicAdd(stats_out + 2 * (size_t)row + 1, q); } } }
	v_pk_fma_f32 v[154:155], v[172:173], v[186:187], v[154:155]
	v_pk_fma_f32 v[156:157], v[190:191], v[188:189], v[156:157]
	s_nop 0
	v_pk_fma_f32 v[156:157], v[156:157], s[8:9], v[152:153] op_sel_hi:[1,0,1]
	v_pk_fma_f32 v[152:153], v[154:155], s[8:9], v[150:151] op_sel_hi:[1,0,1]
	v_cvt_pk_bf16_f32 v150, v166, v167
	v_cvt_pk_bf16_f32 v151, v168, v169
	s_nop 0
	v_cvt_pk_bf16_f32 v152, v152, v153
	v_cvt_pk_bf16_f32 v153, v156, v157
	global_store_dwordx4 v[170:171], v[150:153], off offset:256
	v_lshlrev_b32_e32 v0, 16, v150
	v_lshlrev_b32_e32 v154, 16, v151
	v_and_b32_e32 v150, 0xffff0000, v150
	v_and_b32_e32 v151, 0xffff0000, v151
	v_add_f32_e32 v157, v0, v150
	v_mul_f32_e32 v150, v150, v150
	v_fmac_f32_e32 v150, v0, v0
	v_mul_f32_e32 v0, v151, v151
	v_lshlrev_b32_e32 v155, 16, v152
	v_and_b32_e32 v152, 0xffff0000, v152
	v_fmac_f32_e32 v0, v154, v154
	v_add_f32_e32 v0, v150, v0
	v_mul_f32_e32 v150, v152, v152
	v_lshlrev_b32_e32 v156, 16, v153
	v_and_b32_e32 v153, 0xffff0000, v153
	v_fmac_f32_e32 v150, v155, v155
	v_add_f32_e32 v0, v0, v150
	v_mul_f32_e32 v150, v153, v153
	v_fmac_f32_e32 v150, v156, v156
	v_add_f32_e32 v166, v154, v151
	v_add_f32_e32 v0, v0, v150
	v_and_b32_e32 v150, 64, v221
	v_add_f32_e32 v157, v157, v166
	v_add_f32_e32 v166, v155, v152
	v_add_f32_e32 v151, v238, v0
	v_xor_b32_e32 v0, 16, v221
	v_add_u32_e32 v150, 64, v150
	v_add_f32_e32 v157, v157, v166
	v_add_f32_e32 v166, v156, v153
	v_cmp_lt_i32_e32 vcc, v0, v150
	v_add_f32_e32 v157, v157, v166
	v_xor_b32_e32 v152, 32, v221
	v_cndmask_b32_e32 v0, v221, v0, vcc
	v_add_f32_e32 v157, v231, v157
	v_lshlrev_b32_e32 v153, 2, v0
	v_cmp_lt_i32_e32 vcc, v152, v150
	ds_bpermute_b32 v0, v153, v157
	s_waitcnt lgkmcnt(0)
	v_add_f32_e32 v0, v157, v0
	v_cndmask_b32_e32 v150, v221, v152, vcc
	ds_bpermute_b32 v152, v153, v151
	v_lshlrev_b32_e32 v154, 2, v150
	ds_bpermute_b32 v150, v154, v0
	s_waitcnt lgkmcnt(1)
	v_add_f32_e32 v151, v151, v152
	ds_bpermute_b32 v152, v154, v151
	s_mov_b32 s26, -1
	s_mov_b32 s27, 0
	s_and_saveexec_b64 s[26:27], s[26:27]
	s_mov_b32 s96, 0x11000
	s_mov_b64 s[84:85], 0x100
	s_cbranch_execz .LBB0_987
	v_lshl_add_u64 v[156:157], v[212:213], 3, s[28:29]
	s_waitcnt lgkmcnt(1)
	v_add_f32_e32 v0, v0, v150
	s_waitcnt lgkmcnt(0)
	v_add_f32_e32 v150, v151, v152
	v_cndmask_b32_e64 v152, 4, 0, s[10:11]
	v_cndmask_b32_e64 v0, v150, v0, s[10:11]
	v_or_b32_e32 v156, v156, v152
	global_atomic_add_f32 v[156:157], v0, off
.LBB0_987:
	s_or_b64 exec, exec, s[26:27]
	ds_read_b64 v[156:157], v230 offset:128
	s_waitcnt vmcnt(15)
	v_lshlrev_b32_e32 v166, 16, v182
	v_and_b32_e32 v167, 0xffff0000, v182
	v_lshlrev_b32_e32 v168, 16, v183
	v_and_b32_e32 v169, 0xffff0000, v183
	s_waitcnt lgkmcnt(0)
	v_pk_mul_f32 v[156:157], v[156:157], s[6:7] op_sel_hi:[1,0]
	v_lshlrev_b32_e32 v186, 16, v184
	v_fma_f32 v0, -v156, v156, v157
	v_max_f32_e32 v0, 0, v0
	v_add_f32_e32 v0, 0x3727c5ac, v0
	v_rsq_f32_e32 v0, v0
	v_and_b32_e32 v187, 0xffff0000, v184
	v_lshlrev_b32_e32 v188, 16, v185
	v_and_b32_e32 v189, 0xffff0000, v185
	v_mul_f32_e64 v152, v156, -v0
	v_pk_fma_f32 v[190:191], v[0:1], v[168:169], v[152:153] op_sel_hi:[0,1,0]
	v_pk_fma_f32 v[216:217], v[0:1], v[166:167], v[152:153] op_sel_hi:[0,1,0]
	ds_read_b128 v[166:169], v229 offset:2048
	ds_read_b128 v[170:173], v229 offset:2064
	ds_read_b128 v[182:185], v229 offset:3072
	v_or_b32_e32 v150, 16, v212
	v_ashrrev_i32_e32 v151, 31, v150
	v_lshlrev_b64 v[156:157], 11, v[150:151]
	s_waitcnt lgkmcnt(0)
	v_pk_fma_f32 v[166:167], v[166:167], v[216:217], v[182:183]
	v_pk_fma_f32 v[168:169], v[168:169], v[190:191], v[184:185]
	v_pk_fma_f32 v[166:167], v[166:167], s[8:9], v[142:143] op_sel_hi:[1,0,1]
	v_pk_fma_f32 v[168:169], v[168:169], s[8:9], v[144:145] op_sel_hi:[1,0,1]
	ds_read_b128 v[142:145], v229 offset:3088
	v_pk_fma_f32 v[182:183], v[0:1], v[188:189], v[152:153] op_sel_hi:[0,1,0]
	v_pk_fma_f32 v[184:185], v[0:1], v[186:187], v[152:153] op_sel_hi:[0,1,0]
	s_waitcnt lgkmcnt(0)
	v_pk_fma_f32 v[142:143], v[170:171], v[184:185], v[142:143]
	v_pk_fma_f32 v[144:145], v[172:173], v[182:183], v[144:145]
	s_waitcnt vmcnt(14)
	v_lshlrev_b32_e32 v170, 16, v180
	v_pk_fma_f32 v[144:145], v[144:145], s[8:9], v[136:137] op_sel_hi:[1,0,1]
	v_pk_fma_f32 v[136:137], v[142:143], s[8:9], v[134:135] op_sel_hi:[1,0,1]
	v_lshl_add_u64 v[142:143], s[72:73], 0, v[156:157]
	v_cvt_pk_bf16_f32 v134, v166, v167
	v_cvt_pk_bf16_f32 v135, v168, v169
	v_lshl_add_u64 v[156:157], v[210:211], 1, v[142:143]
	v_cvt_pk_bf16_f32 v136, v136, v137
	v_cvt_pk_bf16_f32 v137, v144, v145
	global_store_dwordx4 v[156:157], v[134:137], off
	v_lshlrev_b32_e32 v142, 16, v134
	v_lshlrev_b32_e32 v143, 16, v135
	v_and_b32_e32 v134, 0xffff0000, v134
	v_and_b32_e32 v135, 0xffff0000, v135
	v_add_f32_e32 v155, v142, v134
	v_add_f32_e32 v166, v143, v135
	v_mul_f32_e32 v134, v134, v134
	v_mul_f32_e32 v135, v135, v135
	v_lshlrev_b32_e32 v144, 16, v136
	v_and_b32_e32 v136, 0xffff0000, v136
	v_fmac_f32_e32 v134, v142, v142
	v_fmac_f32_e32 v135, v143, v143
	v_add_f32_e32 v134, v134, v135
	v_mul_f32_e32 v135, v136, v136
	v_lshlrev_b32_e32 v145, 16, v137
	v_and_b32_e32 v137, 0xffff0000, v137
	v_fmac_f32_e32 v135, v144, v144
	v_add_f32_e32 v134, v134, v135
	v_mul_f32_e32 v135, v137, v137
	v_add_f32_e32 v155, v155, v166
	v_add_f32_e32 v166, v144, v136
	v_fmac_f32_e32 v135, v145, v145
	v_add_f32_e32 v155, v155, v166
	v_add_f32_e32 v166, v145, v137
	v_add_f32_e32 v182, v134, v135
	v_lshlrev_b32_e32 v134, 16, v178
	v_and_b32_e32 v135, 0xffff0000, v178
	v_lshlrev_b32_e32 v136, 16, v179
	v_and_b32_e32 v137, 0xffff0000, v179
	v_add_f32_e32 v155, v155, v166
	v_and_b32_e32 v171, 0xffff0000, v180
	v_lshlrev_b32_e32 v172, 16, v181
	v_and_b32_e32 v173, 0xffff0000, v181
	v_pk_fma_f32 v[178:179], v[0:1], v[136:137], v[152:153] op_sel_hi:[0,1,0]
	v_pk_fma_f32 v[180:181], v[0:1], v[134:135], v[152:153] op_sel_hi:[0,1,0]
	ds_read_b128 v[134:137], v229 offset:2560
	ds_read_b128 v[142:145], v229 offset:2576
	ds_read_b128 v[166:169], v229 offset:3584
	v_add_f32_e32 v155, 0, v155
	s_waitcnt lgkmcnt(0)
; #define PG8_LAS __attribute__((address_space(3)))
; __device__ __forceinline__ float bf_lo(unsigned w) { return __uint_as_float(w << 16); }
; __device__ __forceinline__ float bf_hi(unsigned w) { return __uint_as_float(w & 0xffff0000u); }
; __device__ __forceinline__ void st16_sel(void* p, u32x4 v, bool wt) { if (wt) st16_wt_e(p, v); else *(u32x4*)p = v; }
;     __device__ __forceinline__ void operator()(const f32x4 (&acc)[2][2][4][2], const Unit& u, int wr, int wc, int fr, int fq, int rowmask, const PG8_LAS unsigned char* ev) const {
;     ...
;             for (int m = 0; m < 4; ++m) { if (!((rowmask >> (ai * 4 + m)) & 1)) continue; const int row = row0 + ai * HALF + m * 16; float rA, rB; ln_row_lds(ev, wr * 64 + fr + ai * HALF + m * 16, rA, rB);
;                 float s = 0.f, q = 0.f;
; #pragma unroll
;                 for (int bj = 0; bj < 2; ++bj) { const u32x4 zr = zpre[ai][m][bj];
;                     f32x4 x0 = {bf_lo(zr.x), bf_hi(zr.x), bf_lo(zr.y), bf_hi(zr.y)}, x1 = {bf_lo(zr.z), bf_hi(zr.z), bf_lo(zr.w), bf_hi(zr.w)};
;                     const PG8_LAS f32x4* kp = (const PG8_LAS f32x4*)(ev + 2048 + (wc * 32 + 8 * fq + bj * HALF) * 4);
;                     f32x4 z0 = ((x0 * rA + rB) * kp[0] + kp[64]) * ALPHA_ + acc[ai][bj][m][0], z1 = ((x1 * rA + rB) * kp[1] + kp[65]) * ALPHA_ + acc[ai][bj][m][1];
;                     if (F32OUT) { if (row < MP_ + NSMP_) { float* p = Fout + (size_t)row * 1024 + gcol0 + bj * HALF; *(f32x4*)p = z0; *(f32x4*)(p + 4) = z1; } }
;                     else { const u32x4 w = pack8(z0, z1); st16_sel(Zout + (size_t)row * 1024 + gcol0 + bj * HALF, w, (rowmask & 0x200) != 0);
;                         z0 = (f32x4){bf_lo(w.x), bf_hi(w.x), bf_lo(w.y), bf_hi(w.y)}; z1 = (f32x4){bf_lo(w.z), bf_hi(w.z), bf_lo(w.w), bf_hi(w.w)}; }
;                     s += (z0[0] + z0[1]) + (z0[2] + z0[3]) + (z1[0] + z1[1]) + (z1[2] + z1[3]);
;                     q += (z0[0] * z0[0] + z0[1] * z0[1]) + (z0[2] * z0[2] + z0[3] * z0[3]) + (z1[0] * z1[0] + z1[1] * z1[1]) + (z1[2] * z1[2] + z1[3] * z1[3]); }
;                 s += __shfl_xor(s, 16); s += __shfl_xor(s, 32); q += __shfl_xor(q, 16); q += __shfl_xor(q, 32);
;                 if (fq == 0) { atomicAdd(stats_out + 2 * (size_t)row, s); atomicAdd(stats_out + 2 * (size_t)row + 1, q); } } }
	v_pk_fma_f32 v[134:135], v[134:135], v[180:181], v[166:167]
	v_pk_fma_f32 v[136:137], v[136:137], v[178:179], v[168:169]
	v_pk_fma_f32 v[134:135], v[134:135], s[8:9], v[130:131] op_sel_hi:[1,0,1]
	v_pk_fma_f32 v[136:137], v[136:137], s[8:9], v[132:133] op_sel_hi:[1,0,1]
	ds_read_b128 v[130:133], v229 offset:3600
	v_pk_fma_f32 v[166:167], v[0:1], v[172:173], v[152:153] op_sel_hi:[0,1,0]
	v_pk_fma_f32 v[168:169], v[0:1], v[170:171], v[152:153] op_sel_hi:[0,1,0]
	s_waitcnt lgkmcnt(0)
	v_pk_fma_f32 v[130:131], v[168:169], v[142:143], v[130:131]
	v_pk_fma_f32 v[132:133], v[166:167], v[144:145], v[132:133]
	s_nop 0
	v_pk_fma_f32 v[132:133], v[132:133], s[8:9], v[128:129] op_sel_hi:[1,0,1]
	v_pk_fma_f32 v[128:129], v[130:131], s[8:9], v[126:127] op_sel_hi:[1,0,1]
	v_cvt_pk_bf16_f32 v126, v134, v135
	v_cvt_pk_bf16_f32 v127, v136, v137
	s_nop 0
	v_cvt_pk_bf16_f32 v128, v128, v129
	v_cvt_pk_bf16_f32 v129, v132, v133
	global_store_dwordx4 v[156:157], v[126:129], off offset:256
	v_lshlrev_b32_e32 v0, 16, v126
	v_lshlrev_b32_e32 v130, 16, v127
	v_and_b32_e32 v126, 0xffff0000, v126
	v_and_b32_e32 v127, 0xffff0000, v127
	v_add_f32_e32 v133, v0, v126
	v_mul_f32_e32 v126, v126, v126
	v_fmac_f32_e32 v126, v0, v0
	v_mul_f32_e32 v0, v127, v127
	v_lshlrev_b32_e32 v131, 16, v128
	v_and_b32_e32 v128, 0xffff0000, v128
	v_fmac_f32_e32 v0, v130, v130
	v_add_f32_e32 v0, v126, v0
	v_mul_f32_e32 v126, v128, v128
	v_lshlrev_b32_e32 v132, 16, v129
	v_and_b32_e32 v129, 0xffff0000, v129
	v_add_f32_e32 v134, v130, v127
	v_fmac_f32_e32 v126, v131, v131
	v_add_f32_e32 v133, v133, v134
	v_add_f32_e32 v134, v131, v128
	v_add_f32_e32 v0, v0, v126
	v_mul_f32_e32 v126, v129, v129
	v_add_f32_e32 v133, v133, v134
	v_add_f32_e32 v134, v132, v129
	v_fmac_f32_e32 v126, v132, v132
	v_add_f32_e32 v133, v133, v134
	v_add_f32_e32 v0, v0, v126
	v_add_f32_e32 v133, v155, v133
	v_add_f32_e32 v127, v182, v0
	ds_bpermute_b32 v0, v153, v133
	ds_bpermute_b32 v128, v153, v127
	s_waitcnt lgkmcnt(1)
	v_add_f32_e32 v0, v133, v0
	s_waitcnt lgkmcnt(0)
	v_add_f32_e32 v127, v127, v128
	ds_bpermute_b32 v126, v154, v0
	ds_bpermute_b32 v128, v154, v127
	s_mov_b32 s26, -1
	s_mov_b32 s27, 0
	s_and_saveexec_b64 s[26:27], s[26:27]
	s_cbranch_execz .LBB0_989
	v_lshl_add_u64 v[130:131], v[150:151], 3, s[28:29]
	s_waitcnt lgkmcnt(1)
	v_add_f32_e32 v0, v0, v126
	s_waitcnt lgkmcnt(0)
	v_add_f32_e32 v126, v127, v128
	v_cndmask_b32_e64 v128, 4, 0, s[10:11]
	v_cndmask_b32_e64 v0, v126, v0, s[10:11]
	v_or_b32_e32 v130, v130, v128
	global_atomic_add_f32 v[130:131], v0, off
.LBB0_989:
	s_or_b64 exec, exec, s[26:27]
	s_waitcnt lgkmcnt(0)
	ds_read_b64 v[128:129], v230 offset:256
	s_waitcnt vmcnt(15)
	v_lshlrev_b32_e32 v130, 16, v174
	v_and_b32_e32 v131, 0xffff0000, v174
	v_lshlrev_b32_e32 v132, 16, v175
	v_and_b32_e32 v133, 0xffff0000, v175
	s_waitcnt lgkmcnt(0)
	v_pk_mul_f32 v[128:129], v[128:129], s[6:7] op_sel_hi:[1,0]
	v_or_b32_e32 v126, 32, v212
	v_fma_f32 v0, -v128, v128, v129
	v_max_f32_e32 v0, 0, v0
	v_add_f32_e32 v0, 0x3727c5ac, v0
	v_rsq_f32_e32 v0, v0
	v_lshlrev_b32_e32 v156, 16, v176
	v_and_b32_e32 v157, 0xffff0000, v176
	v_lshlrev_b32_e32 v166, 16, v177
	v_mul_f32_e64 v128, v128, -v0
	v_pk_fma_f32 v[168:169], v[0:1], v[132:133], v[128:129] op_sel_hi:[0,1,0]
	v_pk_fma_f32 v[170:171], v[0:1], v[130:131], v[128:129] op_sel_hi:[0,1,0]
	ds_read_b128 v[130:133], v229 offset:2048
	ds_read_b128 v[134:137], v229 offset:2064
	ds_read_b128 v[142:145], v229 offset:3072
	v_and_b32_e32 v167, 0xffff0000, v177
	v_ashrrev_i32_e32 v127, 31, v126
	v_lshlrev_b64 v[150:151], 11, v[126:127]
	s_waitcnt lgkmcnt(0)
	v_pk_fma_f32 v[130:131], v[130:131], v[170:171], v[142:143]
	v_pk_fma_f32 v[132:133], v[132:133], v[168:169], v[144:145]
	v_pk_fma_f32 v[130:131], v[130:131], s[8:9], v[118:119] op_sel_hi:[1,0,1]
	v_pk_fma_f32 v[132:133], v[132:133], s[8:9], v[120:121] op_sel_hi:[1,0,1]
	ds_read_b128 v[118:121], v229 offset:3088
	v_pk_fma_f32 v[142:143], v[0:1], v[166:167], v[128:129] op_sel_hi:[0,1,0]
	v_pk_fma_f32 v[144:145], v[0:1], v[156:157], v[128:129] op_sel_hi:[0,1,0]
	s_waitcnt lgkmcnt(0)
	v_pk_fma_f32 v[118:119], v[134:135], v[144:145], v[118:119]
	v_pk_fma_f32 v[120:121], v[136:137], v[142:143], v[120:121]
	s_waitcnt vmcnt(14)
	v_lshlrev_b32_e32 v136, 16, v164
	v_pk_fma_f32 v[120:121], v[120:121], s[8:9], v[112:113] op_sel_hi:[1,0,1]
	v_pk_fma_f32 v[112:113], v[118:119], s[8:9], v[110:111] op_sel_hi:[1,0,1]
	v_lshl_add_u64 v[118:119], s[72:73], 0, v[150:151]
	v_cvt_pk_bf16_f32 v110, v130, v131
	v_cvt_pk_bf16_f32 v111, v132, v133
	v_lshl_add_u64 v[134:135], v[210:211], 1, v[118:119]
	v_cvt_pk_bf16_f32 v112, v112, v113
	v_cvt_pk_bf16_f32 v113, v120, v121
	global_store_dwordx4 v[134:135], v[110:113], off
	v_lshlrev_b32_e32 v118, 16, v110
	v_lshlrev_b32_e32 v119, 16, v111
	v_and_b32_e32 v110, 0xffff0000, v110
	v_and_b32_e32 v111, 0xffff0000, v111
	v_add_f32_e32 v129, v118, v110
	v_add_f32_e32 v130, v119, v111
	v_mul_f32_e32 v110, v110, v110
	v_mul_f32_e32 v111, v111, v111
	v_lshlrev_b32_e32 v120, 16, v112
	v_and_b32_e32 v112, 0xffff0000, v112
	v_fmac_f32_e32 v110, v118, v118
	v_fmac_f32_e32 v111, v119, v119
	v_add_f32_e32 v110, v110, v111
	v_mul_f32_e32 v111, v112, v112
	v_lshlrev_b32_e32 v121, 16, v113
	v_and_b32_e32 v113, 0xffff0000, v113
	v_fmac_f32_e32 v111, v120, v120
	v_add_f32_e32 v129, v129, v130
	v_add_f32_e32 v130, v120, v112
	v_add_f32_e32 v110, v110, v111
	v_mul_f32_e32 v111, v113, v113
	v_add_f32_e32 v129, v129, v130
	v_add_f32_e32 v130, v121, v113
	v_fmac_f32_e32 v111, v121, v121
	v_add_f32_e32 v129, v129, v130
	v_add_f32_e32 v155, v110, v111
	v_lshlrev_b32_e32 v110, 16, v162
	v_and_b32_e32 v111, 0xffff0000, v162
	v_lshlrev_b32_e32 v112, 16, v163
	v_and_b32_e32 v113, 0xffff0000, v163
	v_pk_fma_f32 v[144:145], v[0:1], v[112:113], v[128:129] op_sel_hi:[0,1,0]
	v_pk_fma_f32 v[150:151], v[0:1], v[110:111], v[128:129] op_sel_hi:[0,1,0]
	ds_read_b128 v[110:113], v229 offset:2560
	ds_read_b128 v[118:121], v229 offset:2576
	ds_read_b128 v[130:133], v229 offset:3584
	v_and_b32_e32 v137, 0xffff0000, v164
	v_lshlrev_b32_e32 v142, 16, v165
	v_and_b32_e32 v143, 0xffff0000, v165
	v_add_f32_e32 v152, 0, v129
	s_waitcnt lgkmcnt(0)
; #define PG8_LAS __attribute__((address_space(3)))
; __device__ __forceinline__ float bf_lo(unsigned w) { return __uint_as_float(w << 16); }
; __device__ __forceinline__ float bf_hi(unsigned w) { return __uint_as_float(w & 0xffff0000u); }
; __device__ __forceinline__ void st16_sel(void* p, u32x4 v, bool wt) { if (wt) st16_wt_e(p, v); else *(u32x4*)p = v; }
;     __device__ __forceinline__ void operator()(const f32x4 (&acc)[2][2][4][2], const Unit& u, int wr, int wc, int fr, int fq, int rowmask, const PG8_LAS unsigned char* ev) const {
;     ...
;             for (int m = 0; m < 4; ++m) { if (!((rowmask >> (ai * 4 + m)) & 1)) continue; const int row = row0 + ai * HALF + m * 16; float rA, rB; ln_row_lds(ev, wr * 64 + fr + ai * HALF + m * 16, rA, rB);
;                 float s = 0.f, q = 0.f;
; #pragma unroll
;                 for (int bj = 0; bj < 2; ++bj) { const u32x4 zr = zpre[ai][m][bj];
;                     f32x4 x0 = {bf_lo(zr.x), bf_hi(zr.x), bf_lo(zr.y), bf_hi(zr.y)}, x1 = {bf_lo(zr.z), bf_hi(zr.z), bf_lo(zr.w), bf_hi(zr.w)};
;                     const PG8_LAS f32x4* kp = (const PG8_LAS f32x4*)(ev + 2048 + (wc * 32 + 8 * fq + bj * HALF) * 4);
;                     f32x4 z0 = ((x0 * rA + rB) * kp[0] + kp[64]) * ALPHA_ + acc[ai][bj][m][0], z1 = ((x1 * rA + rB) * kp[1] + kp[65]) * ALPHA_ + acc[ai][bj][m][1];
;                     if (F32OUT) { if (row < MP_ + NSMP_) { float* p = Fout + (size_t)row * 1024 + gcol0 + bj * HALF; *(f32x4*)p = z0; *(f32x4*)(p + 4) = z1; } }
;                     else { const u32x4 w = pack8(z0, z1); st16_sel(Zout + (size_t)row * 1024 + gcol0 + bj * HALF, w, (rowmask & 0x200) != 0);
;                         z0 = (f32x4){bf_lo(w.x), bf_hi(w.x), bf_lo(w.y), bf_hi(w.y)}; z1 = (f32x4){bf_lo(w.z), bf_hi(w.z), bf_lo(w.w), bf_hi(w.w)}; }
;                     s += (z0[0] + z0[1]) + (z0[2] + z0[3]) + (z1[0] + z1[1]) + (z1[2] + z1[3]);
;                     q += (z0[0] * z0[0] + z0[1] * z0[1]) + (z0[2] * z0[2] + z0[3] * z0[3]) + (z1[0] * z1[0] + z1[1] * z1[1]) + (z1[2] * z1[2] + z1[3] * z1[3]); }
;                 s += __shfl_xor(s, 16); s += __shfl_xor(s, 32); q += __shfl_xor(q, 16); q += __shfl_xor(q, 32);
;                 if (fq == 0) { atomicAdd(stats_out + 2 * (size_t)row, s); atomicAdd(stats_out + 2 * (size_t)row + 1, q); } } }
	v_pk_fma_f32 v[110:111], v[110:111], v[150:151], v[130:131]
	v_pk_fma_f32 v[112:113], v[112:113], v[144:145], v[132:133]
	v_pk_fma_f32 v[110:111], v[110:111], s[8:9], v[106:107] op_sel_hi:[1,0,1]
	v_pk_fma_f32 v[112:113], v[112:113], s[8:9], v[108:109] op_sel_hi:[1,0,1]
	ds_read_b128 v[106:109], v229 offset:3600
	v_pk_fma_f32 v[130:131], v[0:1], v[142:143], v[128:129] op_sel_hi:[0,1,0]
	v_pk_fma_f32 v[128:129], v[0:1], v[136:137], v[128:129] op_sel_hi:[0,1,0]
	s_waitcnt lgkmcnt(0)
	v_pk_fma_f32 v[106:107], v[128:129], v[118:119], v[106:107]
	v_pk_fma_f32 v[108:109], v[130:131], v[120:121], v[108:109]
	s_nop 0
	v_pk_fma_f32 v[108:109], v[108:109], s[8:9], v[104:105] op_sel_hi:[1,0,1]
	v_pk_fma_f32 v[104:105], v[106:107], s[8:9], v[102:103] op_sel_hi:[1,0,1]
	v_cvt_pk_bf16_f32 v102, v110, v111
	v_cvt_pk_bf16_f32 v103, v112, v113
	s_nop 0
	v_cvt_pk_bf16_f32 v104, v104, v105
	v_cvt_pk_bf16_f32 v105, v108, v109
	global_store_dwordx4 v[134:135], v[102:105], off offset:256
	v_lshlrev_b32_e32 v0, 16, v102
	v_lshlrev_b32_e32 v106, 16, v103
	v_and_b32_e32 v102, 0xffff0000, v102
	v_and_b32_e32 v103, 0xffff0000, v103
	v_add_f32_e32 v109, v0, v102
	v_mul_f32_e32 v102, v102, v102
	v_fmac_f32_e32 v102, v0, v0
	v_mul_f32_e32 v0, v103, v103
	v_lshlrev_b32_e32 v107, 16, v104
	v_and_b32_e32 v104, 0xffff0000, v104
	v_fmac_f32_e32 v0, v106, v106
	v_add_f32_e32 v0, v102, v0
	v_mul_f32_e32 v102, v104, v104
	v_lshlrev_b32_e32 v108, 16, v105
	v_and_b32_e32 v105, 0xffff0000, v105
	v_add_f32_e32 v110, v106, v103
	v_fmac_f32_e32 v102, v107, v107
	v_add_f32_e32 v109, v109, v110
	v_add_f32_e32 v110, v107, v104
	v_add_f32_e32 v0, v0, v102
	v_mul_f32_e32 v102, v105, v105
	v_add_f32_e32 v109, v109, v110
	v_add_f32_e32 v110, v108, v105
	v_fmac_f32_e32 v102, v108, v108
	v_add_f32_e32 v109, v109, v110
	v_add_f32_e32 v0, v0, v102
	v_add_f32_e32 v109, v152, v109
	v_add_f32_e32 v103, v155, v0
	ds_bpermute_b32 v0, v153, v109
	ds_bpermute_b32 v104, v153, v103
	s_waitcnt lgkmcnt(1)
	v_add_f32_e32 v0, v109, v0
	s_waitcnt lgkmcnt(0)
	v_add_f32_e32 v103, v103, v104
	ds_bpermute_b32 v102, v154, v0
	ds_bpermute_b32 v104, v154, v103
	s_mov_b32 s26, -1
	s_mov_b32 s27, 0
	s_and_saveexec_b64 s[26:27], s[26:27]
	s_cbranch_execz .LBB0_991
	v_lshl_add_u64 v[106:107], v[126:127], 3, s[28:29]
	s_waitcnt lgkmcnt(1)
	v_add_f32_e32 v0, v0, v102
	s_waitcnt lgkmcnt(0)
	v_add_f32_e32 v102, v103, v104
	v_cndmask_b32_e64 v104, 4, 0, s[10:11]
	v_cndmask_b32_e64 v0, v102, v0, s[10:11]
	v_or_b32_e32 v106, v106, v104
	global_atomic_add_f32 v[106:107], v0, off
.LBB0_991:
	s_or_b64 exec, exec, s[26:27]
	s_waitcnt lgkmcnt(0)
	ds_read_b64 v[104:105], v230 offset:384
	s_waitcnt vmcnt(15)
	v_lshlrev_b32_e32 v106, 16, v158
	v_and_b32_e32 v107, 0xffff0000, v158
	v_lshlrev_b32_e32 v108, 16, v159
	v_and_b32_e32 v109, 0xffff0000, v159
	s_waitcnt lgkmcnt(0)
	v_pk_mul_f32 v[104:105], v[104:105], s[6:7] op_sel_hi:[1,0]
	v_or_b32_e32 v102, 48, v212
	v_fma_f32 v0, -v104, v104, v105
	v_max_f32_e32 v0, 0, v0
	v_add_f32_e32 v0, 0x3727c5ac, v0
	v_rsq_f32_e32 v0, v0
	v_lshlrev_b32_e32 v128, 16, v160
	v_and_b32_e32 v129, 0xffff0000, v160
	v_lshlrev_b32_e32 v130, 16, v161
	v_mul_f32_e64 v104, v104, -v0
	v_pk_fma_f32 v[132:133], v[0:1], v[108:109], v[104:105] op_sel_hi:[0,1,0]
	v_pk_fma_f32 v[134:135], v[0:1], v[106:107], v[104:105] op_sel_hi:[0,1,0]
	ds_read_b128 v[106:109], v229 offset:2048
	ds_read_b128 v[110:113], v229 offset:2064
	ds_read_b128 v[118:121], v229 offset:3072
	v_and_b32_e32 v131, 0xffff0000, v161
	v_ashrrev_i32_e32 v103, 31, v102
	v_lshlrev_b64 v[126:127], 11, v[102:103]
	s_waitcnt lgkmcnt(0)
	v_pk_fma_f32 v[106:107], v[106:107], v[134:135], v[118:119]
	v_pk_fma_f32 v[108:109], v[108:109], v[132:133], v[120:121]
	v_pk_fma_f32 v[106:107], v[106:107], s[8:9], v[94:95] op_sel_hi:[1,0,1]
	v_pk_fma_f32 v[108:109], v[108:109], s[8:9], v[96:97] op_sel_hi:[1,0,1]
	ds_read_b128 v[94:97], v229 offset:3088
	v_pk_fma_f32 v[118:119], v[0:1], v[130:131], v[104:105] op_sel_hi:[0,1,0]
	v_pk_fma_f32 v[120:121], v[0:1], v[128:129], v[104:105] op_sel_hi:[0,1,0]
	s_waitcnt lgkmcnt(0)
	v_pk_fma_f32 v[94:95], v[110:111], v[120:121], v[94:95]
	v_pk_fma_f32 v[96:97], v[112:113], v[118:119], v[96:97]
	s_waitcnt vmcnt(14)
	v_lshlrev_b32_e32 v112, 16, v148
	v_pk_fma_f32 v[96:97], v[96:97], s[8:9], v[88:89] op_sel_hi:[1,0,1]
	v_pk_fma_f32 v[88:89], v[94:95], s[8:9], v[86:87] op_sel_hi:[1,0,1]
	v_lshl_add_u64 v[94:95], s[72:73], 0, v[126:127]
	v_cvt_pk_bf16_f32 v86, v106, v107
	v_cvt_pk_bf16_f32 v87, v108, v109
	v_lshl_add_u64 v[110:111], v[210:211], 1, v[94:95]
	v_cvt_pk_bf16_f32 v88, v88, v89
	v_cvt_pk_bf16_f32 v89, v96, v97
	global_store_dwordx4 v[110:111], v[86:89], off
	v_lshlrev_b32_e32 v94, 16, v86
	v_lshlrev_b32_e32 v95, 16, v87
	v_and_b32_e32 v86, 0xffff0000, v86
	v_and_b32_e32 v87, 0xffff0000, v87
	v_add_f32_e32 v105, v94, v86
	v_add_f32_e32 v106, v95, v87
	v_mul_f32_e32 v86, v86, v86
	v_mul_f32_e32 v87, v87, v87
	v_lshlrev_b32_e32 v96, 16, v88
	v_and_b32_e32 v88, 0xffff0000, v88
	v_fmac_f32_e32 v86, v94, v94
	v_fmac_f32_e32 v87, v95, v95
	v_add_f32_e32 v86, v86, v87
	v_mul_f32_e32 v87, v88, v88
	v_lshlrev_b32_e32 v97, 16, v89
	v_and_b32_e32 v89, 0xffff0000, v89
	v_fmac_f32_e32 v87, v96, v96
	v_add_f32_e32 v105, v105, v106
	v_add_f32_e32 v106, v96, v88
	v_add_f32_e32 v86, v86, v87
	v_mul_f32_e32 v87, v89, v89
	v_add_f32_e32 v105, v105, v106
	v_add_f32_e32 v106, v97, v89
	v_fmac_f32_e32 v87, v97, v97
	v_add_f32_e32 v105, v105, v106
	v_add_f32_e32 v129, v86, v87
	v_lshlrev_b32_e32 v86, 16, v146
	v_and_b32_e32 v87, 0xffff0000, v146
	v_lshlrev_b32_e32 v88, 16, v147
	v_and_b32_e32 v89, 0xffff0000, v147
	v_pk_fma_f32 v[120:121], v[0:1], v[88:89], v[104:105] op_sel_hi:[0,1,0]
	v_pk_fma_f32 v[126:127], v[0:1], v[86:87], v[104:105] op_sel_hi:[0,1,0]
	ds_read_b128 v[86:89], v229 offset:2560
	ds_read_b128 v[94:97], v229 offset:2576
	ds_read_b128 v[106:109], v229 offset:3584
	v_and_b32_e32 v113, 0xffff0000, v148
	v_lshlrev_b32_e32 v118, 16, v149
	v_and_b32_e32 v119, 0xffff0000, v149
	v_add_f32_e32 v128, 0, v105
	s_waitcnt lgkmcnt(0)
; #define PG8_LAS __attribute__((address_space(3)))
; __device__ __forceinline__ float bf_lo(unsigned w) { return __uint_as_float(w << 16); }
; __device__ __forceinline__ float bf_hi(unsigned w) { return __uint_as_float(w & 0xffff0000u); }
; __device__ __forceinline__ void st16_sel(void* p, u32x4 v, bool wt) { if (wt) st16_wt_e(p, v); else *(u32x4*)p = v; }
;     __device__ __forceinline__ void operator()(const f32x4 (&acc)[2][2][4][2], const Unit& u, int wr, int wc, int fr, int fq, int rowmask, const PG8_LAS unsigned char* ev) const {
;     ...
;             for (int m = 0; m < 4; ++m) { if (!((rowmask >> (ai * 4 + m)) & 1)) continue; const int row = row0 + ai * HALF + m * 16; float rA, rB; ln_row_lds(ev, wr * 64 + fr + ai * HALF + m * 16, rA, rB);
;                 float s = 0.f, q = 0.f;
; #pragma unroll
;                 for (int bj = 0; bj < 2; ++bj) { const u32x4 zr = zpre[ai][m][bj];
;                     f32x4 x0 = {bf_lo(zr.x), bf_hi(zr.x), bf_lo(zr.y), bf_hi(zr.y)}, x1 = {bf_lo(zr.z), bf_hi(zr.z), bf_lo(zr.w), bf_hi(zr.w)};
;                     const PG8_LAS f32x4* kp = (const PG8_LAS f32x4*)(ev + 2048 + (wc * 32 + 8 * fq + bj * HALF) * 4);
;                     f32x4 z0 = ((x0 * rA + rB) * kp[0] + kp[64]) * ALPHA_ + acc[ai][bj][m][0], z1 = ((x1 * rA + rB) * kp[1] + kp[65]) * ALPHA_ + acc[ai][bj][m][1];
;                     if (F32OUT) { if (row < MP_ + NSMP_) { float* p = Fout + (size_t)row * 1024 + gcol0 + bj * HALF; *(f32x4*)p = z0; *(f32x4*)(p + 4) = z1; } }
;                     else { const u32x4 w = pack8(z0, z1); st16_sel(Zout + (size_t)row * 1024 + gcol0 + bj * HALF, w, (rowmask & 0x200) != 0);
;                         z0 = (f32x4){bf_lo(w.x), bf_hi(w.x), bf_lo(w.y), bf_hi(w.y)}; z1 = (f32x4){bf_lo(w.z), bf_hi(w.z), bf_lo(w.w), bf_hi(w.w)}; }
;                     s += (z0[0] + z0[1]) + (z0[2] + z0[3]) + (z1[0] + z1[1]) + (z1[2] + z1[3]);
;                     q += (z0[0] * z0[0] + z0[1] * z0[1]) + (z0[2] * z0[2] + z0[3] * z0[3]) + (z1[0] * z1[0] + z1[1] * z1[1]) + (z1[2] * z1[2] + z1[3] * z1[3]); }
;                 s += __shfl_xor(s, 16); s += __shfl_xor(s, 32); q += __shfl_xor(q, 16); q += __shfl_xor(q, 32);
;                 if (fq == 0) { atomicAdd(stats_out + 2 * (size_t)row, s); atomicAdd(stats_out + 2 * (size_t)row + 1, q); } } }
	v_pk_fma_f32 v[86:87], v[86:87], v[126:127], v[106:107]
	v_pk_fma_f32 v[88:89], v[88:89], v[120:121], v[108:109]
	v_pk_fma_f32 v[86:87], v[86:87], s[8:9], v[82:83] op_sel_hi:[1,0,1]
	v_pk_fma_f32 v[88:89], v[88:89], s[8:9], v[84:85] op_sel_hi:[1,0,1]
	ds_read_b128 v[82:85], v229 offset:3600
	v_pk_fma_f32 v[106:107], v[0:1], v[118:119], v[104:105] op_sel_hi:[0,1,0]
	v_pk_fma_f32 v[104:105], v[0:1], v[112:113], v[104:105] op_sel_hi:[0,1,0]
	s_waitcnt lgkmcnt(0)
	v_pk_fma_f32 v[82:83], v[104:105], v[94:95], v[82:83]
	v_pk_fma_f32 v[84:85], v[106:107], v[96:97], v[84:85]
	s_nop 0
	v_pk_fma_f32 v[84:85], v[84:85], s[8:9], v[80:81] op_sel_hi:[1,0,1]
	v_pk_fma_f32 v[80:81], v[82:83], s[8:9], v[78:79] op_sel_hi:[1,0,1]
	v_cvt_pk_bf16_f32 v78, v86, v87
	v_cvt_pk_bf16_f32 v79, v88, v89
	s_nop 0
	v_cvt_pk_bf16_f32 v80, v80, v81
	v_cvt_pk_bf16_f32 v81, v84, v85
	global_store_dwordx4 v[110:111], v[78:81], off offset:256
	v_lshlrev_b32_e32 v0, 16, v78
	v_lshlrev_b32_e32 v82, 16, v79
	v_and_b32_e32 v78, 0xffff0000, v78
	v_and_b32_e32 v79, 0xffff0000, v79
	v_add_f32_e32 v85, v0, v78
	v_mul_f32_e32 v78, v78, v78
	v_fmac_f32_e32 v78, v0, v0
	v_mul_f32_e32 v0, v79, v79
	v_lshlrev_b32_e32 v83, 16, v80
	v_and_b32_e32 v80, 0xffff0000, v80
	v_fmac_f32_e32 v0, v82, v82
	v_add_f32_e32 v0, v78, v0
	v_mul_f32_e32 v78, v80, v80
	v_lshlrev_b32_e32 v84, 16, v81
	v_and_b32_e32 v81, 0xffff0000, v81
	v_add_f32_e32 v86, v82, v79
	v_fmac_f32_e32 v78, v83, v83
	v_add_f32_e32 v85, v85, v86
	v_add_f32_e32 v86, v83, v80
	v_add_f32_e32 v0, v0, v78
	v_mul_f32_e32 v78, v81, v81
	v_add_f32_e32 v85, v85, v86
	v_add_f32_e32 v86, v84, v81
	v_fmac_f32_e32 v78, v84, v84
	v_add_f32_e32 v85, v85, v86
	v_add_f32_e32 v0, v0, v78
	v_add_f32_e32 v85, v128, v85
	v_add_f32_e32 v79, v129, v0
	ds_bpermute_b32 v0, v153, v85
	ds_bpermute_b32 v80, v153, v79
	s_waitcnt lgkmcnt(1)
	v_add_f32_e32 v0, v85, v0
	s_waitcnt lgkmcnt(0)
	v_add_f32_e32 v79, v79, v80
	ds_bpermute_b32 v78, v154, v0
	ds_bpermute_b32 v80, v154, v79
	s_mov_b32 s26, -1
	s_mov_b32 s27, 0
	s_and_saveexec_b64 s[26:27], s[26:27]
	s_cbranch_execz .LBB0_993
	v_lshl_add_u64 v[82:83], v[102:103], 3, s[28:29]
	s_waitcnt lgkmcnt(1)
	v_add_f32_e32 v0, v0, v78
	s_waitcnt lgkmcnt(0)
	v_add_f32_e32 v78, v79, v80
	v_cndmask_b32_e64 v80, 4, 0, s[10:11]
	v_cndmask_b32_e64 v0, v78, v0, s[10:11]
	v_or_b32_e32 v82, v82, v80
	global_atomic_add_f32 v[82:83], v0, off
.LBB0_993:
	s_or_b64 exec, exec, s[26:27]
	s_waitcnt lgkmcnt(0)
	ds_read_b64 v[80:81], v230 offset:1024
	s_waitcnt vmcnt(15)
	v_lshlrev_b32_e32 v82, 16, v138
	v_and_b32_e32 v83, 0xffff0000, v138
	v_lshlrev_b32_e32 v84, 16, v139
	v_and_b32_e32 v85, 0xffff0000, v139
	s_waitcnt lgkmcnt(0)
	v_pk_mul_f32 v[80:81], v[80:81], s[6:7] op_sel_hi:[1,0]
	v_add_u32_e32 v78, 0x80, v212
	v_fma_f32 v0, -v80, v80, v81
	v_max_f32_e32 v0, 0, v0
	v_add_f32_e32 v0, 0x3727c5ac, v0
	v_rsq_f32_e32 v0, v0
	v_lshlrev_b32_e32 v104, 16, v140
	v_and_b32_e32 v105, 0xffff0000, v140
	v_lshlrev_b32_e32 v106, 16, v141
	v_mul_f32_e64 v80, v80, -v0
	v_pk_fma_f32 v[108:109], v[0:1], v[84:85], v[80:81] op_sel_hi:[0,1,0]
	v_pk_fma_f32 v[110:111], v[0:1], v[82:83], v[80:81] op_sel_hi:[0,1,0]
	ds_read_b128 v[82:85], v229 offset:2048
	ds_read_b128 v[86:89], v229 offset:2064
	ds_read_b128 v[94:97], v229 offset:3072
	v_and_b32_e32 v107, 0xffff0000, v141
	v_ashrrev_i32_e32 v79, 31, v78
	v_lshlrev_b64 v[102:103], 11, v[78:79]
	s_waitcnt lgkmcnt(0)
	v_pk_fma_f32 v[82:83], v[82:83], v[110:111], v[94:95]
	v_pk_fma_f32 v[84:85], v[84:85], v[108:109], v[96:97]
	v_pk_fma_f32 v[82:83], v[82:83], s[8:9], v[70:71] op_sel_hi:[1,0,1]
	v_pk_fma_f32 v[84:85], v[84:85], s[8:9], v[72:73] op_sel_hi:[1,0,1]
	ds_read_b128 v[70:73], v229 offset:3088
	v_pk_fma_f32 v[94:95], v[0:1], v[106:107], v[80:81] op_sel_hi:[0,1,0]
	v_pk_fma_f32 v[96:97], v[0:1], v[104:105], v[80:81] op_sel_hi:[0,1,0]
	s_waitcnt lgkmcnt(0)
	v_pk_fma_f32 v[70:71], v[86:87], v[96:97], v[70:71]
	v_pk_fma_f32 v[72:73], v[88:89], v[94:95], v[72:73]
	s_waitcnt vmcnt(14)
	v_lshlrev_b32_e32 v88, 16, v124
	v_pk_fma_f32 v[72:73], v[72:73], s[8:9], v[68:69] op_sel_hi:[1,0,1]
	v_pk_fma_f32 v[68:69], v[70:71], s[8:9], v[66:67] op_sel_hi:[1,0,1]
	v_lshl_add_u64 v[70:71], s[72:73], 0, v[102:103]
	v_cvt_pk_bf16_f32 v66, v82, v83
	v_cvt_pk_bf16_f32 v67, v84, v85
	v_lshl_add_u64 v[86:87], v[210:211], 1, v[70:71]
	v_cvt_pk_bf16_f32 v68, v68, v69
	v_cvt_pk_bf16_f32 v69, v72, v73
	global_store_dwordx4 v[86:87], v[66:69], off
	v_lshlrev_b32_e32 v70, 16, v66
	v_lshlrev_b32_e32 v71, 16, v67
	v_and_b32_e32 v66, 0xffff0000, v66
	v_and_b32_e32 v67, 0xffff0000, v67
	v_add_f32_e32 v81, v70, v66
	v_add_f32_e32 v82, v71, v67
	v_mul_f32_e32 v66, v66, v66
	v_mul_f32_e32 v67, v67, v67
	v_lshlrev_b32_e32 v72, 16, v68
	v_and_b32_e32 v68, 0xffff0000, v68
	v_fmac_f32_e32 v66, v70, v70
	v_fmac_f32_e32 v67, v71, v71
	v_add_f32_e32 v66, v66, v67
	v_mul_f32_e32 v67, v68, v68
	v_lshlrev_b32_e32 v73, 16, v69
	v_and_b32_e32 v69, 0xffff0000, v69
	v_fmac_f32_e32 v67, v72, v72
	v_add_f32_e32 v81, v81, v82
	v_add_f32_e32 v82, v72, v68
	v_add_f32_e32 v66, v66, v67
	v_mul_f32_e32 v67, v69, v69
	v_add_f32_e32 v81, v81, v82
	v_add_f32_e32 v82, v73, v69
	v_fmac_f32_e32 v67, v73, v73
	v_add_f32_e32 v81, v81, v82
	v_add_f32_e32 v105, v66, v67
	v_lshlrev_b32_e32 v66, 16, v122
	v_and_b32_e32 v67, 0xffff0000, v122
	v_lshlrev_b32_e32 v68, 16, v123
	v_and_b32_e32 v69, 0xffff0000, v123
	v_pk_fma_f32 v[96:97], v[0:1], v[68:69], v[80:81] op_sel_hi:[0,1,0]
	v_pk_fma_f32 v[102:103], v[0:1], v[66:67], v[80:81] op_sel_hi:[0,1,0]
	ds_read_b128 v[66:69], v229 offset:2560
	ds_read_b128 v[70:73], v229 offset:2576
	ds_read_b128 v[82:85], v229 offset:3584
	v_and_b32_e32 v89, 0xffff0000, v124
	v_lshlrev_b32_e32 v94, 16, v125
	v_and_b32_e32 v95, 0xffff0000, v125
	v_add_f32_e32 v104, 0, v81
	s_waitcnt lgkmcnt(0)
; #define PG8_LAS __attribute__((address_space(3)))
; __device__ __forceinline__ float bf_lo(unsigned w) { return __uint_as_float(w << 16); }
; __device__ __forceinline__ float bf_hi(unsigned w) { return __uint_as_float(w & 0xffff0000u); }
; __device__ __forceinline__ void st16_sel(void* p, u32x4 v, bool wt) { if (wt) st16_wt_e(p, v); else *(u32x4*)p = v; }
;     __device__ __forceinline__ void operator()(const f32x4 (&acc)[2][2][4][2], const Unit& u, int wr, int wc, int fr, int fq, int rowmask, const PG8_LAS unsigned char* ev) const {
;     ...
;             for (int m = 0; m < 4; ++m) { if (!((rowmask >> (ai * 4 + m)) & 1)) continue; const int row = row0 + ai * HALF + m * 16; float rA, rB; ln_row_lds(ev, wr * 64 + fr + ai * HALF + m * 16, rA, rB);
;                 float s = 0.f, q = 0.f;
; #pragma unroll
;                 for (int bj = 0; bj < 2; ++bj) { const u32x4 zr = zpre[ai][m][bj];
;                     f32x4 x0 = {bf_lo(zr.x), bf_hi(zr.x), bf_lo(zr.y), bf_hi(zr.y)}, x1 = {bf_lo(zr.z), bf_hi(zr.z), bf_lo(zr.w), bf_hi(zr.w)};
;                     const PG8_LAS f32x4* kp = (const PG8_LAS f32x4*)(ev + 2048 + (wc * 32 + 8 * fq + bj * HALF) * 4);
;                     f32x4 z0 = ((x0 * rA + rB) * kp[0] + kp[64]) * ALPHA_ + acc[ai][bj][m][0], z1 = ((x1 * rA + rB) * kp[1] + kp[65]) * ALPHA_ + acc[ai][bj][m][1];
;                     if (F32OUT) { if (row < MP_ + NSMP_) { float* p = Fout + (size_t)row * 1024 + gcol0 + bj * HALF; *(f32x4*)p = z0; *(f32x4*)(p + 4) = z1; } }
;                     else { const u32x4 w = pack8(z0, z1); st16_sel(Zout + (size_t)row * 1024 + gcol0 + bj * HALF, w, (rowmask & 0x200) != 0);
;                         z0 = (f32x4){bf_lo(w.x), bf_hi(w.x), bf_lo(w.y), bf_hi(w.y)}; z1 = (f32x4){bf_lo(w.z), bf_hi(w.z), bf_lo(w.w), bf_hi(w.w)}; }
;                     s += (z0[0] + z0[1]) + (z0[2] + z0[3]) + (z1[0] + z1[1]) + (z1[2] + z1[3]);
;                     q += (z0[0] * z0[0] + z0[1] * z0[1]) + (z0[2] * z0[2] + z0[3] * z0[3]) + (z1[0] * z1[0] + z1[1] * z1[1]) + (z1[2] * z1[2] + z1[3] * z1[3]); }
;                 s += __shfl_xor(s, 16); s += __shfl_xor(s, 32); q += __shfl_xor(q, 16); q += __shfl_xor(q, 32);
;                 if (fq == 0) { atomicAdd(stats_out + 2 * (size_t)row, s); atomicAdd(stats_out + 2 * (size_t)row + 1, q); } } }
	v_pk_fma_f32 v[66:67], v[66:67], v[102:103], v[82:83]
	v_pk_fma_f32 v[68:69], v[68:69], v[96:97], v[84:85]
	v_pk_fma_f32 v[66:67], v[66:67], s[8:9], v[58:59] op_sel_hi:[1,0,1]
	v_pk_fma_f32 v[68:69], v[68:69], s[8:9], v[60:61] op_sel_hi:[1,0,1]
	ds_read_b128 v[58:61], v229 offset:3600
	v_pk_fma_f32 v[82:83], v[0:1], v[94:95], v[80:81] op_sel_hi:[0,1,0]
	v_pk_fma_f32 v[80:81], v[0:1], v[88:89], v[80:81] op_sel_hi:[0,1,0]
	s_waitcnt lgkmcnt(0)
	v_pk_fma_f32 v[58:59], v[80:81], v[70:71], v[58:59]
	v_pk_fma_f32 v[60:61], v[82:83], v[72:73], v[60:61]
	s_nop 0
	v_pk_fma_f32 v[60:61], v[60:61], s[8:9], v[56:57] op_sel_hi:[1,0,1]
	v_pk_fma_f32 v[56:57], v[58:59], s[8:9], v[54:55] op_sel_hi:[1,0,1]
	v_cvt_pk_bf16_f32 v54, v66, v67
	v_cvt_pk_bf16_f32 v55, v68, v69
	s_nop 0
	v_cvt_pk_bf16_f32 v56, v56, v57
	v_cvt_pk_bf16_f32 v57, v60, v61
	global_store_dwordx4 v[86:87], v[54:57], off offset:256
	v_lshlrev_b32_e32 v0, 16, v54
	v_lshlrev_b32_e32 v58, 16, v55
	v_and_b32_e32 v54, 0xffff0000, v54
	v_and_b32_e32 v55, 0xffff0000, v55
	v_add_f32_e32 v61, v0, v54
	v_mul_f32_e32 v54, v54, v54
	v_fmac_f32_e32 v54, v0, v0
	v_mul_f32_e32 v0, v55, v55
	v_lshlrev_b32_e32 v59, 16, v56
	v_and_b32_e32 v56, 0xffff0000, v56
	v_fmac_f32_e32 v0, v58, v58
	v_add_f32_e32 v0, v54, v0
	v_mul_f32_e32 v54, v56, v56
	v_lshlrev_b32_e32 v60, 16, v57
	v_and_b32_e32 v57, 0xffff0000, v57
	v_add_f32_e32 v66, v58, v55
	v_fmac_f32_e32 v54, v59, v59
	v_add_f32_e32 v61, v61, v66
	v_add_f32_e32 v66, v59, v56
	v_add_f32_e32 v0, v0, v54
	v_mul_f32_e32 v54, v57, v57
	v_add_f32_e32 v61, v61, v66
	v_add_f32_e32 v66, v60, v57
	v_fmac_f32_e32 v54, v60, v60
	v_add_f32_e32 v61, v61, v66
	v_add_f32_e32 v0, v0, v54
	v_add_f32_e32 v61, v104, v61
	v_add_f32_e32 v55, v105, v0
	ds_bpermute_b32 v0, v153, v61
	ds_bpermute_b32 v56, v153, v55
	s_waitcnt lgkmcnt(1)
	v_add_f32_e32 v0, v61, v0
	s_waitcnt lgkmcnt(0)
	v_add_f32_e32 v55, v55, v56
	ds_bpermute_b32 v54, v154, v0
	ds_bpermute_b32 v56, v154, v55
	s_mov_b32 s26, -1
	s_mov_b32 s27, 0
	s_and_saveexec_b64 s[26:27], s[26:27]
	s_cbranch_execz .LBB0_995
	v_lshl_add_u64 v[58:59], v[78:79], 3, s[28:29]
	s_waitcnt lgkmcnt(1)
	v_add_f32_e32 v0, v0, v54
	s_waitcnt lgkmcnt(0)
	v_add_f32_e32 v54, v55, v56
	v_cndmask_b32_e64 v56, 4, 0, s[10:11]
	v_cndmask_b32_e64 v0, v54, v0, s[10:11]
	v_or_b32_e32 v58, v58, v56
	global_atomic_add_f32 v[58:59], v0, off
.LBB0_995:
	s_or_b64 exec, exec, s[26:27]
	s_waitcnt lgkmcnt(0)
	ds_read_b64 v[56:57], v230 offset:1152
	s_waitcnt vmcnt(15)
	v_lshlrev_b32_e32 v58, 16, v114
	v_and_b32_e32 v59, 0xffff0000, v114
	v_lshlrev_b32_e32 v60, 16, v115
	v_and_b32_e32 v61, 0xffff0000, v115
	s_waitcnt lgkmcnt(0)
	v_pk_mul_f32 v[56:57], v[56:57], s[6:7] op_sel_hi:[1,0]
	v_add_u32_e32 v54, 0x90, v212
	v_fma_f32 v0, -v56, v56, v57
	v_max_f32_e32 v0, 0, v0
	v_add_f32_e32 v0, 0x3727c5ac, v0
	v_rsq_f32_e32 v0, v0
	v_lshlrev_b32_e32 v80, 16, v116
	v_and_b32_e32 v81, 0xffff0000, v116
	v_lshlrev_b32_e32 v82, 16, v117
	v_mul_f32_e64 v56, v56, -v0
	v_pk_fma_f32 v[84:85], v[0:1], v[60:61], v[56:57] op_sel_hi:[0,1,0]
	v_pk_fma_f32 v[86:87], v[0:1], v[58:59], v[56:57] op_sel_hi:[0,1,0]
	ds_read_b128 v[58:61], v229 offset:2048
	ds_read_b128 v[66:69], v229 offset:2064
	ds_read_b128 v[70:73], v229 offset:3072
	v_and_b32_e32 v83, 0xffff0000, v117
	v_ashrrev_i32_e32 v55, 31, v54
	v_lshlrev_b64 v[78:79], 11, v[54:55]
	s_waitcnt lgkmcnt(0)
	v_pk_fma_f32 v[58:59], v[58:59], v[86:87], v[70:71]
	v_pk_fma_f32 v[60:61], v[60:61], v[84:85], v[72:73]
	v_pk_fma_f32 v[58:59], v[58:59], s[8:9], v[46:47] op_sel_hi:[1,0,1]
	v_pk_fma_f32 v[60:61], v[60:61], s[8:9], v[48:49] op_sel_hi:[1,0,1]
	ds_read_b128 v[46:49], v229 offset:3088
	v_pk_fma_f32 v[70:71], v[0:1], v[82:83], v[56:57] op_sel_hi:[0,1,0]
	v_pk_fma_f32 v[72:73], v[0:1], v[80:81], v[56:57] op_sel_hi:[0,1,0]
	s_waitcnt lgkmcnt(0)
	v_pk_fma_f32 v[46:47], v[66:67], v[72:73], v[46:47]
	v_pk_fma_f32 v[48:49], v[68:69], v[70:71], v[48:49]
	s_waitcnt vmcnt(14)
	v_lshlrev_b32_e32 v68, 16, v100
	v_pk_fma_f32 v[48:49], v[48:49], s[8:9], v[44:45] op_sel_hi:[1,0,1]
	v_pk_fma_f32 v[44:45], v[46:47], s[8:9], v[42:43] op_sel_hi:[1,0,1]
	v_lshl_add_u64 v[46:47], s[72:73], 0, v[78:79]
	v_cvt_pk_bf16_f32 v42, v58, v59
	v_cvt_pk_bf16_f32 v43, v60, v61
	v_lshl_add_u64 v[66:67], v[210:211], 1, v[46:47]
	v_cvt_pk_bf16_f32 v44, v44, v45
	v_cvt_pk_bf16_f32 v45, v48, v49
	global_store_dwordx4 v[66:67], v[42:45], off
	v_lshlrev_b32_e32 v46, 16, v42
	v_lshlrev_b32_e32 v47, 16, v43
	v_and_b32_e32 v42, 0xffff0000, v42
	v_and_b32_e32 v43, 0xffff0000, v43
	v_add_f32_e32 v57, v46, v42
	v_add_f32_e32 v58, v47, v43
	v_mul_f32_e32 v42, v42, v42
	v_mul_f32_e32 v43, v43, v43
	v_lshlrev_b32_e32 v48, 16, v44
	v_and_b32_e32 v44, 0xffff0000, v44
	v_fmac_f32_e32 v42, v46, v46
	v_fmac_f32_e32 v43, v47, v47
	v_add_f32_e32 v42, v42, v43
	v_mul_f32_e32 v43, v44, v44
	v_lshlrev_b32_e32 v49, 16, v45
	v_and_b32_e32 v45, 0xffff0000, v45
	v_fmac_f32_e32 v43, v48, v48
	v_add_f32_e32 v57, v57, v58
	v_add_f32_e32 v58, v48, v44
	v_add_f32_e32 v42, v42, v43
	v_mul_f32_e32 v43, v45, v45
	v_add_f32_e32 v57, v57, v58
	v_add_f32_e32 v58, v49, v45
	v_fmac_f32_e32 v43, v49, v49
	v_add_f32_e32 v57, v57, v58
	v_add_f32_e32 v81, v42, v43
	v_lshlrev_b32_e32 v42, 16, v98
	v_and_b32_e32 v43, 0xffff0000, v98
	v_lshlrev_b32_e32 v44, 16, v99
	v_and_b32_e32 v45, 0xffff0000, v99
	v_pk_fma_f32 v[72:73], v[0:1], v[44:45], v[56:57] op_sel_hi:[0,1,0]
	v_pk_fma_f32 v[78:79], v[0:1], v[42:43], v[56:57] op_sel_hi:[0,1,0]
	ds_read_b128 v[42:45], v229 offset:2560
	ds_read_b128 v[46:49], v229 offset:2576
	ds_read_b128 v[58:61], v229 offset:3584
	v_and_b32_e32 v69, 0xffff0000, v100
	v_lshlrev_b32_e32 v70, 16, v101
	v_and_b32_e32 v71, 0xffff0000, v101
	v_add_f32_e32 v80, 0, v57
	s_waitcnt lgkmcnt(0)
; #define PG8_LAS __attribute__((address_space(3)))
; __device__ __forceinline__ float bf_lo(unsigned w) { return __uint_as_float(w << 16); }
; __device__ __forceinline__ float bf_hi(unsigned w) { return __uint_as_float(w & 0xffff0000u); }
; __device__ __forceinline__ void st16_sel(void* p, u32x4 v, bool wt) { if (wt) st16_wt_e(p, v); else *(u32x4*)p = v; }
;     __device__ __forceinline__ void operator()(const f32x4 (&acc)[2][2][4][2], const Unit& u, int wr, int wc, int fr, int fq, int rowmask, const PG8_LAS unsigned char* ev) const {
;     ...
;             for (int m = 0; m < 4; ++m) { if (!((rowmask >> (ai * 4 + m)) & 1)) continue; const int row = row0 + ai * HALF + m * 16; float rA, rB; ln_row_lds(ev, wr * 64 + fr + ai * HALF + m * 16, rA, rB);
;                 float s = 0.f, q = 0.f;
; #pragma unroll
;                 for (int bj = 0; bj < 2; ++bj) { const u32x4 zr = zpre[ai][m][bj];
;                     f32x4 x0 = {bf_lo(zr.x), bf_hi(zr.x), bf_lo(zr.y), bf_hi(zr.y)}, x1 = {bf_lo(zr.z), bf_hi(zr.z), bf_lo(zr.w), bf_hi(zr.w)};
;                     const PG8_LAS f32x4* kp = (const PG8_LAS f32x4*)(ev + 2048 + (wc * 32 + 8 * fq + bj * HALF) * 4);
;                     f32x4 z0 = ((x0 * rA + rB) * kp[0] + kp[64]) * ALPHA_ + acc[ai][bj][m][0], z1 = ((x1 * rA + rB) * kp[1] + kp[65]) * ALPHA_ + acc[ai][bj][m][1];
;                     if (F32OUT) { if (row < MP_ + NSMP_) { float* p = Fout + (size_t)row * 1024 + gcol0 + bj * HALF; *(f32x4*)p = z0; *(f32x4*)(p + 4) = z1; } }
;                     else { const u32x4 w = pack8(z0, z1); st16_sel(Zout + (size_t)row * 1024 + gcol0 + bj * HALF, w, (rowmask & 0x200) != 0);
;                         z0 = (f32x4){bf_lo(w.x), bf_hi(w.x), bf_lo(w.y), bf_hi(w.y)}; z1 = (f32x4){bf_lo(w.z), bf_hi(w.z), bf_lo(w.w), bf_hi(w.w)}; }
;                     s += (z0[0] + z0[1]) + (z0[2] + z0[3]) + (z1[0] + z1[1]) + (z1[2] + z1[3]);
;                     q += (z0[0] * z0[0] + z0[1] * z0[1]) + (z0[2] * z0[2] + z0[3] * z0[3]) + (z1[0] * z1[0] + z1[1] * z1[1]) + (z1[2] * z1[2] + z1[3] * z1[3]); }
;                 s += __shfl_xor(s, 16); s += __shfl_xor(s, 32); q += __shfl_xor(q, 16); q += __shfl_xor(q, 32);
;                 if (fq == 0) { atomicAdd(stats_out + 2 * (size_t)row, s); atomicAdd(stats_out + 2 * (size_t)row + 1, q); } } }
	v_pk_fma_f32 v[42:43], v[42:43], v[78:79], v[58:59]
	v_pk_fma_f32 v[44:45], v[44:45], v[72:73], v[60:61]
	v_pk_fma_f32 v[42:43], v[42:43], s[8:9], v[38:39] op_sel_hi:[1,0,1]
	v_pk_fma_f32 v[44:45], v[44:45], s[8:9], v[40:41] op_sel_hi:[1,0,1]
	ds_read_b128 v[38:41], v229 offset:3600
	v_pk_fma_f32 v[58:59], v[0:1], v[70:71], v[56:57] op_sel_hi:[0,1,0]
	v_pk_fma_f32 v[56:57], v[0:1], v[68:69], v[56:57] op_sel_hi:[0,1,0]
	s_waitcnt lgkmcnt(0)
	v_pk_fma_f32 v[38:39], v[56:57], v[46:47], v[38:39]
	v_pk_fma_f32 v[40:41], v[58:59], v[48:49], v[40:41]
	s_nop 0
	v_pk_fma_f32 v[40:41], v[40:41], s[8:9], v[36:37] op_sel_hi:[1,0,1]
	v_pk_fma_f32 v[36:37], v[38:39], s[8:9], v[34:35] op_sel_hi:[1,0,1]
	v_cvt_pk_bf16_f32 v34, v42, v43
	v_cvt_pk_bf16_f32 v35, v44, v45
	s_nop 0
	v_cvt_pk_bf16_f32 v36, v36, v37
	v_cvt_pk_bf16_f32 v37, v40, v41
	global_store_dwordx4 v[66:67], v[34:37], off offset:256
	v_lshlrev_b32_e32 v0, 16, v34
	v_lshlrev_b32_e32 v38, 16, v35
	v_and_b32_e32 v34, 0xffff0000, v34
	v_and_b32_e32 v35, 0xffff0000, v35
	v_add_f32_e32 v41, v0, v34
	v_mul_f32_e32 v34, v34, v34
	v_fmac_f32_e32 v34, v0, v0
	v_mul_f32_e32 v0, v35, v35
	v_lshlrev_b32_e32 v39, 16, v36
	v_and_b32_e32 v36, 0xffff0000, v36
	v_fmac_f32_e32 v0, v38, v38
	v_add_f32_e32 v0, v34, v0
	v_mul_f32_e32 v34, v36, v36
	v_lshlrev_b32_e32 v40, 16, v37
	v_and_b32_e32 v37, 0xffff0000, v37
	v_add_f32_e32 v42, v38, v35
	v_fmac_f32_e32 v34, v39, v39
	v_add_f32_e32 v41, v41, v42
	v_add_f32_e32 v42, v39, v36
	v_add_f32_e32 v0, v0, v34
	v_mul_f32_e32 v34, v37, v37
	v_add_f32_e32 v41, v41, v42
	v_add_f32_e32 v42, v40, v37
	v_fmac_f32_e32 v34, v40, v40
	v_add_f32_e32 v41, v41, v42
	v_add_f32_e32 v0, v0, v34
	v_add_f32_e32 v41, v80, v41
	v_add_f32_e32 v35, v81, v0
	ds_bpermute_b32 v0, v153, v41
	ds_bpermute_b32 v36, v153, v35
	s_waitcnt lgkmcnt(1)
	v_add_f32_e32 v0, v41, v0
	s_waitcnt lgkmcnt(0)
	v_add_f32_e32 v35, v35, v36
	ds_bpermute_b32 v34, v154, v0
	ds_bpermute_b32 v36, v154, v35
	s_mov_b32 s26, -1
	s_mov_b32 s27, 0
	s_and_saveexec_b64 s[26:27], s[26:27]
	s_cbranch_execz .LBB0_997
	v_lshl_add_u64 v[38:39], v[54:55], 3, s[28:29]
	s_waitcnt lgkmcnt(1)
	v_add_f32_e32 v0, v0, v34
	s_waitcnt lgkmcnt(0)
	v_add_f32_e32 v34, v35, v36
	v_cndmask_b32_e64 v36, 4, 0, s[10:11]
	v_cndmask_b32_e64 v0, v34, v0, s[10:11]
	v_or_b32_e32 v38, v38, v36
	global_atomic_add_f32 v[38:39], v0, off
.LBB0_997:
	s_or_b64 exec, exec, s[26:27]
	s_waitcnt lgkmcnt(0)
	ds_read_b64 v[36:37], v230 offset:1280
	s_waitcnt vmcnt(15)
	v_lshlrev_b32_e32 v38, 16, v90
	v_and_b32_e32 v39, 0xffff0000, v90
	v_lshlrev_b32_e32 v40, 16, v91
	v_and_b32_e32 v41, 0xffff0000, v91
	s_waitcnt lgkmcnt(0)
	v_pk_mul_f32 v[36:37], v[36:37], s[6:7] op_sel_hi:[1,0]
	v_add_u32_e32 v34, 0xa0, v212
	v_fma_f32 v0, -v36, v36, v37
	v_max_f32_e32 v0, 0, v0
	v_add_f32_e32 v0, 0x3727c5ac, v0
	v_rsq_f32_e32 v0, v0
	v_lshlrev_b32_e32 v56, 16, v92
	v_and_b32_e32 v57, 0xffff0000, v92
	v_lshlrev_b32_e32 v58, 16, v93
	v_mul_f32_e64 v36, v36, -v0
	v_pk_fma_f32 v[60:61], v[0:1], v[40:41], v[36:37] op_sel_hi:[0,1,0]
	v_pk_fma_f32 v[66:67], v[0:1], v[38:39], v[36:37] op_sel_hi:[0,1,0]
	ds_read_b128 v[38:41], v229 offset:2048
	ds_read_b128 v[42:45], v229 offset:2064
	ds_read_b128 v[46:49], v229 offset:3072
	v_and_b32_e32 v59, 0xffff0000, v93
	v_ashrrev_i32_e32 v35, 31, v34
	v_lshlrev_b64 v[54:55], 11, v[34:35]
	s_waitcnt lgkmcnt(0)
	v_pk_fma_f32 v[38:39], v[38:39], v[66:67], v[46:47]
	v_pk_fma_f32 v[40:41], v[40:41], v[60:61], v[48:49]
	v_pk_fma_f32 v[38:39], v[38:39], s[8:9], v[30:31] op_sel_hi:[1,0,1]
	v_pk_fma_f32 v[40:41], v[40:41], s[8:9], v[32:33] op_sel_hi:[1,0,1]
	ds_read_b128 v[30:33], v229 offset:3088
	v_pk_fma_f32 v[46:47], v[0:1], v[58:59], v[36:37] op_sel_hi:[0,1,0]
	v_pk_fma_f32 v[48:49], v[0:1], v[56:57], v[36:37] op_sel_hi:[0,1,0]
	s_waitcnt lgkmcnt(0)
	v_pk_fma_f32 v[30:31], v[42:43], v[48:49], v[30:31]
	v_pk_fma_f32 v[32:33], v[44:45], v[46:47], v[32:33]
	s_waitcnt vmcnt(14)
	v_lshlrev_b32_e32 v44, 16, v76
	v_pk_fma_f32 v[32:33], v[32:33], s[8:9], v[28:29] op_sel_hi:[1,0,1]
	v_pk_fma_f32 v[28:29], v[30:31], s[8:9], v[26:27] op_sel_hi:[1,0,1]
	v_lshl_add_u64 v[30:31], s[72:73], 0, v[54:55]
	v_cvt_pk_bf16_f32 v26, v38, v39
	v_cvt_pk_bf16_f32 v27, v40, v41
	v_lshl_add_u64 v[42:43], v[210:211], 1, v[30:31]
	v_cvt_pk_bf16_f32 v28, v28, v29
	v_cvt_pk_bf16_f32 v29, v32, v33
	global_store_dwordx4 v[42:43], v[26:29], off
	v_lshlrev_b32_e32 v30, 16, v26
	v_lshlrev_b32_e32 v31, 16, v27
	v_and_b32_e32 v26, 0xffff0000, v26
	v_and_b32_e32 v27, 0xffff0000, v27
	v_add_f32_e32 v37, v30, v26
	v_add_f32_e32 v38, v31, v27
	v_mul_f32_e32 v26, v26, v26
	v_mul_f32_e32 v27, v27, v27
	v_lshlrev_b32_e32 v32, 16, v28
	v_and_b32_e32 v28, 0xffff0000, v28
	v_fmac_f32_e32 v26, v30, v30
	v_fmac_f32_e32 v27, v31, v31
	v_add_f32_e32 v26, v26, v27
	v_mul_f32_e32 v27, v28, v28
	v_lshlrev_b32_e32 v33, 16, v29
	v_and_b32_e32 v29, 0xffff0000, v29
	v_fmac_f32_e32 v27, v32, v32
	v_add_f32_e32 v37, v37, v38
	v_add_f32_e32 v38, v32, v28
	v_add_f32_e32 v26, v26, v27
	v_mul_f32_e32 v27, v29, v29
	v_add_f32_e32 v37, v37, v38
	v_add_f32_e32 v38, v33, v29
	v_fmac_f32_e32 v27, v33, v33
	v_add_f32_e32 v37, v37, v38
	v_add_f32_e32 v57, v26, v27
	v_lshlrev_b32_e32 v26, 16, v74
	v_and_b32_e32 v27, 0xffff0000, v74
	v_lshlrev_b32_e32 v28, 16, v75
	v_and_b32_e32 v29, 0xffff0000, v75
	v_pk_fma_f32 v[48:49], v[0:1], v[28:29], v[36:37] op_sel_hi:[0,1,0]
	v_pk_fma_f32 v[54:55], v[0:1], v[26:27], v[36:37] op_sel_hi:[0,1,0]
	ds_read_b128 v[26:29], v229 offset:2560
	ds_read_b128 v[30:33], v229 offset:2576
	ds_read_b128 v[38:41], v229 offset:3584
	v_and_b32_e32 v45, 0xffff0000, v76
	v_lshlrev_b32_e32 v46, 16, v77
	v_and_b32_e32 v47, 0xffff0000, v77
	v_add_f32_e32 v56, 0, v37
	s_waitcnt lgkmcnt(0)
; #define PG8_LAS __attribute__((address_space(3)))
; __device__ __forceinline__ float bf_lo(unsigned w) { return __uint_as_float(w << 16); }
; __device__ __forceinline__ float bf_hi(unsigned w) { return __uint_as_float(w & 0xffff0000u); }
; __device__ __forceinline__ void st16_sel(void* p, u32x4 v, bool wt) { if (wt) st16_wt_e(p, v); else *(u32x4*)p = v; }
;     __device__ __forceinline__ void operator()(const f32x4 (&acc)[2][2][4][2], const Unit& u, int wr, int wc, int fr, int fq, int rowmask, const PG8_LAS unsigned char* ev) const {
;     ...
;             for (int m = 0; m < 4; ++m) { if (!((rowmask >> (ai * 4 + m)) & 1)) continue; const int row = row0 + ai * HALF + m * 16; float rA, rB; ln_row_lds(ev, wr * 64 + fr + ai * HALF + m * 16, rA, rB);
;                 float s = 0.f, q = 0.f;
; #pragma unroll
;                 for (int bj = 0; bj < 2; ++bj) { const u32x4 zr = zpre[ai][m][bj];
;                     f32x4 x0 = {bf_lo(zr.x), bf_hi(zr.x), bf_lo(zr.y), bf_hi(zr.y)}, x1 = {bf_lo(zr.z), bf_hi(zr.z), bf_lo(zr.w), bf_hi(zr.w)};
;                     const PG8_LAS f32x4* kp = (const PG8_LAS f32x4*)(ev + 2048 + (wc * 32 + 8 * fq + bj * HALF) * 4);
;                     f32x4 z0 = ((x0 * rA + rB) * kp[0] + kp[64]) * ALPHA_ + acc[ai][bj][m][0], z1 = ((x1 * rA + rB) * kp[1] + kp[65]) * ALPHA_ + acc[ai][bj][m][1];
;                     if (F32OUT) { if (row < MP_ + NSMP_) { float* p = Fout + (size_t)row * 1024 + gcol0 + bj * HALF; *(f32x4*)p = z0; *(f32x4*)(p + 4) = z1; } }
;                     else { const u32x4 w = pack8(z0, z1); st16_sel(Zout + (size_t)row * 1024 + gcol0 + bj * HALF, w, (rowmask & 0x200) != 0);
;                         z0 = (f32x4){bf_lo(w.x), bf_hi(w.x), bf_lo(w.y), bf_hi(w.y)}; z1 = (f32x4){bf_lo(w.z), bf_hi(w.z), bf_lo(w.w), bf_hi(w.w)}; }
;                     s += (z0[0] + z0[1]) + (z0[2] + z0[3]) + (z1[0] + z1[1]) + (z1[2] + z1[3]);
;                     q += (z0[0] * z0[0] + z0[1] * z0[1]) + (z0[2] * z0[2] + z0[3] * z0[3]) + (z1[0] * z1[0] + z1[1] * z1[1]) + (z1[2] * z1[2] + z1[3] * z1[3]); }
;                 s += __shfl_xor(s, 16); s += __shfl_xor(s, 32); q += __shfl_xor(q, 16); q += __shfl_xor(q, 32);
;                 if (fq == 0) { atomicAdd(stats_out + 2 * (size_t)row, s); atomicAdd(stats_out + 2 * (size_t)row + 1, q); } } }
	v_pk_fma_f32 v[26:27], v[26:27], v[54:55], v[38:39]
	v_pk_fma_f32 v[28:29], v[28:29], v[48:49], v[40:41]
	v_pk_fma_f32 v[26:27], v[26:27], s[8:9], v[22:23] op_sel_hi:[1,0,1]
	v_pk_fma_f32 v[28:29], v[28:29], s[8:9], v[24:25] op_sel_hi:[1,0,1]
	ds_read_b128 v[22:25], v229 offset:3600
	v_pk_fma_f32 v[38:39], v[0:1], v[46:47], v[36:37] op_sel_hi:[0,1,0]
	v_pk_fma_f32 v[36:37], v[0:1], v[44:45], v[36:37] op_sel_hi:[0,1,0]
	s_waitcnt lgkmcnt(0)
	v_pk_fma_f32 v[22:23], v[36:37], v[30:31], v[22:23]
	v_pk_fma_f32 v[24:25], v[38:39], v[32:33], v[24:25]
	s_nop 0
	v_pk_fma_f32 v[24:25], v[24:25], s[8:9], v[20:21] op_sel_hi:[1,0,1]
	v_pk_fma_f32 v[20:21], v[22:23], s[8:9], v[18:19] op_sel_hi:[1,0,1]
	v_cvt_pk_bf16_f32 v18, v26, v27
	v_cvt_pk_bf16_f32 v19, v28, v29
	s_nop 0
	v_cvt_pk_bf16_f32 v20, v20, v21
	v_cvt_pk_bf16_f32 v21, v24, v25
	global_store_dwordx4 v[42:43], v[18:21], off offset:256
	v_lshlrev_b32_e32 v0, 16, v18
	v_lshlrev_b32_e32 v22, 16, v19
	v_and_b32_e32 v18, 0xffff0000, v18
	v_and_b32_e32 v19, 0xffff0000, v19
	v_add_f32_e32 v25, v0, v18
	v_mul_f32_e32 v18, v18, v18
	v_fmac_f32_e32 v18, v0, v0
	v_mul_f32_e32 v0, v19, v19
	v_lshlrev_b32_e32 v23, 16, v20
	v_and_b32_e32 v20, 0xffff0000, v20
	v_fmac_f32_e32 v0, v22, v22
	v_add_f32_e32 v0, v18, v0
	v_mul_f32_e32 v18, v20, v20
	v_lshlrev_b32_e32 v24, 16, v21
	v_and_b32_e32 v21, 0xffff0000, v21
	v_add_f32_e32 v26, v22, v19
	v_fmac_f32_e32 v18, v23, v23
	v_add_f32_e32 v25, v25, v26
	v_add_f32_e32 v26, v23, v20
	v_add_f32_e32 v0, v0, v18
	v_mul_f32_e32 v18, v21, v21
	v_add_f32_e32 v25, v25, v26
	v_add_f32_e32 v26, v24, v21
	v_fmac_f32_e32 v18, v24, v24
	v_add_f32_e32 v25, v25, v26
	v_add_f32_e32 v0, v0, v18
	v_add_f32_e32 v25, v56, v25
	v_add_f32_e32 v19, v57, v0
	ds_bpermute_b32 v0, v153, v25
	ds_bpermute_b32 v20, v153, v19
	s_waitcnt lgkmcnt(1)
	v_add_f32_e32 v0, v25, v0
	s_waitcnt lgkmcnt(0)
	v_add_f32_e32 v19, v19, v20
	ds_bpermute_b32 v18, v154, v0
	ds_bpermute_b32 v20, v154, v19
	s_mov_b32 s26, -1
	s_mov_b32 s27, 0
	s_and_saveexec_b64 s[26:27], s[26:27]
	s_cbranch_execz .LBB0_999
	v_lshl_add_u64 v[22:23], v[34:35], 3, s[28:29]
	s_waitcnt lgkmcnt(1)
	v_add_f32_e32 v0, v0, v18
	s_waitcnt lgkmcnt(0)
	v_add_f32_e32 v18, v19, v20
	v_cndmask_b32_e64 v20, 4, 0, s[10:11]
	v_cndmask_b32_e64 v0, v18, v0, s[10:11]
	v_or_b32_e32 v22, v22, v20
	global_atomic_add_f32 v[22:23], v0, off
; #define PG8_LAS __attribute__((address_space(3)))
; __device__ __forceinline__ float bf_lo(unsigned w) { return __uint_as_float(w << 16); }
; __device__ __forceinline__ float bf_hi(unsigned w) { return __uint_as_float(w & 0xffff0000u); }
; __device__ __forceinline__ void st16_sel(void* p, u32x4 v, bool wt) { if (wt) st16_wt_e(p, v); else *(u32x4*)p = v; }
;     __device__ __forceinline__ void operator()(const f32x4 (&acc)[2][2][4][2], const Unit& u, int wr, int wc, int fr, int fq, int rowmask, const PG8_LAS unsigned char* ev) const {
;     ...
;             for (int m = 0; m < 4; ++m) { if (!((rowmask >> (ai * 4 + m)) & 1)) continue; const int row = row0 + ai * HALF + m * 16; float rA, rB; ln_row_lds(ev, wr * 64 + fr + ai * HALF + m * 16, rA, rB);
;                 float s = 0.f, q = 0.f;
; #pragma unroll
;                 for (int bj = 0; bj < 2; ++bj) { const u32x4 zr = zpre[ai][m][bj];
;                     f32x4 x0 = {bf_lo(zr.x), bf_hi(zr.x), bf_lo(zr.y), bf_hi(zr.y)}, x1 = {bf_lo(zr.z), bf_hi(zr.z), bf_lo(zr.w), bf_hi(zr.w)};
;                     const PG8_LAS f32x4* kp = (const PG8_LAS f32x4*)(ev + 2048 + (wc * 32 + 8 * fq + bj * HALF) * 4);
;                     f32x4 z0 = ((x0 * rA + rB) * kp[0] + kp[64]) * ALPHA_ + acc[ai][bj][m][0], z1 = ((x1 * rA + rB) * kp[1] + kp[65]) * ALPHA_ + acc[ai][bj][m][1];
;                     if (F32OUT) { if (row < MP_ + NSMP_) { float* p = Fout + (size_t)row * 1024 + gcol0 + bj * HALF; *(f32x4*)p = z0; *(f32x4*)(p + 4) = z1; } }
;                     else { const u32x4 w = pack8(z0, z1); st16_sel(Zout + (size_t)row * 1024 + gcol0 + bj * HALF, w, (rowmask & 0x200) != 0);
;                         z0 = (f32x4){bf_lo(w.x), bf_hi(w.x), bf_lo(w.y), bf_hi(w.y)}; z1 = (f32x4){bf_lo(w.z), bf_hi(w.z), bf_lo(w.w), bf_hi(w.w)}; }
;                     s += (z0[0] + z0[1]) + (z0[2] + z0[3]) + (z1[0] + z1[1]) + (z1[2] + z1[3]);
;                     q += (z0[0] * z0[0] + z0[1] * z0[1]) + (z0[2] * z0[2] + z0[3] * z0[3]) + (z1[0] * z1[0] + z1[1] * z1[1]) + (z1[2] * z1[2] + z1[3] * z1[3]); }
;                 s += __shfl_xor(s, 16); s += __shfl_xor(s, 32); q += __shfl_xor(q, 16); q += __shfl_xor(q, 32);
;                 if (fq == 0) { atomicAdd(stats_out + 2 * (size_t)row, s); atomicAdd(stats_out + 2 * (size_t)row + 1, q); } } }
.LBB0_999:
	s_or_b64 exec, exec, s[26:27]
	s_waitcnt lgkmcnt(0)
	ds_read_b64 v[20:21], v230 offset:1408
	s_waitcnt vmcnt(15)
	v_lshlrev_b32_e32 v22, 16, v62
	v_and_b32_e32 v23, 0xffff0000, v62
	v_lshlrev_b32_e32 v24, 16, v63
	v_and_b32_e32 v25, 0xffff0000, v63
	s_waitcnt lgkmcnt(0)
	v_pk_mul_f32 v[20:21], v[20:21], s[6:7] op_sel_hi:[1,0]
	v_add_u32_e32 v18, 0xb0, v212
	v_fma_f32 v0, -v20, v20, v21
	v_max_f32_e32 v0, 0, v0
	v_add_f32_e32 v0, 0x3727c5ac, v0
	v_rsq_f32_e32 v0, v0
	v_lshlrev_b32_e32 v36, 16, v64
	v_and_b32_e32 v37, 0xffff0000, v64
	v_lshlrev_b32_e32 v38, 16, v65
	v_mul_f32_e64 v20, v20, -v0
	v_pk_fma_f32 v[40:41], v[0:1], v[24:25], v[20:21] op_sel_hi:[0,1,0]
	v_pk_fma_f32 v[42:43], v[0:1], v[22:23], v[20:21] op_sel_hi:[0,1,0]
	ds_read_b128 v[22:25], v229 offset:2048
	ds_read_b128 v[26:29], v229 offset:2064
	ds_read_b128 v[30:33], v229 offset:3072
	v_and_b32_e32 v39, 0xffff0000, v65
	v_ashrrev_i32_e32 v19, 31, v18
	v_lshlrev_b64 v[34:35], 11, v[18:19]
	s_waitcnt lgkmcnt(0)
	v_pk_fma_f32 v[22:23], v[22:23], v[42:43], v[30:31]
	v_pk_fma_f32 v[24:25], v[24:25], v[40:41], v[32:33]
	v_pk_fma_f32 v[22:23], v[22:23], s[8:9], v[14:15] op_sel_hi:[1,0,1]
	v_pk_fma_f32 v[24:25], v[24:25], s[8:9], v[16:17] op_sel_hi:[1,0,1]
	ds_read_b128 v[14:17], v229 offset:3088
	v_pk_fma_f32 v[30:31], v[0:1], v[38:39], v[20:21] op_sel_hi:[0,1,0]
	v_pk_fma_f32 v[32:33], v[0:1], v[36:37], v[20:21] op_sel_hi:[0,1,0]
	s_waitcnt lgkmcnt(0)
	v_pk_fma_f32 v[14:15], v[26:27], v[32:33], v[14:15]
	v_pk_fma_f32 v[16:17], v[28:29], v[30:31], v[16:17]
	s_waitcnt vmcnt(14)
	v_lshlrev_b32_e32 v28, 16, v52
	v_pk_fma_f32 v[16:17], v[16:17], s[8:9], v[12:13] op_sel_hi:[1,0,1]
	v_pk_fma_f32 v[12:13], v[14:15], s[8:9], v[10:11] op_sel_hi:[1,0,1]
	v_lshl_add_u64 v[14:15], s[72:73], 0, v[34:35]
	v_cvt_pk_bf16_f32 v10, v22, v23
	v_cvt_pk_bf16_f32 v11, v24, v25
	v_lshl_add_u64 v[26:27], v[210:211], 1, v[14:15]
	v_cvt_pk_bf16_f32 v12, v12, v13
	v_cvt_pk_bf16_f32 v13, v16, v17
	global_store_dwordx4 v[26:27], v[10:13], off
	v_lshlrev_b32_e32 v14, 16, v10
	v_lshlrev_b32_e32 v15, 16, v11
	v_and_b32_e32 v10, 0xffff0000, v10
	v_and_b32_e32 v11, 0xffff0000, v11
	v_add_f32_e32 v21, v14, v10
	v_add_f32_e32 v22, v15, v11
	v_mul_f32_e32 v10, v10, v10
	v_mul_f32_e32 v11, v11, v11
	v_lshlrev_b32_e32 v16, 16, v12
	v_and_b32_e32 v12, 0xffff0000, v12
	v_fmac_f32_e32 v10, v14, v14
	v_fmac_f32_e32 v11, v15, v15
	v_add_f32_e32 v10, v10, v11
	v_mul_f32_e32 v11, v12, v12
	v_lshlrev_b32_e32 v17, 16, v13
	v_and_b32_e32 v13, 0xffff0000, v13
	v_fmac_f32_e32 v11, v16, v16
	v_add_f32_e32 v21, v21, v22
	v_add_f32_e32 v22, v16, v12
	v_add_f32_e32 v10, v10, v11
	v_mul_f32_e32 v11, v13, v13
	v_add_f32_e32 v21, v21, v22
	v_add_f32_e32 v22, v17, v13
	v_fmac_f32_e32 v11, v17, v17
	v_add_f32_e32 v21, v21, v22
	v_add_f32_e32 v37, v10, v11
	v_lshlrev_b32_e32 v10, 16, v50
	v_and_b32_e32 v11, 0xffff0000, v50
	v_lshlrev_b32_e32 v12, 16, v51
	v_and_b32_e32 v13, 0xffff0000, v51
	v_pk_fma_f32 v[32:33], v[0:1], v[12:13], v[20:21] op_sel_hi:[0,1,0]
	v_pk_fma_f32 v[34:35], v[0:1], v[10:11], v[20:21] op_sel_hi:[0,1,0]
	ds_read_b128 v[10:13], v229 offset:2560
	ds_read_b128 v[14:17], v229 offset:2576
	ds_read_b128 v[22:25], v229 offset:3584
	v_and_b32_e32 v29, 0xffff0000, v52
	v_lshlrev_b32_e32 v30, 16, v53
	v_and_b32_e32 v31, 0xffff0000, v53
	v_add_f32_e32 v36, 0, v21
	s_waitcnt lgkmcnt(0)
	v_pk_fma_f32 v[10:11], v[10:11], v[34:35], v[22:23]
	v_pk_fma_f32 v[12:13], v[12:13], v[32:33], v[24:25]
	v_pk_fma_f32 v[10:11], v[10:11], s[8:9], v[6:7] op_sel_hi:[1,0,1]
	v_pk_fma_f32 v[12:13], v[12:13], s[8:9], v[8:9] op_sel_hi:[1,0,1]
	ds_read_b128 v[6:9], v229 offset:3600
	v_pk_fma_f32 v[22:23], v[0:1], v[30:31], v[20:21] op_sel_hi:[0,1,0]
	v_pk_fma_f32 v[20:21], v[0:1], v[28:29], v[20:21] op_sel_hi:[0,1,0]
	s_waitcnt lgkmcnt(0)
	v_pk_fma_f32 v[6:7], v[20:21], v[14:15], v[6:7]
	v_pk_fma_f32 v[8:9], v[22:23], v[16:17], v[8:9]
	s_nop 0
	v_pk_fma_f32 v[8:9], v[8:9], s[8:9], v[4:5] op_sel_hi:[1,0,1]
	v_pk_fma_f32 v[4:5], v[6:7], s[8:9], v[2:3] op_sel_hi:[1,0,1]
	v_cvt_pk_bf16_f32 v2, v10, v11
	v_cvt_pk_bf16_f32 v3, v12, v13
	s_nop 0
	v_cvt_pk_bf16_f32 v4, v4, v5
	v_cvt_pk_bf16_f32 v5, v8, v9
	global_store_dwordx4 v[26:27], v[2:5], off offset:256
	v_lshlrev_b32_e32 v0, 16, v2
	v_lshlrev_b32_e32 v6, 16, v3
	v_and_b32_e32 v2, 0xffff0000, v2
	v_and_b32_e32 v3, 0xffff0000, v3
	v_add_f32_e32 v9, v0, v2
	v_mul_f32_e32 v2, v2, v2
	v_fmac_f32_e32 v2, v0, v0
	v_mul_f32_e32 v0, v3, v3
	v_lshlrev_b32_e32 v7, 16, v4
	v_and_b32_e32 v4, 0xffff0000, v4
	v_fmac_f32_e32 v0, v6, v6
	v_add_f32_e32 v0, v2, v0
	v_mul_f32_e32 v2, v4, v4
	v_lshlrev_b32_e32 v8, 16, v5
	v_and_b32_e32 v5, 0xffff0000, v5
	v_add_f32_e32 v10, v6, v3
	v_fmac_f32_e32 v2, v7, v7
	v_add_f32_e32 v9, v9, v10
	v_add_f32_e32 v10, v7, v4
	v_add_f32_e32 v0, v0, v2
	v_mul_f32_e32 v2, v5, v5
	v_add_f32_e32 v9, v9, v10
	v_add_f32_e32 v10, v8, v5
	v_fmac_f32_e32 v2, v8, v8
	v_add_f32_e32 v9, v9, v10
	v_add_f32_e32 v0, v0, v2
	v_add_f32_e32 v9, v36, v9
	v_add_f32_e32 v3, v37, v0
	ds_bpermute_b32 v0, v153, v9
	ds_bpermute_b32 v4, v153, v3
	s_waitcnt lgkmcnt(1)
	v_add_f32_e32 v0, v9, v0
	s_waitcnt lgkmcnt(0)
	v_add_f32_e32 v3, v3, v4
	ds_bpermute_b32 v2, v154, v0
	ds_bpermute_b32 v4, v154, v3
	s_mov_b32 s26, -1
	s_mov_b32 s27, 0
	s_and_saveexec_b64 s[26:27], s[26:27]
	s_cbranch_execz .LBB0_1001
	v_lshl_add_u64 v[6:7], v[18:19], 3, s[28:29]
	s_waitcnt lgkmcnt(1)
	v_add_f32_e32 v0, v0, v2
	s_waitcnt lgkmcnt(0)
	v_add_f32_e32 v2, v3, v4
	v_cndmask_b32_e64 v4, 4, 0, s[10:11]
	v_cndmask_b32_e64 v0, v2, v0, s[10:11]
	v_or_b32_e32 v6, v6, v4
	global_atomic_add_f32 v[6:7], v0, off

; #define PG8_LAS __attribute__((address_space(3)))
; __device__ __forceinline__ void ln_row_lds(const PG8_LAS unsigned char* ev, int rl, float& rA, float& rB) {
;     __device__ __forceinline__ void operator()(const f32x4 (&acc)[2][2][4][2], const Unit& u, int wr, int wc, int fr, int fq, int rowmask, const PG8_LAS unsigned char* ev) const {
;     ...
;         const unsigned zoff0 = (unsigned)(row0 * 1024 + gcol0) * 2u;
;         u32x4 zpre[2][4][2];
; #pragma unroll
;         for (int ai = 0; ai < 2; ++ai)
; #pragma unroll
;             for (int m = 0; m < 4; ++m)
; #pragma unroll
;                 for (int bj = 0; bj < 2; ++bj) zpre[ai][m][bj] = ((rowmask >> (ai * 4 + m)) & 1) ? *(const u32x4*)((const char*)Zres + (zoff0 + (unsigned)((ai * HALF + m * 16) * 2048 + bj * HALF * 2))) : (u32x4){0u, 0u, 0u, 0u};
; #pragma unroll
;         for (int ai = 0; ai < 2; ++ai) {
; #pragma unroll
;             for (int m = 0; m < 4; ++m) { if (!((rowmask >> (ai * 4 + m)) & 1)) continue; const int row = row0 + ai * HALF + m * 16; float rA, rB; ln_row_lds(ev, wr * 64 + fr + ai * HALF + m * 16, rA, rB);
;                 float s = 0.f, q = 0.f;
; #pragma unroll
;                 for (int bj = 0; bj < 2; ++bj) { const u32x4 zr = zpre[ai][m][bj];
;                     f32x4 x0 = {bf_lo(zr.x), bf_hi(zr.x), bf_lo(zr.y), bf_hi(zr.y)}, x1 = {bf_lo(zr.z), bf_hi(zr.z), bf_lo(zr.w), bf_hi(zr.w)};
;                     const PG8_LAS f32x4* kp = (const PG8_LAS f32x4*)(ev + 2048 + (wc * 32 + 8 * fq + bj * HALF) * 4);
;                     f32x4 z0 = ((x0 * rA + rB) * kp[0] + kp[64]) * ALPHA_ + acc[ai][bj][m][0], z1 = ((x1 * rA + rB) * kp[1] + kp[65]) * ALPHA_ + acc[ai][bj][m][1];
;                     if (F32OUT) { if (row < MP_ + NSMP_) { float* p = Fout + (size_t)row * 1024 + gcol0 + bj * HALF; *(f32x4*)p = z0; *(f32x4*)(p + 4) = z1; } }
;                     else { const u32x4 w = pack8(z0, z1); st16_sel(Zout + (size_t)row * 1024 + gcol0 + bj * HALF, w, (rowmask & 0x200) != 0);
;                         z0 = (f32x4){bf_lo(w.x), bf_hi(w.x), bf_lo(w.y), bf_hi(w.y)}; z1 = (f32x4){bf_lo(w.z), bf_hi(w.z), bf_lo(w.w), bf_hi(w.w)}; }
;                     s += (z0[0] + z0[1]) + (z0[2] + z0[3]) + (z1[0] + z1[1]) + (z1[2] + z1[3]);
;                     q += (z0[0] * z0[0] + z0[1] * z0[1]) + (z0[2] * z0[2] + z0[3] * z0[3]) + (z1[0] * z1[0] + z1[1] * z1[1]) + (z1[2] * z1[2] + z1[3] * z1[3]); }
.LBB0_1433:
	v_lshl_or_b32 v210, s52, 8, v224
	v_lshl_add_u32 v212, s26, 8, v223
	v_lshlrev_b32_e32 v0, 1, v210
	v_lshl_add_u32 v0, v212, 11, v0
	global_load_dwordx4 v[232:235], v0, s[72:73]
	v_or_b32_e32 v50, 0x100, v0
	global_load_dwordx4 v[186:189], v50, s[72:73]
	v_add_u32_e32 v50, 0x8000, v0
	global_load_dwordx4 v[182:185], v50, s[72:73]
	v_add_u32_e32 v50, 0x8100, v0
	global_load_dwordx4 v[178:181], v50, s[72:73]
	v_add_u32_e32 v50, 0x10000, v0
	global_load_dwordx4 v[174:177], v50, s[72:73]
	v_add_u32_e32 v50, 0x10100, v0
	global_load_dwordx4 v[162:165], v50, s[72:73]
	v_add_u32_e32 v50, 0x18000, v0
	global_load_dwordx4 v[158:161], v50, s[72:73]
	v_add_u32_e32 v50, 0x18100, v0
	global_load_dwordx4 v[146:149], v50, s[72:73]
	v_add_u32_e32 v50, 0x40000, v0
	global_load_dwordx4 v[138:141], v50, s[72:73]
	v_add_u32_e32 v50, 0x40100, v0
	global_load_dwordx4 v[122:125], v50, s[72:73]
	v_add_u32_e32 v50, 0x48000, v0
	global_load_dwordx4 v[114:117], v50, s[72:73]
	v_add_u32_e32 v50, 0x48100, v0
	global_load_dwordx4 v[98:101], v50, s[72:73]
	v_add_u32_e32 v50, 0x50000, v0
	global_load_dwordx4 v[90:93], v50, s[72:73]
	v_add_u32_e32 v50, 0x50100, v0
	global_load_dwordx4 v[74:77], v50, s[72:73]
	v_add_u32_e32 v50, 0x58000, v0
	v_add_u32_e32 v0, 0x58100, v0
	global_load_dwordx4 v[62:65], v50, s[72:73]
	s_lshl_b32 s0, s79, 12
	global_load_dwordx4 v[50:53], v0, s[72:73]
	s_and_b32 s0, s0, 0x1000
	s_add_i32 s0, s0, 0
	s_add_i32 s0, s0, 0x20400
	v_add_u32_e32 v230, s0, v225
	ds_read_b64 v[190:191], v230
	v_add_u32_e32 v229, s0, v226
	v_ashrrev_i32_e32 v213, 31, v212
	v_ashrrev_i32_e32 v211, 31, v210
	s_waitcnt lgkmcnt(0)
	v_pk_mul_f32 v[190:191], v[190:191], s[6:7] op_sel_hi:[1,0]
	s_nop 0
	v_fma_f32 v0, -v190, v190, v191
	v_max_f32_e32 v0, 0, v0
	v_add_f32_e32 v0, 0x3727c5ac, v0
	v_rsq_f32_e32 v0, v0
	s_waitcnt vmcnt(15)
	v_lshlrev_b32_e32 v216, 16, v232
	v_mul_f32_e64 v214, v190, -v0
	v_and_b32_e32 v217, 0xffff0000, v232
	v_lshlrev_b32_e32 v232, 16, v233
	v_and_b32_e32 v233, 0xffff0000, v233
	v_lshlrev_b32_e32 v244, 16, v234
	v_and_b32_e32 v245, 0xffff0000, v234
	v_lshlrev_b32_e32 v246, 16, v235
	v_and_b32_e32 v247, 0xffff0000, v235
	v_pk_fma_f32 v[248:249], v[0:1], v[232:233], v[214:215] op_sel_hi:[0,1,0]
	ds_read_b128 v[232:235], v229 offset:2048
	ds_read_b128 v[236:239], v229 offset:2064
	ds_read_b128 v[240:243], v229 offset:3072
	v_pk_fma_f32 v[216:217], v[0:1], v[216:217], v[214:215] op_sel_hi:[0,1,0]
	v_lshlrev_b64 v[190:191], 11, v[212:213]
	s_waitcnt lgkmcnt(0)
	v_pk_fma_f32 v[216:217], v[232:233], v[216:217], v[240:241]
	v_pk_fma_f32 v[232:233], v[234:235], v[248:249], v[242:243]
	v_pk_fma_f32 v[216:217], v[216:217], s[8:9], v[170:171] op_sel_hi:[1,0,1]
	v_pk_fma_f32 v[232:233], v[232:233], s[8:9], v[172:173] op_sel_hi:[1,0,1]
	ds_read_b128 v[170:173], v229 offset:3088
	v_pk_fma_f32 v[234:235], v[0:1], v[246:247], v[214:215] op_sel_hi:[0,1,0]
	v_pk_fma_f32 v[240:241], v[0:1], v[244:245], v[214:215] op_sel_hi:[0,1,0]
	s_waitcnt lgkmcnt(0)
	v_pk_fma_f32 v[170:171], v[236:237], v[240:241], v[170:171]
	v_pk_fma_f32 v[172:173], v[238:239], v[234:235], v[172:173]
	s_nop 0
	v_pk_fma_f32 v[172:173], v[172:173], s[8:9], v[168:169] op_sel_hi:[1,0,1]
	v_pk_fma_f32 v[168:169], v[170:171], s[8:9], v[166:167] op_sel_hi:[1,0,1]
	v_lshl_add_u64 v[170:171], s[70:71], 0, v[190:191]
	v_cvt_pk_bf16_f32 v166, v216, v217
	v_cvt_pk_bf16_f32 v167, v232, v233
	v_lshl_add_u64 v[170:171], v[210:211], 1, v[170:171]
	v_cvt_pk_bf16_f32 v168, v168, v169
	v_cvt_pk_bf16_f32 v169, v172, v173
	global_store_dwordx4 v[170:171], v[166:169], off
	v_lshlrev_b32_e32 v172, 16, v166
	v_lshlrev_b32_e32 v173, 16, v167
	v_and_b32_e32 v166, 0xffff0000, v166
	v_and_b32_e32 v167, 0xffff0000, v167
	v_add_f32_e32 v216, v172, v166
	v_add_f32_e32 v217, v173, v167
	v_mul_f32_e32 v166, v166, v166
	v_mul_f32_e32 v167, v167, v167
	v_lshlrev_b32_e32 v190, 16, v168
	v_and_b32_e32 v168, 0xffff0000, v168
	v_fmac_f32_e32 v166, v172, v172
	v_fmac_f32_e32 v167, v173, v173
	v_add_f32_e32 v166, v166, v167
	v_mul_f32_e32 v167, v168, v168
	v_lshlrev_b32_e32 v191, 16, v169
	v_and_b32_e32 v169, 0xffff0000, v169
	v_fmac_f32_e32 v167, v190, v190
	v_add_f32_e32 v216, v216, v217
	v_add_f32_e32 v217, v190, v168
	v_add_f32_e32 v166, v166, v167
	v_mul_f32_e32 v167, v169, v169
	v_add_f32_e32 v216, v216, v217
	v_add_f32_e32 v217, v191, v169
	v_fmac_f32_e32 v167, v191, v191
	v_add_f32_e32 v216, v216, v217
	v_add_f32_e32 v238, v166, v167
	s_waitcnt vmcnt(15)
	v_lshlrev_b32_e32 v166, 16, v186
	v_and_b32_e32 v167, 0xffff0000, v186
	v_lshlrev_b32_e32 v168, 16, v187
	v_and_b32_e32 v169, 0xffff0000, v187
	v_add_f32_e32 v231, 0, v216
	v_lshlrev_b32_e32 v172, 16, v188
	v_and_b32_e32 v173, 0xffff0000, v188
	v_lshlrev_b32_e32 v190, 16, v189
	v_and_b32_e32 v191, 0xffff0000, v189
	v_pk_fma_f32 v[216:217], v[0:1], v[168:169], v[214:215] op_sel_hi:[0,1,0]
	v_pk_fma_f32 v[236:237], v[0:1], v[166:167], v[214:215] op_sel_hi:[0,1,0]
	ds_read_b128 v[166:169], v229 offset:2560
	ds_read_b128 v[186:189], v229 offset:2576
	ds_read_b128 v[232:235], v229 offset:3584
	v_pk_fma_f32 v[190:191], v[0:1], v[190:191], v[214:215] op_sel_hi:[0,1,0]
	v_pk_fma_f32 v[172:173], v[0:1], v[172:173], v[214:215] op_sel_hi:[0,1,0]
	s_waitcnt lgkmcnt(0)
	v_pk_fma_f32 v[166:167], v[166:167], v[236:237], v[232:233]
	v_pk_fma_f32 v[168:169], v[168:169], v[216:217], v[234:235]
	v_pk_fma_f32 v[166:167], v[166:167], s[8:9], v[154:155] op_sel_hi:[1,0,1]
	v_pk_fma_f32 v[168:169], v[168:169], s[8:9], v[156:157] op_sel_hi:[1,0,1]
	ds_read_b128 v[154:157], v229 offset:3600
	s_waitcnt lgkmcnt(0)
; #define PG8_LAS __attribute__((address_space(3)))
; __device__ __forceinline__ float bf_lo(unsigned w) { return __uint_as_float(w << 16); }
; __device__ __forceinline__ float bf_hi(unsigned w) { return __uint_as_float(w & 0xffff0000u); }
; __device__ __forceinline__ void st16_sel(void* p, u32x4 v, bool wt) { if (wt) st16_wt_e(p, v); else *(u32x4*)p = v; }
;     __device__ __forceinline__ void operator()(const f32x4 (&acc)[2][2][4][2], const Unit& u, int wr, int wc, int fr, int fq, int rowmask, const PG8_LAS unsigned char* ev) const {
;     ...
;             for (int m = 0; m < 4; ++m) { if (!((rowmask >> (ai * 4 + m)) & 1)) continue; const int row = row0 + ai * HALF + m * 16; float rA, rB; ln_row_lds(ev, wr * 64 + fr + ai * HALF + m * 16, rA, rB);
;                 float s = 0.f, q = 0.f;
; #pragma unroll
;                 for (int bj = 0; bj < 2; ++bj) { const u32x4 zr = zpre[ai][m][bj];
;                     f32x4 x0 = {bf_lo(zr.x), bf_hi(zr.x), bf_lo(zr.y), bf_hi(zr.y)}, x1 = {bf_lo(zr.z), bf_hi(zr.z), bf_lo(zr.w), bf_hi(zr.w)};
;                     const PG8_LAS f32x4* kp = (const PG8_LAS f32x4*)(ev + 2048 + (wc * 32 + 8 * fq + bj * HALF) * 4);
;                     f32x4 z0 = ((x0 * rA + rB) * kp[0] + kp[64]) * ALPHA_ + acc[ai][bj][m][0], z1 = ((x1 * rA + rB) * kp[1] + kp[65]) * ALPHA_ + acc[ai][bj][m][1];
;                     if (F32OUT) { if (row < MP_ + NSMP_) { float* p = Fout + (size_t)row * 1024 + gcol0 + bj * HALF; *(f32x4*)p = z0; *(f32x4*)(p + 4) = z1; } }
;                     else { const u32x4 w = pack8(z0, z1); st16_sel(Zout + (size_t)row * 1024 + gcol0 + bj * HALF, w, (rowmask & 0x200) != 0);
;                         z0 = (f32x4){bf_lo(w.x), bf_hi(w.x), bf_lo(w.y), bf_hi(w.y)}; z1 = (f32x4){bf_lo(w.z), bf_hi(w.z), bf_lo(w.w), bf_hi(w.w)}; }
;                     s += (z0[0] + z0[1]) + (z0[2] + z0[3]) + (z1[0] + z1[1]) + (z1[2] + z1[3]);
;                     q += (z0[0] * z0[0] + z0[1] * z0[1]) + (z0[2] * z0[2] + z0[3] * z0[3]) + (z1[0] * z1[0] + z1[1] * z1[1]) + (z1[2] * z1[2] + z1[3] * z1[3]); }
;                 s += __shfl_xor(s, 16); s += __shfl_xor(s, 32); q += __shfl_xor(q, 16); q += __shfl_xor(q, 32);
;                 if (fq == 0) { atomicAdd(stats_out + 2 * (size_t)row, s); atomicAdd(stats_out + 2 * (size_t)row + 1, q); } } }
	v_pk_fma_f32 v[154:155], v[172:173], v[186:187], v[154:155]
	v_pk_fma_f32 v[156:157], v[190:191], v[188:189], v[156:157]
	s_nop 0
	v_pk_fma_f32 v[156:157], v[156:157], s[8:9], v[152:153] op_sel_hi:[1,0,1]
	v_pk_fma_f32 v[152:153], v[154:155], s[8:9], v[150:151] op_sel_hi:[1,0,1]
	v_cvt_pk_bf16_f32 v150, v166, v167
	v_cvt_pk_bf16_f32 v151, v168, v169
	s_nop 0
	v_cvt_pk_bf16_f32 v152, v152, v153
	v_cvt_pk_bf16_f32 v153, v156, v157
	global_store_dwordx4 v[170:171], v[150:153], off offset:256
	v_lshlrev_b32_e32 v0, 16, v150
	v_lshlrev_b32_e32 v154, 16, v151
	v_and_b32_e32 v150, 0xffff0000, v150
	v_and_b32_e32 v151, 0xffff0000, v151
	v_add_f32_e32 v157, v0, v150
	v_mul_f32_e32 v150, v150, v150
	v_fmac_f32_e32 v150, v0, v0
	v_mul_f32_e32 v0, v151, v151
	v_lshlrev_b32_e32 v155, 16, v152
	v_and_b32_e32 v152, 0xffff0000, v152
	v_fmac_f32_e32 v0, v154, v154
	v_add_f32_e32 v0, v150, v0
	v_mul_f32_e32 v150, v152, v152
	v_lshlrev_b32_e32 v156, 16, v153
	v_and_b32_e32 v153, 0xffff0000, v153
	v_fmac_f32_e32 v150, v155, v155
	v_add_f32_e32 v0, v0, v150
	v_mul_f32_e32 v150, v153, v153
	v_fmac_f32_e32 v150, v156, v156
	v_add_f32_e32 v166, v154, v151
	v_add_f32_e32 v0, v0, v150
	v_and_b32_e32 v150, 64, v221
	v_add_f32_e32 v157, v157, v166
	v_add_f32_e32 v166, v155, v152
	v_add_f32_e32 v151, v238, v0
	v_xor_b32_e32 v0, 16, v221
	v_add_u32_e32 v150, 64, v150
	v_add_f32_e32 v157, v157, v166
	v_add_f32_e32 v166, v156, v153
	v_cmp_lt_i32_e32 vcc, v0, v150
	v_add_f32_e32 v157, v157, v166
	v_xor_b32_e32 v152, 32, v221
	v_cndmask_b32_e32 v0, v221, v0, vcc
	v_add_f32_e32 v157, v231, v157
	v_lshlrev_b32_e32 v153, 2, v0
	v_cmp_lt_i32_e32 vcc, v152, v150
	ds_bpermute_b32 v0, v153, v157
	s_waitcnt lgkmcnt(0)
	v_add_f32_e32 v0, v157, v0
	v_cndmask_b32_e32 v150, v221, v152, vcc
	ds_bpermute_b32 v152, v153, v151
	v_lshlrev_b32_e32 v154, 2, v150
	ds_bpermute_b32 v150, v154, v0
	s_waitcnt lgkmcnt(1)
	v_add_f32_e32 v151, v151, v152
	ds_bpermute_b32 v152, v154, v151
	s_mov_b32 s14, -1
	s_mov_b32 s15, 0
	s_and_saveexec_b64 s[14:15], s[14:15]
	s_cbranch_execz .LBB0_1435
	v_lshl_add_u64 v[156:157], v[212:213], 3, s[34:35]
	s_waitcnt lgkmcnt(1)
	v_add_f32_e32 v0, v0, v150
	s_waitcnt lgkmcnt(0)
	v_add_f32_e32 v150, v151, v152
	v_cndmask_b32_e64 v152, 4, 0, s[10:11]
	v_cndmask_b32_e64 v0, v150, v0, s[10:11]
	v_or_b32_e32 v156, v156, v152
	global_atomic_add_f32 v[156:157], v0, off
.LBB0_1435:
	s_or_b64 exec, exec, s[14:15]
	ds_read_b64 v[156:157], v230 offset:128
	s_waitcnt vmcnt(15)
	v_lshlrev_b32_e32 v166, 16, v182
	v_and_b32_e32 v167, 0xffff0000, v182
	v_lshlrev_b32_e32 v168, 16, v183
	v_and_b32_e32 v169, 0xffff0000, v183
	s_waitcnt lgkmcnt(0)
	v_pk_mul_f32 v[156:157], v[156:157], s[6:7] op_sel_hi:[1,0]
	v_lshlrev_b32_e32 v186, 16, v184
	v_fma_f32 v0, -v156, v156, v157
	v_max_f32_e32 v0, 0, v0
	v_add_f32_e32 v0, 0x3727c5ac, v0
	v_rsq_f32_e32 v0, v0
	v_and_b32_e32 v187, 0xffff0000, v184
	v_lshlrev_b32_e32 v188, 16, v185
	v_and_b32_e32 v189, 0xffff0000, v185
	v_mul_f32_e64 v152, v156, -v0
	v_pk_fma_f32 v[190:191], v[0:1], v[168:169], v[152:153] op_sel_hi:[0,1,0]
	v_pk_fma_f32 v[216:217], v[0:1], v[166:167], v[152:153] op_sel_hi:[0,1,0]
	ds_read_b128 v[166:169], v229 offset:2048
	ds_read_b128 v[170:173], v229 offset:2064
	ds_read_b128 v[182:185], v229 offset:3072
	v_or_b32_e32 v150, 16, v212
	v_ashrrev_i32_e32 v151, 31, v150
	v_lshlrev_b64 v[156:157], 11, v[150:151]
	s_waitcnt lgkmcnt(0)
	v_pk_fma_f32 v[166:167], v[166:167], v[216:217], v[182:183]
	v_pk_fma_f32 v[168:169], v[168:169], v[190:191], v[184:185]
	v_pk_fma_f32 v[166:167], v[166:167], s[8:9], v[142:143] op_sel_hi:[1,0,1]
	v_pk_fma_f32 v[168:169], v[168:169], s[8:9], v[144:145] op_sel_hi:[1,0,1]
	ds_read_b128 v[142:145], v229 offset:3088
	v_pk_fma_f32 v[182:183], v[0:1], v[188:189], v[152:153] op_sel_hi:[0,1,0]
	v_pk_fma_f32 v[184:185], v[0:1], v[186:187], v[152:153] op_sel_hi:[0,1,0]
	s_waitcnt lgkmcnt(0)
	v_pk_fma_f32 v[142:143], v[170:171], v[184:185], v[142:143]
	v_pk_fma_f32 v[144:145], v[172:173], v[182:183], v[144:145]
	s_waitcnt vmcnt(14)
	v_lshlrev_b32_e32 v170, 16, v180
	v_pk_fma_f32 v[144:145], v[144:145], s[8:9], v[136:137] op_sel_hi:[1,0,1]
	v_pk_fma_f32 v[136:137], v[142:143], s[8:9], v[134:135] op_sel_hi:[1,0,1]
	v_lshl_add_u64 v[142:143], s[70:71], 0, v[156:157]
	v_cvt_pk_bf16_f32 v134, v166, v167
	v_cvt_pk_bf16_f32 v135, v168, v169
	v_lshl_add_u64 v[156:157], v[210:211], 1, v[142:143]
	v_cvt_pk_bf16_f32 v136, v136, v137
	v_cvt_pk_bf16_f32 v137, v144, v145
	global_store_dwordx4 v[156:157], v[134:137], off
	v_lshlrev_b32_e32 v142, 16, v134
	v_lshlrev_b32_e32 v143, 16, v135
	v_and_b32_e32 v134, 0xffff0000, v134
	v_and_b32_e32 v135, 0xffff0000, v135
	v_add_f32_e32 v155, v142, v134
	v_add_f32_e32 v166, v143, v135
	v_mul_f32_e32 v134, v134, v134
	v_mul_f32_e32 v135, v135, v135
	v_lshlrev_b32_e32 v144, 16, v136
	v_and_b32_e32 v136, 0xffff0000, v136
	v_fmac_f32_e32 v134, v142, v142
	v_fmac_f32_e32 v135, v143, v143
	v_add_f32_e32 v134, v134, v135
	v_mul_f32_e32 v135, v136, v136
	v_lshlrev_b32_e32 v145, 16, v137
	v_and_b32_e32 v137, 0xffff0000, v137
	v_fmac_f32_e32 v135, v144, v144
	v_add_f32_e32 v134, v134, v135
	v_mul_f32_e32 v135, v137, v137
	v_add_f32_e32 v155, v155, v166
	v_add_f32_e32 v166, v144, v136
	v_fmac_f32_e32 v135, v145, v145
	v_add_f32_e32 v155, v155, v166
	v_add_f32_e32 v166, v145, v137
	v_add_f32_e32 v182, v134, v135
	v_lshlrev_b32_e32 v134, 16, v178
	v_and_b32_e32 v135, 0xffff0000, v178
	v_lshlrev_b32_e32 v136, 16, v179
	v_and_b32_e32 v137, 0xffff0000, v179
	v_add_f32_e32 v155, v155, v166
	v_and_b32_e32 v171, 0xffff0000, v180
	v_lshlrev_b32_e32 v172, 16, v181
	v_and_b32_e32 v173, 0xffff0000, v181
	v_pk_fma_f32 v[178:179], v[0:1], v[136:137], v[152:153] op_sel_hi:[0,1,0]
	v_pk_fma_f32 v[180:181], v[0:1], v[134:135], v[152:153] op_sel_hi:[0,1,0]
	ds_read_b128 v[134:137], v229 offset:2560
	ds_read_b128 v[142:145], v229 offset:2576
	ds_read_b128 v[166:169], v229 offset:3584
	v_add_f32_e32 v155, 0, v155
	s_waitcnt lgkmcnt(0)
; #define PG8_LAS __attribute__((address_space(3)))
; __device__ __forceinline__ float bf_lo(unsigned w) { return __uint_as_float(w << 16); }
; __device__ __forceinline__ float bf_hi(unsigned w) { return __uint_as_float(w & 0xffff0000u); }
; __device__ __forceinline__ void st16_sel(void* p, u32x4 v, bool wt) { if (wt) st16_wt_e(p, v); else *(u32x4*)p = v; }
;     __device__ __forceinline__ void operator()(const f32x4 (&acc)[2][2][4][2], const Unit& u, int wr, int wc, int fr, int fq, int rowmask, const PG8_LAS unsigned char* ev) const {
;     ...
;             for (int m = 0; m < 4; ++m) { if (!((rowmask >> (ai * 4 + m)) & 1)) continue; const int row = row0 + ai * HALF + m * 16; float rA, rB; ln_row_lds(ev, wr * 64 + fr + ai * HALF + m * 16, rA, rB);
;                 float s = 0.f, q = 0.f;
; #pragma unroll
;                 for (int bj = 0; bj < 2; ++bj) { const u32x4 zr = zpre[ai][m][bj];
;                     f32x4 x0 = {bf_lo(zr.x), bf_hi(zr.x), bf_lo(zr.y), bf_hi(zr.y)}, x1 = {bf_lo(zr.z), bf_hi(zr.z), bf_lo(zr.w), bf_hi(zr.w)};
;                     const PG8_LAS f32x4* kp = (const PG8_LAS f32x4*)(ev + 2048 + (wc * 32 + 8 * fq + bj * HALF) * 4);
;                     f32x4 z0 = ((x0 * rA + rB) * kp[0] + kp[64]) * ALPHA_ + acc[ai][bj][m][0], z1 = ((x1 * rA + rB) * kp[1] + kp[65]) * ALPHA_ + acc[ai][bj][m][1];
;                     if (F32OUT) { if (row < MP_ + NSMP_) { float* p = Fout + (size_t)row * 1024 + gcol0 + bj * HALF; *(f32x4*)p = z0; *(f32x4*)(p + 4) = z1; } }
;                     else { const u32x4 w = pack8(z0, z1); st16_sel(Zout + (size_t)row * 1024 + gcol0 + bj * HALF, w, (rowmask & 0x200) != 0);
;                         z0 = (f32x4){bf_lo(w.x), bf_hi(w.x), bf_lo(w.y), bf_hi(w.y)}; z1 = (f32x4){bf_lo(w.z), bf_hi(w.z), bf_lo(w.w), bf_hi(w.w)}; }
;                     s += (z0[0] + z0[1]) + (z0[2] + z0[3]) + (z1[0] + z1[1]) + (z1[2] + z1[3]);
;                     q += (z0[0] * z0[0] + z0[1] * z0[1]) + (z0[2] * z0[2] + z0[3] * z0[3]) + (z1[0] * z1[0] + z1[1] * z1[1]) + (z1[2] * z1[2] + z1[3] * z1[3]); }
;                 s += __shfl_xor(s, 16); s += __shfl_xor(s, 32); q += __shfl_xor(q, 16); q += __shfl_xor(q, 32);
;                 if (fq == 0) { atomicAdd(stats_out + 2 * (size_t)row, s); atomicAdd(stats_out + 2 * (size_t)row + 1, q); } } }
	v_pk_fma_f32 v[134:135], v[134:135], v[180:181], v[166:167]
	v_pk_fma_f32 v[136:137], v[136:137], v[178:179], v[168:169]
	v_pk_fma_f32 v[134:135], v[134:135], s[8:9], v[130:131] op_sel_hi:[1,0,1]
	v_pk_fma_f32 v[136:137], v[136:137], s[8:9], v[132:133] op_sel_hi:[1,0,1]
	ds_read_b128 v[130:133], v229 offset:3600
	v_pk_fma_f32 v[166:167], v[0:1], v[172:173], v[152:153] op_sel_hi:[0,1,0]
	v_pk_fma_f32 v[168:169], v[0:1], v[170:171], v[152:153] op_sel_hi:[0,1,0]
	s_waitcnt lgkmcnt(0)
	v_pk_fma_f32 v[130:131], v[168:169], v[142:143], v[130:131]
	v_pk_fma_f32 v[132:133], v[166:167], v[144:145], v[132:133]
	s_nop 0
	v_pk_fma_f32 v[132:133], v[132:133], s[8:9], v[128:129] op_sel_hi:[1,0,1]
	v_pk_fma_f32 v[128:129], v[130:131], s[8:9], v[126:127] op_sel_hi:[1,0,1]
	v_cvt_pk_bf16_f32 v126, v134, v135
	v_cvt_pk_bf16_f32 v127, v136, v137
	s_nop 0
	v_cvt_pk_bf16_f32 v128, v128, v129
	v_cvt_pk_bf16_f32 v129, v132, v133
	global_store_dwordx4 v[156:157], v[126:129], off offset:256
	v_lshlrev_b32_e32 v0, 16, v126
	v_lshlrev_b32_e32 v130, 16, v127
	v_and_b32_e32 v126, 0xffff0000, v126
	v_and_b32_e32 v127, 0xffff0000, v127
	v_add_f32_e32 v133, v0, v126
	v_mul_f32_e32 v126, v126, v126
	v_fmac_f32_e32 v126, v0, v0
	v_mul_f32_e32 v0, v127, v127
	v_lshlrev_b32_e32 v131, 16, v128
	v_and_b32_e32 v128, 0xffff0000, v128
	v_fmac_f32_e32 v0, v130, v130
	v_add_f32_e32 v0, v126, v0
	v_mul_f32_e32 v126, v128, v128
	v_lshlrev_b32_e32 v132, 16, v129
	v_and_b32_e32 v129, 0xffff0000, v129
	v_add_f32_e32 v134, v130, v127
	v_fmac_f32_e32 v126, v131, v131
	v_add_f32_e32 v133, v133, v134
	v_add_f32_e32 v134, v131, v128
	v_add_f32_e32 v0, v0, v126
	v_mul_f32_e32 v126, v129, v129
	v_add_f32_e32 v133, v133, v134
	v_add_f32_e32 v134, v132, v129
	v_fmac_f32_e32 v126, v132, v132
	v_add_f32_e32 v133, v133, v134
	v_add_f32_e32 v0, v0, v126
	v_add_f32_e32 v133, v155, v133
	v_add_f32_e32 v127, v182, v0
	ds_bpermute_b32 v0, v153, v133
	ds_bpermute_b32 v128, v153, v127
	s_waitcnt lgkmcnt(1)
	v_add_f32_e32 v0, v133, v0
	s_waitcnt lgkmcnt(0)
	v_add_f32_e32 v127, v127, v128
	ds_bpermute_b32 v126, v154, v0
	ds_bpermute_b32 v128, v154, v127
	s_mov_b32 s14, -1
	s_mov_b32 s15, 0
	s_and_saveexec_b64 s[14:15], s[14:15]
	s_cbranch_execz .LBB0_1437
	v_lshl_add_u64 v[130:131], v[150:151], 3, s[34:35]
	s_waitcnt lgkmcnt(1)
	v_add_f32_e32 v0, v0, v126
	s_waitcnt lgkmcnt(0)
	v_add_f32_e32 v126, v127, v128
	v_cndmask_b32_e64 v128, 4, 0, s[10:11]
	v_cndmask_b32_e64 v0, v126, v0, s[10:11]
	v_or_b32_e32 v130, v130, v128
	global_atomic_add_f32 v[130:131], v0, off
.LBB0_1437:
	s_or_b64 exec, exec, s[14:15]
	s_waitcnt lgkmcnt(0)
	ds_read_b64 v[128:129], v230 offset:256
	s_waitcnt vmcnt(15)
	v_lshlrev_b32_e32 v130, 16, v174
	v_and_b32_e32 v131, 0xffff0000, v174
	v_lshlrev_b32_e32 v132, 16, v175
	v_and_b32_e32 v133, 0xffff0000, v175
	s_waitcnt lgkmcnt(0)
	v_pk_mul_f32 v[128:129], v[128:129], s[6:7] op_sel_hi:[1,0]
	v_or_b32_e32 v126, 32, v212
	v_fma_f32 v0, -v128, v128, v129
	v_max_f32_e32 v0, 0, v0
	v_add_f32_e32 v0, 0x3727c5ac, v0
	v_rsq_f32_e32 v0, v0
	v_lshlrev_b32_e32 v156, 16, v176
	v_and_b32_e32 v157, 0xffff0000, v176
	v_lshlrev_b32_e32 v166, 16, v177
	v_mul_f32_e64 v128, v128, -v0
	v_pk_fma_f32 v[168:169], v[0:1], v[132:133], v[128:129] op_sel_hi:[0,1,0]
	v_pk_fma_f32 v[170:171], v[0:1], v[130:131], v[128:129] op_sel_hi:[0,1,0]
	ds_read_b128 v[130:133], v229 offset:2048
	ds_read_b128 v[134:137], v229 offset:2064
	ds_read_b128 v[142:145], v229 offset:3072
	v_and_b32_e32 v167, 0xffff0000, v177
	v_ashrrev_i32_e32 v127, 31, v126
	v_lshlrev_b64 v[150:151], 11, v[126:127]
	s_waitcnt lgkmcnt(0)
	v_pk_fma_f32 v[130:131], v[130:131], v[170:171], v[142:143]
	v_pk_fma_f32 v[132:133], v[132:133], v[168:169], v[144:145]
	v_pk_fma_f32 v[130:131], v[130:131], s[8:9], v[118:119] op_sel_hi:[1,0,1]
	v_pk_fma_f32 v[132:133], v[132:133], s[8:9], v[120:121] op_sel_hi:[1,0,1]
	ds_read_b128 v[118:121], v229 offset:3088
	v_pk_fma_f32 v[142:143], v[0:1], v[166:167], v[128:129] op_sel_hi:[0,1,0]
	v_pk_fma_f32 v[144:145], v[0:1], v[156:157], v[128:129] op_sel_hi:[0,1,0]
	s_waitcnt lgkmcnt(0)
	v_pk_fma_f32 v[118:119], v[134:135], v[144:145], v[118:119]
	v_pk_fma_f32 v[120:121], v[136:137], v[142:143], v[120:121]
	s_waitcnt vmcnt(14)
	v_lshlrev_b32_e32 v136, 16, v164
	v_pk_fma_f32 v[120:121], v[120:121], s[8:9], v[112:113] op_sel_hi:[1,0,1]
	v_pk_fma_f32 v[112:113], v[118:119], s[8:9], v[110:111] op_sel_hi:[1,0,1]
	v_lshl_add_u64 v[118:119], s[70:71], 0, v[150:151]
	v_cvt_pk_bf16_f32 v110, v130, v131
	v_cvt_pk_bf16_f32 v111, v132, v133
	v_lshl_add_u64 v[134:135], v[210:211], 1, v[118:119]
	v_cvt_pk_bf16_f32 v112, v112, v113
	v_cvt_pk_bf16_f32 v113, v120, v121
	global_store_dwordx4 v[134:135], v[110:113], off
	v_lshlrev_b32_e32 v118, 16, v110
	v_lshlrev_b32_e32 v119, 16, v111
	v_and_b32_e32 v110, 0xffff0000, v110
	v_and_b32_e32 v111, 0xffff0000, v111
	v_add_f32_e32 v129, v118, v110
	v_add_f32_e32 v130, v119, v111
	v_mul_f32_e32 v110, v110, v110
	v_mul_f32_e32 v111, v111, v111
	v_lshlrev_b32_e32 v120, 16, v112
	v_and_b32_e32 v112, 0xffff0000, v112
	v_fmac_f32_e32 v110, v118, v118
	v_fmac_f32_e32 v111, v119, v119
	v_add_f32_e32 v110, v110, v111
	v_mul_f32_e32 v111, v112, v112
	v_lshlrev_b32_e32 v121, 16, v113
	v_and_b32_e32 v113, 0xffff0000, v113
	v_fmac_f32_e32 v111, v120, v120
	v_add_f32_e32 v129, v129, v130
	v_add_f32_e32 v130, v120, v112
	v_add_f32_e32 v110, v110, v111
	v_mul_f32_e32 v111, v113, v113
	v_add_f32_e32 v129, v129, v130
	v_add_f32_e32 v130, v121, v113
	v_fmac_f32_e32 v111, v121, v121
	v_add_f32_e32 v129, v129, v130
	v_add_f32_e32 v155, v110, v111
	v_lshlrev_b32_e32 v110, 16, v162
	v_and_b32_e32 v111, 0xffff0000, v162
	v_lshlrev_b32_e32 v112, 16, v163
	v_and_b32_e32 v113, 0xffff0000, v163
	v_pk_fma_f32 v[144:145], v[0:1], v[112:113], v[128:129] op_sel_hi:[0,1,0]
	v_pk_fma_f32 v[150:151], v[0:1], v[110:111], v[128:129] op_sel_hi:[0,1,0]
	ds_read_b128 v[110:113], v229 offset:2560
	ds_read_b128 v[118:121], v229 offset:2576
	ds_read_b128 v[130:133], v229 offset:3584
	v_and_b32_e32 v137, 0xffff0000, v164
	v_lshlrev_b32_e32 v142, 16, v165
	v_and_b32_e32 v143, 0xffff0000, v165
	v_add_f32_e32 v152, 0, v129
	s_waitcnt lgkmcnt(0)
; #define PG8_LAS __attribute__((address_space(3)))
; __device__ __forceinline__ float bf_lo(unsigned w) { return __uint_as_float(w << 16); }
; __device__ __forceinline__ float bf_hi(unsigned w) { return __uint_as_float(w & 0xffff0000u); }
; __device__ __forceinline__ void st16_sel(void* p, u32x4 v, bool wt) { if (wt) st16_wt_e(p, v); else *(u32x4*)p = v; }
;     __device__ __forceinline__ void operator()(const f32x4 (&acc)[2][2][4][2], const Unit& u, int wr, int wc, int fr, int fq, int rowmask, const PG8_LAS unsigned char* ev) const {
;     ...
;             for (int m = 0; m < 4; ++m) { if (!((rowmask >> (ai * 4 + m)) & 1)) continue; const int row = row0 + ai * HALF + m * 16; float rA, rB; ln_row_lds(ev, wr * 64 + fr + ai * HALF + m * 16, rA, rB);
;                 float s = 0.f, q = 0.f;
; #pragma unroll
;                 for (int bj = 0; bj < 2; ++bj) { const u32x4 zr = zpre[ai][m][bj];
;                     f32x4 x0 = {bf_lo(zr.x), bf_hi(zr.x), bf_lo(zr.y), bf_hi(zr.y)}, x1 = {bf_lo(zr.z), bf_hi(zr.z), bf_lo(zr.w), bf_hi(zr.w)};
;                     const PG8_LAS f32x4* kp = (const PG8_LAS f32x4*)(ev + 2048 + (wc * 32 + 8 * fq + bj * HALF) * 4);
;                     f32x4 z0 = ((x0 * rA + rB) * kp[0] + kp[64]) * ALPHA_ + acc[ai][bj][m][0], z1 = ((x1 * rA + rB) * kp[1] + kp[65]) * ALPHA_ + acc[ai][bj][m][1];
;                     if (F32OUT) { if (row < MP_ + NSMP_) { float* p = Fout + (size_t)row * 1024 + gcol0 + bj * HALF; *(f32x4*)p = z0; *(f32x4*)(p + 4) = z1; } }
;                     else { const u32x4 w = pack8(z0, z1); st16_sel(Zout + (size_t)row * 1024 + gcol0 + bj * HALF, w, (rowmask & 0x200) != 0);
;                         z0 = (f32x4){bf_lo(w.x), bf_hi(w.x), bf_lo(w.y), bf_hi(w.y)}; z1 = (f32x4){bf_lo(w.z), bf_hi(w.z), bf_lo(w.w), bf_hi(w.w)}; }
;                     s += (z0[0] + z0[1]) + (z0[2] + z0[3]) + (z1[0] + z1[1]) + (z1[2] + z1[3]);
;                     q += (z0[0] * z0[0] + z0[1] * z0[1]) + (z0[2] * z0[2] + z0[3] * z0[3]) + (z1[0] * z1[0] + z1[1] * z1[1]) + (z1[2] * z1[2] + z1[3] * z1[3]); }
;                 s += __shfl_xor(s, 16); s += __shfl_xor(s, 32); q += __shfl_xor(q, 16); q += __shfl_xor(q, 32);
;                 if (fq == 0) { atomicAdd(stats_out + 2 * (size_t)row, s); atomicAdd(stats_out + 2 * (size_t)row + 1, q); } } }
	v_pk_fma_f32 v[110:111], v[110:111], v[150:151], v[130:131]
	v_pk_fma_f32 v[112:113], v[112:113], v[144:145], v[132:133]
	v_pk_fma_f32 v[110:111], v[110:111], s[8:9], v[106:107] op_sel_hi:[1,0,1]
	v_pk_fma_f32 v[112:113], v[112:113], s[8:9], v[108:109] op_sel_hi:[1,0,1]
	ds_read_b128 v[106:109], v229 offset:3600
	v_pk_fma_f32 v[130:131], v[0:1], v[142:143], v[128:129] op_sel_hi:[0,1,0]
	v_pk_fma_f32 v[128:129], v[0:1], v[136:137], v[128:129] op_sel_hi:[0,1,0]
	s_waitcnt lgkmcnt(0)
	v_pk_fma_f32 v[106:107], v[128:129], v[118:119], v[106:107]
	v_pk_fma_f32 v[108:109], v[130:131], v[120:121], v[108:109]
	s_nop 0
	v_pk_fma_f32 v[108:109], v[108:109], s[8:9], v[104:105] op_sel_hi:[1,0,1]
	v_pk_fma_f32 v[104:105], v[106:107], s[8:9], v[102:103] op_sel_hi:[1,0,1]
	v_cvt_pk_bf16_f32 v102, v110, v111
	v_cvt_pk_bf16_f32 v103, v112, v113
	s_nop 0
	v_cvt_pk_bf16_f32 v104, v104, v105
	v_cvt_pk_bf16_f32 v105, v108, v109
	global_store_dwordx4 v[134:135], v[102:105], off offset:256
	v_lshlrev_b32_e32 v0, 16, v102
	v_lshlrev_b32_e32 v106, 16, v103
	v_and_b32_e32 v102, 0xffff0000, v102
	v_and_b32_e32 v103, 0xffff0000, v103
	v_add_f32_e32 v109, v0, v102
	v_mul_f32_e32 v102, v102, v102
	v_fmac_f32_e32 v102, v0, v0
	v_mul_f32_e32 v0, v103, v103
	v_lshlrev_b32_e32 v107, 16, v104
	v_and_b32_e32 v104, 0xffff0000, v104
	v_fmac_f32_e32 v0, v106, v106
	v_add_f32_e32 v0, v102, v0
	v_mul_f32_e32 v102, v104, v104
	v_lshlrev_b32_e32 v108, 16, v105
	v_and_b32_e32 v105, 0xffff0000, v105
	v_add_f32_e32 v110, v106, v103
	v_fmac_f32_e32 v102, v107, v107
	v_add_f32_e32 v109, v109, v110
	v_add_f32_e32 v110, v107, v104
	v_add_f32_e32 v0, v0, v102
	v_mul_f32_e32 v102, v105, v105
	v_add_f32_e32 v109, v109, v110
	v_add_f32_e32 v110, v108, v105
	v_fmac_f32_e32 v102, v108, v108
	v_add_f32_e32 v109, v109, v110
	v_add_f32_e32 v0, v0, v102
	v_add_f32_e32 v109, v152, v109
	v_add_f32_e32 v103, v155, v0
	ds_bpermute_b32 v0, v153, v109
	ds_bpermute_b32 v104, v153, v103
	s_waitcnt lgkmcnt(1)
	v_add_f32_e32 v0, v109, v0
	s_waitcnt lgkmcnt(0)
	v_add_f32_e32 v103, v103, v104
	ds_bpermute_b32 v102, v154, v0
	ds_bpermute_b32 v104, v154, v103
	s_mov_b32 s14, -1
	s_mov_b32 s15, 0
	s_and_saveexec_b64 s[14:15], s[14:15]
	s_cbranch_execz .LBB0_1439
	v_lshl_add_u64 v[106:107], v[126:127], 3, s[34:35]
	s_waitcnt lgkmcnt(1)
	v_add_f32_e32 v0, v0, v102
	s_waitcnt lgkmcnt(0)
	v_add_f32_e32 v102, v103, v104
	v_cndmask_b32_e64 v104, 4, 0, s[10:11]
	v_cndmask_b32_e64 v0, v102, v0, s[10:11]
	v_or_b32_e32 v106, v106, v104
	global_atomic_add_f32 v[106:107], v0, off
.LBB0_1439:
	s_or_b64 exec, exec, s[14:15]
	s_waitcnt lgkmcnt(0)
	ds_read_b64 v[104:105], v230 offset:384
	s_waitcnt vmcnt(15)
	v_lshlrev_b32_e32 v106, 16, v158
	v_and_b32_e32 v107, 0xffff0000, v158
	v_lshlrev_b32_e32 v108, 16, v159
	v_and_b32_e32 v109, 0xffff0000, v159
	s_waitcnt lgkmcnt(0)
	v_pk_mul_f32 v[104:105], v[104:105], s[6:7] op_sel_hi:[1,0]
	v_or_b32_e32 v102, 48, v212
	v_fma_f32 v0, -v104, v104, v105
	v_max_f32_e32 v0, 0, v0
	v_add_f32_e32 v0, 0x3727c5ac, v0
	v_rsq_f32_e32 v0, v0
	v_lshlrev_b32_e32 v128, 16, v160
	v_and_b32_e32 v129, 0xffff0000, v160
	v_lshlrev_b32_e32 v130, 16, v161
	v_mul_f32_e64 v104, v104, -v0
	v_pk_fma_f32 v[132:133], v[0:1], v[108:109], v[104:105] op_sel_hi:[0,1,0]
	v_pk_fma_f32 v[134:135], v[0:1], v[106:107], v[104:105] op_sel_hi:[0,1,0]
	ds_read_b128 v[106:109], v229 offset:2048
	ds_read_b128 v[110:113], v229 offset:2064
	ds_read_b128 v[118:121], v229 offset:3072
	v_and_b32_e32 v131, 0xffff0000, v161
	v_ashrrev_i32_e32 v103, 31, v102
	v_lshlrev_b64 v[126:127], 11, v[102:103]
	s_waitcnt lgkmcnt(0)
	v_pk_fma_f32 v[106:107], v[106:107], v[134:135], v[118:119]
	v_pk_fma_f32 v[108:109], v[108:109], v[132:133], v[120:121]
	v_pk_fma_f32 v[106:107], v[106:107], s[8:9], v[94:95] op_sel_hi:[1,0,1]
	v_pk_fma_f32 v[108:109], v[108:109], s[8:9], v[96:97] op_sel_hi:[1,0,1]
	ds_read_b128 v[94:97], v229 offset:3088
	v_pk_fma_f32 v[118:119], v[0:1], v[130:131], v[104:105] op_sel_hi:[0,1,0]
	v_pk_fma_f32 v[120:121], v[0:1], v[128:129], v[104:105] op_sel_hi:[0,1,0]
	s_waitcnt lgkmcnt(0)
	v_pk_fma_f32 v[94:95], v[110:111], v[120:121], v[94:95]
	v_pk_fma_f32 v[96:97], v[112:113], v[118:119], v[96:97]
	s_waitcnt vmcnt(14)
	v_lshlrev_b32_e32 v112, 16, v148
	v_pk_fma_f32 v[96:97], v[96:97], s[8:9], v[88:89] op_sel_hi:[1,0,1]
	v_pk_fma_f32 v[88:89], v[94:95], s[8:9], v[86:87] op_sel_hi:[1,0,1]
	v_lshl_add_u64 v[94:95], s[70:71], 0, v[126:127]
	v_cvt_pk_bf16_f32 v86, v106, v107
	v_cvt_pk_bf16_f32 v87, v108, v109
	v_lshl_add_u64 v[110:111], v[210:211], 1, v[94:95]
	v_cvt_pk_bf16_f32 v88, v88, v89
	v_cvt_pk_bf16_f32 v89, v96, v97
	global_store_dwordx4 v[110:111], v[86:89], off
	v_lshlrev_b32_e32 v94, 16, v86
	v_lshlrev_b32_e32 v95, 16, v87
	v_and_b32_e32 v86, 0xffff0000, v86
	v_and_b32_e32 v87, 0xffff0000, v87
	v_add_f32_e32 v105, v94, v86
	v_add_f32_e32 v106, v95, v87
	v_mul_f32_e32 v86, v86, v86
	v_mul_f32_e32 v87, v87, v87
	v_lshlrev_b32_e32 v96, 16, v88
	v_and_b32_e32 v88, 0xffff0000, v88
	v_fmac_f32_e32 v86, v94, v94
	v_fmac_f32_e32 v87, v95, v95
	v_add_f32_e32 v86, v86, v87
	v_mul_f32_e32 v87, v88, v88
	v_lshlrev_b32_e32 v97, 16, v89
	v_and_b32_e32 v89, 0xffff0000, v89
	v_fmac_f32_e32 v87, v96, v96
	v_add_f32_e32 v105, v105, v106
	v_add_f32_e32 v106, v96, v88
	v_add_f32_e32 v86, v86, v87
	v_mul_f32_e32 v87, v89, v89
	v_add_f32_e32 v105, v105, v106
	v_add_f32_e32 v106, v97, v89
	v_fmac_f32_e32 v87, v97, v97
	v_add_f32_e32 v105, v105, v106
	v_add_f32_e32 v129, v86, v87
	v_lshlrev_b32_e32 v86, 16, v146
	v_and_b32_e32 v87, 0xffff0000, v146
	v_lshlrev_b32_e32 v88, 16, v147
	v_and_b32_e32 v89, 0xffff0000, v147
	v_pk_fma_f32 v[120:121], v[0:1], v[88:89], v[104:105] op_sel_hi:[0,1,0]
	v_pk_fma_f32 v[126:127], v[0:1], v[86:87], v[104:105] op_sel_hi:[0,1,0]
	ds_read_b128 v[86:89], v229 offset:2560
	ds_read_b128 v[94:97], v229 offset:2576
	ds_read_b128 v[106:109], v229 offset:3584
	v_and_b32_e32 v113, 0xffff0000, v148
	v_lshlrev_b32_e32 v118, 16, v149
	v_and_b32_e32 v119, 0xffff0000, v149
	v_add_f32_e32 v128, 0, v105
	s_waitcnt lgkmcnt(0)
; #define PG8_LAS __attribute__((address_space(3)))
; __device__ __forceinline__ float bf_lo(unsigned w) { return __uint_as_float(w << 16); }
; __device__ __forceinline__ float bf_hi(unsigned w) { return __uint_as_float(w & 0xffff0000u); }
; __device__ __forceinline__ void st16_sel(void* p, u32x4 v, bool wt) { if (wt) st16_wt_e(p, v); else *(u32x4*)p = v; }
;     __device__ __forceinline__ void operator()(const f32x4 (&acc)[2][2][4][2], const Unit& u, int wr, int wc, int fr, int fq, int rowmask, const PG8_LAS unsigned char* ev) const {
;     ...
;             for (int m = 0; m < 4; ++m) { if (!((rowmask >> (ai * 4 + m)) & 1)) continue; const int row = row0 + ai * HALF + m * 16; float rA, rB; ln_row_lds(ev, wr * 64 + fr + ai * HALF + m * 16, rA, rB);
;                 float s = 0.f, q = 0.f;
; #pragma unroll
;                 for (int bj = 0; bj < 2; ++bj) { const u32x4 zr = zpre[ai][m][bj];
;                     f32x4 x0 = {bf_lo(zr.x), bf_hi(zr.x), bf_lo(zr.y), bf_hi(zr.y)}, x1 = {bf_lo(zr.z), bf_hi(zr.z), bf_lo(zr.w), bf_hi(zr.w)};
;                     const PG8_LAS f32x4* kp = (const PG8_LAS f32x4*)(ev + 2048 + (wc * 32 + 8 * fq + bj * HALF) * 4);
;                     f32x4 z0 = ((x0 * rA + rB) * kp[0] + kp[64]) * ALPHA_ + acc[ai][bj][m][0], z1 = ((x1 * rA + rB) * kp[1] + kp[65]) * ALPHA_ + acc[ai][bj][m][1];
;                     if (F32OUT) { if (row < MP_ + NSMP_) { float* p = Fout + (size_t)row * 1024 + gcol0 + bj * HALF; *(f32x4*)p = z0; *(f32x4*)(p + 4) = z1; } }
;                     else { const u32x4 w = pack8(z0, z1); st16_sel(Zout + (size_t)row * 1024 + gcol0 + bj * HALF, w, (rowmask & 0x200) != 0);
;                         z0 = (f32x4){bf_lo(w.x), bf_hi(w.x), bf_lo(w.y), bf_hi(w.y)}; z1 = (f32x4){bf_lo(w.z), bf_hi(w.z), bf_lo(w.w), bf_hi(w.w)}; }
;                     s += (z0[0] + z0[1]) + (z0[2] + z0[3]) + (z1[0] + z1[1]) + (z1[2] + z1[3]);
;                     q += (z0[0] * z0[0] + z0[1] * z0[1]) + (z0[2] * z0[2] + z0[3] * z0[3]) + (z1[0] * z1[0] + z1[1] * z1[1]) + (z1[2] * z1[2] + z1[3] * z1[3]); }
;                 s += __shfl_xor(s, 16); s += __shfl_xor(s, 32); q += __shfl_xor(q, 16); q += __shfl_xor(q, 32);
;                 if (fq == 0) { atomicAdd(stats_out + 2 * (size_t)row, s); atomicAdd(stats_out + 2 * (size_t)row + 1, q); } } }
	v_pk_fma_f32 v[86:87], v[86:87], v[126:127], v[106:107]
	v_pk_fma_f32 v[88:89], v[88:89], v[120:121], v[108:109]
	v_pk_fma_f32 v[86:87], v[86:87], s[8:9], v[82:83] op_sel_hi:[1,0,1]
	v_pk_fma_f32 v[88:89], v[88:89], s[8:9], v[84:85] op_sel_hi:[1,0,1]
	ds_read_b128 v[82:85], v229 offset:3600
	v_pk_fma_f32 v[106:107], v[0:1], v[118:119], v[104:105] op_sel_hi:[0,1,0]
	v_pk_fma_f32 v[104:105], v[0:1], v[112:113], v[104:105] op_sel_hi:[0,1,0]
	s_waitcnt lgkmcnt(0)
	v_pk_fma_f32 v[82:83], v[104:105], v[94:95], v[82:83]
	v_pk_fma_f32 v[84:85], v[106:107], v[96:97], v[84:85]
	s_nop 0
	v_pk_fma_f32 v[84:85], v[84:85], s[8:9], v[80:81] op_sel_hi:[1,0,1]
	v_pk_fma_f32 v[80:81], v[82:83], s[8:9], v[78:79] op_sel_hi:[1,0,1]
	v_cvt_pk_bf16_f32 v78, v86, v87
	v_cvt_pk_bf16_f32 v79, v88, v89
	s_nop 0
	v_cvt_pk_bf16_f32 v80, v80, v81
	v_cvt_pk_bf16_f32 v81, v84, v85
	global_store_dwordx4 v[110:111], v[78:81], off offset:256
	v_lshlrev_b32_e32 v0, 16, v78
	v_lshlrev_b32_e32 v82, 16, v79
	v_and_b32_e32 v78, 0xffff0000, v78
	v_and_b32_e32 v79, 0xffff0000, v79
	v_add_f32_e32 v85, v0, v78
	v_mul_f32_e32 v78, v78, v78
	v_fmac_f32_e32 v78, v0, v0
	v_mul_f32_e32 v0, v79, v79
	v_lshlrev_b32_e32 v83, 16, v80
	v_and_b32_e32 v80, 0xffff0000, v80
	v_fmac_f32_e32 v0, v82, v82
	v_add_f32_e32 v0, v78, v0
	v_mul_f32_e32 v78, v80, v80
	v_lshlrev_b32_e32 v84, 16, v81
	v_and_b32_e32 v81, 0xffff0000, v81
	v_add_f32_e32 v86, v82, v79
	v_fmac_f32_e32 v78, v83, v83
	v_add_f32_e32 v85, v85, v86
	v_add_f32_e32 v86, v83, v80
	v_add_f32_e32 v0, v0, v78
	v_mul_f32_e32 v78, v81, v81
	v_add_f32_e32 v85, v85, v86
	v_add_f32_e32 v86, v84, v81
	v_fmac_f32_e32 v78, v84, v84
	v_add_f32_e32 v85, v85, v86
	v_add_f32_e32 v0, v0, v78
	v_add_f32_e32 v85, v128, v85
	v_add_f32_e32 v79, v129, v0
	ds_bpermute_b32 v0, v153, v85
	ds_bpermute_b32 v80, v153, v79
	s_waitcnt lgkmcnt(1)
	v_add_f32_e32 v0, v85, v0
	s_waitcnt lgkmcnt(0)
	v_add_f32_e32 v79, v79, v80
	ds_bpermute_b32 v78, v154, v0
	ds_bpermute_b32 v80, v154, v79
	s_mov_b32 s14, -1
	s_mov_b32 s15, 0
	s_and_saveexec_b64 s[14:15], s[14:15]
	s_cbranch_execz .LBB0_1441
	v_lshl_add_u64 v[82:83], v[102:103], 3, s[34:35]
	s_waitcnt lgkmcnt(1)
	v_add_f32_e32 v0, v0, v78
	s_waitcnt lgkmcnt(0)
	v_add_f32_e32 v78, v79, v80
	v_cndmask_b32_e64 v80, 4, 0, s[10:11]
	v_cndmask_b32_e64 v0, v78, v0, s[10:11]
	v_or_b32_e32 v82, v82, v80
	global_atomic_add_f32 v[82:83], v0, off
.LBB0_1441:
	s_or_b64 exec, exec, s[14:15]
	s_waitcnt lgkmcnt(0)
	ds_read_b64 v[80:81], v230 offset:1024
	s_waitcnt vmcnt(15)
	v_lshlrev_b32_e32 v82, 16, v138
	v_and_b32_e32 v83, 0xffff0000, v138
	v_lshlrev_b32_e32 v84, 16, v139
	v_and_b32_e32 v85, 0xffff0000, v139
	s_waitcnt lgkmcnt(0)
	v_pk_mul_f32 v[80:81], v[80:81], s[6:7] op_sel_hi:[1,0]
	v_add_u32_e32 v78, 0x80, v212
	v_fma_f32 v0, -v80, v80, v81
	v_max_f32_e32 v0, 0, v0
	v_add_f32_e32 v0, 0x3727c5ac, v0
	v_rsq_f32_e32 v0, v0
	v_lshlrev_b32_e32 v104, 16, v140
	v_and_b32_e32 v105, 0xffff0000, v140
	v_lshlrev_b32_e32 v106, 16, v141
	v_mul_f32_e64 v80, v80, -v0
	v_pk_fma_f32 v[108:109], v[0:1], v[84:85], v[80:81] op_sel_hi:[0,1,0]
	v_pk_fma_f32 v[110:111], v[0:1], v[82:83], v[80:81] op_sel_hi:[0,1,0]
	ds_read_b128 v[82:85], v229 offset:2048
	ds_read_b128 v[86:89], v229 offset:2064
	ds_read_b128 v[94:97], v229 offset:3072
	v_and_b32_e32 v107, 0xffff0000, v141
	v_ashrrev_i32_e32 v79, 31, v78
	v_lshlrev_b64 v[102:103], 11, v[78:79]
	s_waitcnt lgkmcnt(0)
	v_pk_fma_f32 v[82:83], v[82:83], v[110:111], v[94:95]
	v_pk_fma_f32 v[84:85], v[84:85], v[108:109], v[96:97]
	v_pk_fma_f32 v[82:83], v[82:83], s[8:9], v[70:71] op_sel_hi:[1,0,1]
	v_pk_fma_f32 v[84:85], v[84:85], s[8:9], v[72:73] op_sel_hi:[1,0,1]
	ds_read_b128 v[70:73], v229 offset:3088
	v_pk_fma_f32 v[94:95], v[0:1], v[106:107], v[80:81] op_sel_hi:[0,1,0]
	v_pk_fma_f32 v[96:97], v[0:1], v[104:105], v[80:81] op_sel_hi:[0,1,0]
	s_waitcnt lgkmcnt(0)
	v_pk_fma_f32 v[70:71], v[86:87], v[96:97], v[70:71]
	v_pk_fma_f32 v[72:73], v[88:89], v[94:95], v[72:73]
	s_waitcnt vmcnt(14)
	v_lshlrev_b32_e32 v88, 16, v124
	v_pk_fma_f32 v[72:73], v[72:73], s[8:9], v[68:69] op_sel_hi:[1,0,1]
	v_pk_fma_f32 v[68:69], v[70:71], s[8:9], v[66:67] op_sel_hi:[1,0,1]
	v_lshl_add_u64 v[70:71], s[70:71], 0, v[102:103]
	v_cvt_pk_bf16_f32 v66, v82, v83
	v_cvt_pk_bf16_f32 v67, v84, v85
	v_lshl_add_u64 v[86:87], v[210:211], 1, v[70:71]
	v_cvt_pk_bf16_f32 v68, v68, v69
	v_cvt_pk_bf16_f32 v69, v72, v73
	global_store_dwordx4 v[86:87], v[66:69], off
	v_lshlrev_b32_e32 v70, 16, v66
	v_lshlrev_b32_e32 v71, 16, v67
	v_and_b32_e32 v66, 0xffff0000, v66
	v_and_b32_e32 v67, 0xffff0000, v67
	v_add_f32_e32 v81, v70, v66
	v_add_f32_e32 v82, v71, v67
	v_mul_f32_e32 v66, v66, v66
	v_mul_f32_e32 v67, v67, v67
	v_lshlrev_b32_e32 v72, 16, v68
	v_and_b32_e32 v68, 0xffff0000, v68
	v_fmac_f32_e32 v66, v70, v70
	v_fmac_f32_e32 v67, v71, v71
	v_add_f32_e32 v66, v66, v67
	v_mul_f32_e32 v67, v68, v68
	v_lshlrev_b32_e32 v73, 16, v69
	v_and_b32_e32 v69, 0xffff0000, v69
	v_fmac_f32_e32 v67, v72, v72
	v_add_f32_e32 v81, v81, v82
	v_add_f32_e32 v82, v72, v68
	v_add_f32_e32 v66, v66, v67
	v_mul_f32_e32 v67, v69, v69
	v_add_f32_e32 v81, v81, v82
	v_add_f32_e32 v82, v73, v69
	v_fmac_f32_e32 v67, v73, v73
	v_add_f32_e32 v81, v81, v82
	v_add_f32_e32 v105, v66, v67
	v_lshlrev_b32_e32 v66, 16, v122
	v_and_b32_e32 v67, 0xffff0000, v122
	v_lshlrev_b32_e32 v68, 16, v123
	v_and_b32_e32 v69, 0xffff0000, v123
	v_pk_fma_f32 v[96:97], v[0:1], v[68:69], v[80:81] op_sel_hi:[0,1,0]
	v_pk_fma_f32 v[102:103], v[0:1], v[66:67], v[80:81] op_sel_hi:[0,1,0]
	ds_read_b128 v[66:69], v229 offset:2560
	ds_read_b128 v[70:73], v229 offset:2576
	ds_read_b128 v[82:85], v229 offset:3584
	v_and_b32_e32 v89, 0xffff0000, v124
	v_lshlrev_b32_e32 v94, 16, v125
	v_and_b32_e32 v95, 0xffff0000, v125
	v_add_f32_e32 v104, 0, v81
	s_waitcnt lgkmcnt(0)
; #define PG8_LAS __attribute__((address_space(3)))
; __device__ __forceinline__ float bf_lo(unsigned w) { return __uint_as_float(w << 16); }
; __device__ __forceinline__ float bf_hi(unsigned w) { return __uint_as_float(w & 0xffff0000u); }
; __device__ __forceinline__ void st16_sel(void* p, u32x4 v, bool wt) { if (wt) st16_wt_e(p, v); else *(u32x4*)p = v; }
;     __device__ __forceinline__ void operator()(const f32x4 (&acc)[2][2][4][2], const Unit& u, int wr, int wc, int fr, int fq, int rowmask, const PG8_LAS unsigned char* ev) const {
;     ...
;             for (int m = 0; m < 4; ++m) { if (!((rowmask >> (ai * 4 + m)) & 1)) continue; const int row = row0 + ai * HALF + m * 16; float rA, rB; ln_row_lds(ev, wr * 64 + fr + ai * HALF + m * 16, rA, rB);
;                 float s = 0.f, q = 0.f;
; #pragma unroll
;                 for (int bj = 0; bj < 2; ++bj) { const u32x4 zr = zpre[ai][m][bj];
;                     f32x4 x0 = {bf_lo(zr.x), bf_hi(zr.x), bf_lo(zr.y), bf_hi(zr.y)}, x1 = {bf_lo(zr.z), bf_hi(zr.z), bf_lo(zr.w), bf_hi(zr.w)};
;                     const PG8_LAS f32x4* kp = (const PG8_LAS f32x4*)(ev + 2048 + (wc * 32 + 8 * fq + bj * HALF) * 4);
;                     f32x4 z0 = ((x0 * rA + rB) * kp[0] + kp[64]) * ALPHA_ + acc[ai][bj][m][0], z1 = ((x1 * rA + rB) * kp[1] + kp[65]) * ALPHA_ + acc[ai][bj][m][1];
;                     if (F32OUT) { if (row < MP_ + NSMP_) { float* p = Fout + (size_t)row * 1024 + gcol0 + bj * HALF; *(f32x4*)p = z0; *(f32x4*)(p + 4) = z1; } }
;                     else { const u32x4 w = pack8(z0, z1); st16_sel(Zout + (size_t)row * 1024 + gcol0 + bj * HALF, w, (rowmask & 0x200) != 0);
;                         z0 = (f32x4){bf_lo(w.x), bf_hi(w.x), bf_lo(w.y), bf_hi(w.y)}; z1 = (f32x4){bf_lo(w.z), bf_hi(w.z), bf_lo(w.w), bf_hi(w.w)}; }
;                     s += (z0[0] + z0[1]) + (z0[2] + z0[3]) + (z1[0] + z1[1]) + (z1[2] + z1[3]);
;                     q += (z0[0] * z0[0] + z0[1] * z0[1]) + (z0[2] * z0[2] + z0[3] * z0[3]) + (z1[0] * z1[0] + z1[1] * z1[1]) + (z1[2] * z1[2] + z1[3] * z1[3]); }
;                 s += __shfl_xor(s, 16); s += __shfl_xor(s, 32); q += __shfl_xor(q, 16); q += __shfl_xor(q, 32);
;                 if (fq == 0) { atomicAdd(stats_out + 2 * (size_t)row, s); atomicAdd(stats_out + 2 * (size_t)row + 1, q); } } }
	v_pk_fma_f32 v[66:67], v[66:67], v[102:103], v[82:83]
	v_pk_fma_f32 v[68:69], v[68:69], v[96:97], v[84:85]
	v_pk_fma_f32 v[66:67], v[66:67], s[8:9], v[58:59] op_sel_hi:[1,0,1]
	v_pk_fma_f32 v[68:69], v[68:69], s[8:9], v[60:61] op_sel_hi:[1,0,1]
	ds_read_b128 v[58:61], v229 offset:3600
	v_pk_fma_f32 v[82:83], v[0:1], v[94:95], v[80:81] op_sel_hi:[0,1,0]
	v_pk_fma_f32 v[80:81], v[0:1], v[88:89], v[80:81] op_sel_hi:[0,1,0]
	s_waitcnt lgkmcnt(0)
	v_pk_fma_f32 v[58:59], v[80:81], v[70:71], v[58:59]
	v_pk_fma_f32 v[60:61], v[82:83], v[72:73], v[60:61]
	s_nop 0
	v_pk_fma_f32 v[60:61], v[60:61], s[8:9], v[56:57] op_sel_hi:[1,0,1]
	v_pk_fma_f32 v[56:57], v[58:59], s[8:9], v[54:55] op_sel_hi:[1,0,1]
	v_cvt_pk_bf16_f32 v54, v66, v67
	v_cvt_pk_bf16_f32 v55, v68, v69
	s_nop 0
	v_cvt_pk_bf16_f32 v56, v56, v57
	v_cvt_pk_bf16_f32 v57, v60, v61
	global_store_dwordx4 v[86:87], v[54:57], off offset:256
	v_lshlrev_b32_e32 v0, 16, v54
	v_lshlrev_b32_e32 v58, 16, v55
	v_and_b32_e32 v54, 0xffff0000, v54
	v_and_b32_e32 v55, 0xffff0000, v55
	v_add_f32_e32 v61, v0, v54
	v_mul_f32_e32 v54, v54, v54
	v_fmac_f32_e32 v54, v0, v0
	v_mul_f32_e32 v0, v55, v55
	v_lshlrev_b32_e32 v59, 16, v56
	v_and_b32_e32 v56, 0xffff0000, v56
	v_fmac_f32_e32 v0, v58, v58
	v_add_f32_e32 v0, v54, v0
	v_mul_f32_e32 v54, v56, v56
	v_lshlrev_b32_e32 v60, 16, v57
	v_and_b32_e32 v57, 0xffff0000, v57
	v_add_f32_e32 v66, v58, v55
	v_fmac_f32_e32 v54, v59, v59
	v_add_f32_e32 v61, v61, v66
	v_add_f32_e32 v66, v59, v56
	v_add_f32_e32 v0, v0, v54
	v_mul_f32_e32 v54, v57, v57
	v_add_f32_e32 v61, v61, v66
	v_add_f32_e32 v66, v60, v57
	v_fmac_f32_e32 v54, v60, v60
	v_add_f32_e32 v61, v61, v66
	v_add_f32_e32 v0, v0, v54
	v_add_f32_e32 v61, v104, v61
	v_add_f32_e32 v55, v105, v0
	ds_bpermute_b32 v0, v153, v61
	ds_bpermute_b32 v56, v153, v55
	s_waitcnt lgkmcnt(1)
	v_add_f32_e32 v0, v61, v0
	s_waitcnt lgkmcnt(0)
	v_add_f32_e32 v55, v55, v56
	ds_bpermute_b32 v54, v154, v0
	ds_bpermute_b32 v56, v154, v55
	s_mov_b32 s14, -1
	s_mov_b32 s15, 0
	s_and_saveexec_b64 s[14:15], s[14:15]
	s_cbranch_execz .LBB0_1443
	v_lshl_add_u64 v[58:59], v[78:79], 3, s[34:35]
	s_waitcnt lgkmcnt(1)
	v_add_f32_e32 v0, v0, v54
	s_waitcnt lgkmcnt(0)
	v_add_f32_e32 v54, v55, v56
	v_cndmask_b32_e64 v56, 4, 0, s[10:11]
	v_cndmask_b32_e64 v0, v54, v0, s[10:11]
	v_or_b32_e32 v58, v58, v56
	global_atomic_add_f32 v[58:59], v0, off
.LBB0_1443:
	s_or_b64 exec, exec, s[14:15]
	s_waitcnt lgkmcnt(0)
	ds_read_b64 v[56:57], v230 offset:1152
	s_waitcnt vmcnt(15)
	v_lshlrev_b32_e32 v58, 16, v114
	v_and_b32_e32 v59, 0xffff0000, v114
	v_lshlrev_b32_e32 v60, 16, v115
	v_and_b32_e32 v61, 0xffff0000, v115
	s_waitcnt lgkmcnt(0)
	v_pk_mul_f32 v[56:57], v[56:57], s[6:7] op_sel_hi:[1,0]
	v_add_u32_e32 v54, 0x90, v212
	v_fma_f32 v0, -v56, v56, v57
	v_max_f32_e32 v0, 0, v0
	v_add_f32_e32 v0, 0x3727c5ac, v0
	v_rsq_f32_e32 v0, v0
	v_lshlrev_b32_e32 v80, 16, v116
	v_and_b32_e32 v81, 0xffff0000, v116
	v_lshlrev_b32_e32 v82, 16, v117
	v_mul_f32_e64 v56, v56, -v0
	v_pk_fma_f32 v[84:85], v[0:1], v[60:61], v[56:57] op_sel_hi:[0,1,0]
	v_pk_fma_f32 v[86:87], v[0:1], v[58:59], v[56:57] op_sel_hi:[0,1,0]
	ds_read_b128 v[58:61], v229 offset:2048
	ds_read_b128 v[66:69], v229 offset:2064
	ds_read_b128 v[70:73], v229 offset:3072
	v_and_b32_e32 v83, 0xffff0000, v117
	v_ashrrev_i32_e32 v55, 31, v54
	v_lshlrev_b64 v[78:79], 11, v[54:55]
	s_waitcnt lgkmcnt(0)
	v_pk_fma_f32 v[58:59], v[58:59], v[86:87], v[70:71]
	v_pk_fma_f32 v[60:61], v[60:61], v[84:85], v[72:73]
	v_pk_fma_f32 v[58:59], v[58:59], s[8:9], v[46:47] op_sel_hi:[1,0,1]
	v_pk_fma_f32 v[60:61], v[60:61], s[8:9], v[48:49] op_sel_hi:[1,0,1]
	ds_read_b128 v[46:49], v229 offset:3088
	v_pk_fma_f32 v[70:71], v[0:1], v[82:83], v[56:57] op_sel_hi:[0,1,0]
	v_pk_fma_f32 v[72:73], v[0:1], v[80:81], v[56:57] op_sel_hi:[0,1,0]
	s_waitcnt lgkmcnt(0)
	v_pk_fma_f32 v[46:47], v[66:67], v[72:73], v[46:47]
	v_pk_fma_f32 v[48:49], v[68:69], v[70:71], v[48:49]
	s_waitcnt vmcnt(14)
	v_lshlrev_b32_e32 v68, 16, v100
	v_pk_fma_f32 v[48:49], v[48:49], s[8:9], v[44:45] op_sel_hi:[1,0,1]
	v_pk_fma_f32 v[44:45], v[46:47], s[8:9], v[42:43] op_sel_hi:[1,0,1]
	v_lshl_add_u64 v[46:47], s[70:71], 0, v[78:79]
	v_cvt_pk_bf16_f32 v42, v58, v59
	v_cvt_pk_bf16_f32 v43, v60, v61
	v_lshl_add_u64 v[66:67], v[210:211], 1, v[46:47]
	v_cvt_pk_bf16_f32 v44, v44, v45
	v_cvt_pk_bf16_f32 v45, v48, v49
	global_store_dwordx4 v[66:67], v[42:45], off
	v_lshlrev_b32_e32 v46, 16, v42
	v_lshlrev_b32_e32 v47, 16, v43
	v_and_b32_e32 v42, 0xffff0000, v42
	v_and_b32_e32 v43, 0xffff0000, v43
	v_add_f32_e32 v57, v46, v42
	v_add_f32_e32 v58, v47, v43
	v_mul_f32_e32 v42, v42, v42
	v_mul_f32_e32 v43, v43, v43
	v_lshlrev_b32_e32 v48, 16, v44
	v_and_b32_e32 v44, 0xffff0000, v44
	v_fmac_f32_e32 v42, v46, v46
	v_fmac_f32_e32 v43, v47, v47
	v_add_f32_e32 v42, v42, v43
	v_mul_f32_e32 v43, v44, v44
	v_lshlrev_b32_e32 v49, 16, v45
	v_and_b32_e32 v45, 0xffff0000, v45
	v_fmac_f32_e32 v43, v48, v48
	v_add_f32_e32 v57, v57, v58
	v_add_f32_e32 v58, v48, v44
	v_add_f32_e32 v42, v42, v43
	v_mul_f32_e32 v43, v45, v45
	v_add_f32_e32 v57, v57, v58
	v_add_f32_e32 v58, v49, v45
	v_fmac_f32_e32 v43, v49, v49
	v_add_f32_e32 v57, v57, v58
	v_add_f32_e32 v81, v42, v43
	v_lshlrev_b32_e32 v42, 16, v98
	v_and_b32_e32 v43, 0xffff0000, v98
	v_lshlrev_b32_e32 v44, 16, v99
	v_and_b32_e32 v45, 0xffff0000, v99
	v_pk_fma_f32 v[72:73], v[0:1], v[44:45], v[56:57] op_sel_hi:[0,1,0]
	v_pk_fma_f32 v[78:79], v[0:1], v[42:43], v[56:57] op_sel_hi:[0,1,0]
	ds_read_b128 v[42:45], v229 offset:2560
	ds_read_b128 v[46:49], v229 offset:2576
	ds_read_b128 v[58:61], v229 offset:3584
	v_and_b32_e32 v69, 0xffff0000, v100
	v_lshlrev_b32_e32 v70, 16, v101
	v_and_b32_e32 v71, 0xffff0000, v101
	v_add_f32_e32 v80, 0, v57
	s_waitcnt lgkmcnt(0)
; #define PG8_LAS __attribute__((address_space(3)))
; __device__ __forceinline__ float bf_lo(unsigned w) { return __uint_as_float(w << 16); }
; __device__ __forceinline__ float bf_hi(unsigned w) { return __uint_as_float(w & 0xffff0000u); }
; __device__ __forceinline__ void st16_sel(void* p, u32x4 v, bool wt) { if (wt) st16_wt_e(p, v); else *(u32x4*)p = v; }
;     __device__ __forceinline__ void operator()(const f32x4 (&acc)[2][2][4][2], const Unit& u, int wr, int wc, int fr, int fq, int rowmask, const PG8_LAS unsigned char* ev) const {
;     ...
;             for (int m = 0; m < 4; ++m) { if (!((rowmask >> (ai * 4 + m)) & 1)) continue; const int row = row0 + ai * HALF + m * 16; float rA, rB; ln_row_lds(ev, wr * 64 + fr + ai * HALF + m * 16, rA, rB);
;                 float s = 0.f, q = 0.f;
; #pragma unroll
;                 for (int bj = 0; bj < 2; ++bj) { const u32x4 zr = zpre[ai][m][bj];
;                     f32x4 x0 = {bf_lo(zr.x), bf_hi(zr.x), bf_lo(zr.y), bf_hi(zr.y)}, x1 = {bf_lo(zr.z), bf_hi(zr.z), bf_lo(zr.w), bf_hi(zr.w)};
;                     const PG8_LAS f32x4* kp = (const PG8_LAS f32x4*)(ev + 2048 + (wc * 32 + 8 * fq + bj * HALF) * 4);
;                     f32x4 z0 = ((x0 * rA + rB) * kp[0] + kp[64]) * ALPHA_ + acc[ai][bj][m][0], z1 = ((x1 * rA + rB) * kp[1] + kp[65]) * ALPHA_ + acc[ai][bj][m][1];
;                     if (F32OUT) { if (row < MP_ + NSMP_) { float* p = Fout + (size_t)row * 1024 + gcol0 + bj * HALF; *(f32x4*)p = z0; *(f32x4*)(p + 4) = z1; } }
;                     else { const u32x4 w = pack8(z0, z1); st16_sel(Zout + (size_t)row * 1024 + gcol0 + bj * HALF, w, (rowmask & 0x200) != 0);
;                         z0 = (f32x4){bf_lo(w.x), bf_hi(w.x), bf_lo(w.y), bf_hi(w.y)}; z1 = (f32x4){bf_lo(w.z), bf_hi(w.z), bf_lo(w.w), bf_hi(w.w)}; }
;                     s += (z0[0] + z0[1]) + (z0[2] + z0[3]) + (z1[0] + z1[1]) + (z1[2] + z1[3]);
;                     q += (z0[0] * z0[0] + z0[1] * z0[1]) + (z0[2] * z0[2] + z0[3] * z0[3]) + (z1[0] * z1[0] + z1[1] * z1[1]) + (z1[2] * z1[2] + z1[3] * z1[3]); }
;                 s += __shfl_xor(s, 16); s += __shfl_xor(s, 32); q += __shfl_xor(q, 16); q += __shfl_xor(q, 32);
;                 if (fq == 0) { atomicAdd(stats_out + 2 * (size_t)row, s); atomicAdd(stats_out + 2 * (size_t)row + 1, q); } } }
	v_pk_fma_f32 v[42:43], v[42:43], v[78:79], v[58:59]
	v_pk_fma_f32 v[44:45], v[44:45], v[72:73], v[60:61]
	v_pk_fma_f32 v[42:43], v[42:43], s[8:9], v[38:39] op_sel_hi:[1,0,1]
	v_pk_fma_f32 v[44:45], v[44:45], s[8:9], v[40:41] op_sel_hi:[1,0,1]
	ds_read_b128 v[38:41], v229 offset:3600
	v_pk_fma_f32 v[58:59], v[0:1], v[70:71], v[56:57] op_sel_hi:[0,1,0]
	v_pk_fma_f32 v[56:57], v[0:1], v[68:69], v[56:57] op_sel_hi:[0,1,0]
	s_waitcnt lgkmcnt(0)
	v_pk_fma_f32 v[38:39], v[56:57], v[46:47], v[38:39]
	v_pk_fma_f32 v[40:41], v[58:59], v[48:49], v[40:41]
	s_nop 0
	v_pk_fma_f32 v[40:41], v[40:41], s[8:9], v[36:37] op_sel_hi:[1,0,1]
	v_pk_fma_f32 v[36:37], v[38:39], s[8:9], v[34:35] op_sel_hi:[1,0,1]
	v_cvt_pk_bf16_f32 v34, v42, v43
	v_cvt_pk_bf16_f32 v35, v44, v45
	s_nop 0
	v_cvt_pk_bf16_f32 v36, v36, v37
	v_cvt_pk_bf16_f32 v37, v40, v41
	global_store_dwordx4 v[66:67], v[34:37], off offset:256
	v_lshlrev_b32_e32 v0, 16, v34
	v_lshlrev_b32_e32 v38, 16, v35
	v_and_b32_e32 v34, 0xffff0000, v34
	v_and_b32_e32 v35, 0xffff0000, v35
	v_add_f32_e32 v41, v0, v34
	v_mul_f32_e32 v34, v34, v34
	v_fmac_f32_e32 v34, v0, v0
	v_mul_f32_e32 v0, v35, v35
	v_lshlrev_b32_e32 v39, 16, v36
	v_and_b32_e32 v36, 0xffff0000, v36
	v_fmac_f32_e32 v0, v38, v38
	v_add_f32_e32 v0, v34, v0
	v_mul_f32_e32 v34, v36, v36
	v_lshlrev_b32_e32 v40, 16, v37
	v_and_b32_e32 v37, 0xffff0000, v37
	v_add_f32_e32 v42, v38, v35
	v_fmac_f32_e32 v34, v39, v39
	v_add_f32_e32 v41, v41, v42
	v_add_f32_e32 v42, v39, v36
	v_add_f32_e32 v0, v0, v34
	v_mul_f32_e32 v34, v37, v37
	v_add_f32_e32 v41, v41, v42
	v_add_f32_e32 v42, v40, v37
	v_fmac_f32_e32 v34, v40, v40
	v_add_f32_e32 v41, v41, v42
	v_add_f32_e32 v0, v0, v34
	v_add_f32_e32 v41, v80, v41
	v_add_f32_e32 v35, v81, v0
	ds_bpermute_b32 v0, v153, v41
	ds_bpermute_b32 v36, v153, v35
	s_waitcnt lgkmcnt(1)
	v_add_f32_e32 v0, v41, v0
	s_waitcnt lgkmcnt(0)
	v_add_f32_e32 v35, v35, v36
	ds_bpermute_b32 v34, v154, v0
	ds_bpermute_b32 v36, v154, v35
	s_mov_b32 s14, -1
	s_mov_b32 s15, 0
	s_and_saveexec_b64 s[14:15], s[14:15]
	s_cbranch_execz .LBB0_1445
	v_lshl_add_u64 v[38:39], v[54:55], 3, s[34:35]
	s_waitcnt lgkmcnt(1)
	v_add_f32_e32 v0, v0, v34
	s_waitcnt lgkmcnt(0)
	v_add_f32_e32 v34, v35, v36
	v_cndmask_b32_e64 v36, 4, 0, s[10:11]
	v_cndmask_b32_e64 v0, v34, v0, s[10:11]
	v_or_b32_e32 v38, v38, v36
	global_atomic_add_f32 v[38:39], v0, off
.LBB0_1445:
	s_or_b64 exec, exec, s[14:15]
	s_waitcnt lgkmcnt(0)
	ds_read_b64 v[36:37], v230 offset:1280
	s_waitcnt vmcnt(15)
	v_lshlrev_b32_e32 v38, 16, v90
	v_and_b32_e32 v39, 0xffff0000, v90
	v_lshlrev_b32_e32 v40, 16, v91
	v_and_b32_e32 v41, 0xffff0000, v91
	s_waitcnt lgkmcnt(0)
	v_pk_mul_f32 v[36:37], v[36:37], s[6:7] op_sel_hi:[1,0]
	v_add_u32_e32 v34, 0xa0, v212
	v_fma_f32 v0, -v36, v36, v37
	v_max_f32_e32 v0, 0, v0
	v_add_f32_e32 v0, 0x3727c5ac, v0
	v_rsq_f32_e32 v0, v0
	v_lshlrev_b32_e32 v56, 16, v92
	v_and_b32_e32 v57, 0xffff0000, v92
	v_lshlrev_b32_e32 v58, 16, v93
	v_mul_f32_e64 v36, v36, -v0
	v_pk_fma_f32 v[60:61], v[0:1], v[40:41], v[36:37] op_sel_hi:[0,1,0]
	v_pk_fma_f32 v[66:67], v[0:1], v[38:39], v[36:37] op_sel_hi:[0,1,0]
	ds_read_b128 v[38:41], v229 offset:2048
	ds_read_b128 v[42:45], v229 offset:2064
	ds_read_b128 v[46:49], v229 offset:3072
	v_and_b32_e32 v59, 0xffff0000, v93
	v_ashrrev_i32_e32 v35, 31, v34
	v_lshlrev_b64 v[54:55], 11, v[34:35]
	s_waitcnt lgkmcnt(0)
	v_pk_fma_f32 v[38:39], v[38:39], v[66:67], v[46:47]
	v_pk_fma_f32 v[40:41], v[40:41], v[60:61], v[48:49]
	v_pk_fma_f32 v[38:39], v[38:39], s[8:9], v[30:31] op_sel_hi:[1,0,1]
	v_pk_fma_f32 v[40:41], v[40:41], s[8:9], v[32:33] op_sel_hi:[1,0,1]
	ds_read_b128 v[30:33], v229 offset:3088
	v_pk_fma_f32 v[46:47], v[0:1], v[58:59], v[36:37] op_sel_hi:[0,1,0]
	v_pk_fma_f32 v[48:49], v[0:1], v[56:57], v[36:37] op_sel_hi:[0,1,0]
	s_waitcnt lgkmcnt(0)
	v_pk_fma_f32 v[30:31], v[42:43], v[48:49], v[30:31]
	v_pk_fma_f32 v[32:33], v[44:45], v[46:47], v[32:33]
	s_waitcnt vmcnt(14)
	v_lshlrev_b32_e32 v44, 16, v76
	v_pk_fma_f32 v[32:33], v[32:33], s[8:9], v[28:29] op_sel_hi:[1,0,1]
	v_pk_fma_f32 v[28:29], v[30:31], s[8:9], v[26:27] op_sel_hi:[1,0,1]
	v_lshl_add_u64 v[30:31], s[70:71], 0, v[54:55]
	v_cvt_pk_bf16_f32 v26, v38, v39
	v_cvt_pk_bf16_f32 v27, v40, v41
	v_lshl_add_u64 v[42:43], v[210:211], 1, v[30:31]
	v_cvt_pk_bf16_f32 v28, v28, v29
	v_cvt_pk_bf16_f32 v29, v32, v33
	global_store_dwordx4 v[42:43], v[26:29], off
	v_lshlrev_b32_e32 v30, 16, v26
	v_lshlrev_b32_e32 v31, 16, v27
	v_and_b32_e32 v26, 0xffff0000, v26
	v_and_b32_e32 v27, 0xffff0000, v27
	v_add_f32_e32 v37, v30, v26
	v_add_f32_e32 v38, v31, v27
	v_mul_f32_e32 v26, v26, v26
	v_mul_f32_e32 v27, v27, v27
	v_lshlrev_b32_e32 v32, 16, v28
	v_and_b32_e32 v28, 0xffff0000, v28
	v_fmac_f32_e32 v26, v30, v30
	v_fmac_f32_e32 v27, v31, v31
	v_add_f32_e32 v26, v26, v27
	v_mul_f32_e32 v27, v28, v28
	v_lshlrev_b32_e32 v33, 16, v29
	v_and_b32_e32 v29, 0xffff0000, v29
	v_fmac_f32_e32 v27, v32, v32
	v_add_f32_e32 v37, v37, v38
	v_add_f32_e32 v38, v32, v28
	v_add_f32_e32 v26, v26, v27
	v_mul_f32_e32 v27, v29, v29
	v_add_f32_e32 v37, v37, v38
	v_add_f32_e32 v38, v33, v29
	v_fmac_f32_e32 v27, v33, v33
	v_add_f32_e32 v37, v37, v38
	v_add_f32_e32 v57, v26, v27
	v_lshlrev_b32_e32 v26, 16, v74
	v_and_b32_e32 v27, 0xffff0000, v74
	v_lshlrev_b32_e32 v28, 16, v75
	v_and_b32_e32 v29, 0xffff0000, v75
	v_pk_fma_f32 v[48:49], v[0:1], v[28:29], v[36:37] op_sel_hi:[0,1,0]
	v_pk_fma_f32 v[54:55], v[0:1], v[26:27], v[36:37] op_sel_hi:[0,1,0]
	ds_read_b128 v[26:29], v229 offset:2560
	ds_read_b128 v[30:33], v229 offset:2576
	ds_read_b128 v[38:41], v229 offset:3584
	v_and_b32_e32 v45, 0xffff0000, v76
	v_lshlrev_b32_e32 v46, 16, v77
	v_and_b32_e32 v47, 0xffff0000, v77
	v_add_f32_e32 v56, 0, v37
	s_waitcnt lgkmcnt(0)
; #define PG8_LAS __attribute__((address_space(3)))
; __device__ __forceinline__ float bf_lo(unsigned w) { return __uint_as_float(w << 16); }
; __device__ __forceinline__ float bf_hi(unsigned w) { return __uint_as_float(w & 0xffff0000u); }
; __device__ __forceinline__ void st16_sel(void* p, u32x4 v, bool wt) { if (wt) st16_wt_e(p, v); else *(u32x4*)p = v; }
;     __device__ __forceinline__ void operator()(const f32x4 (&acc)[2][2][4][2], const Unit& u, int wr, int wc, int fr, int fq, int rowmask, const PG8_LAS unsigned char* ev) const {
;     ...
;             for (int m = 0; m < 4; ++m) { if (!((rowmask >> (ai * 4 + m)) & 1)) continue; const int row = row0 + ai * HALF + m * 16; float rA, rB; ln_row_lds(ev, wr * 64 + fr + ai * HALF + m * 16, rA, rB);
;                 float s = 0.f, q = 0.f;
; #pragma unroll
;                 for (int bj = 0; bj < 2; ++bj) { const u32x4 zr = zpre[ai][m][bj];
;                     f32x4 x0 = {bf_lo(zr.x), bf_hi(zr.x), bf_lo(zr.y), bf_hi(zr.y)}, x1 = {bf_lo(zr.z), bf_hi(zr.z), bf_lo(zr.w), bf_hi(zr.w)};
;                     const PG8_LAS f32x4* kp = (const PG8_LAS f32x4*)(ev + 2048 + (wc * 32 + 8 * fq + bj * HALF) * 4);
;                     f32x4 z0 = ((x0 * rA + rB) * kp[0] + kp[64]) * ALPHA_ + acc[ai][bj][m][0], z1 = ((x1 * rA + rB) * kp[1] + kp[65]) * ALPHA_ + acc[ai][bj][m][1];
;                     if (F32OUT) { if (row < MP_ + NSMP_) { float* p = Fout + (size_t)row * 1024 + gcol0 + bj * HALF; *(f32x4*)p = z0; *(f32x4*)(p + 4) = z1; } }
;                     else { const u32x4 w = pack8(z0, z1); st16_sel(Zout + (size_t)row * 1024 + gcol0 + bj * HALF, w, (rowmask & 0x200) != 0);
;                         z0 = (f32x4){bf_lo(w.x), bf_hi(w.x), bf_lo(w.y), bf_hi(w.y)}; z1 = (f32x4){bf_lo(w.z), bf_hi(w.z), bf_lo(w.w), bf_hi(w.w)}; }
;                     s += (z0[0] + z0[1]) + (z0[2] + z0[3]) + (z1[0] + z1[1]) + (z1[2] + z1[3]);
;                     q += (z0[0] * z0[0] + z0[1] * z0[1]) + (z0[2] * z0[2] + z0[3] * z0[3]) + (z1[0] * z1[0] + z1[1] * z1[1]) + (z1[2] * z1[2] + z1[3] * z1[3]); }
;                 s += __shfl_xor(s, 16); s += __shfl_xor(s, 32); q += __shfl_xor(q, 16); q += __shfl_xor(q, 32);
;                 if (fq == 0) { atomicAdd(stats_out + 2 * (size_t)row, s); atomicAdd(stats_out + 2 * (size_t)row + 1, q); } } }
	v_pk_fma_f32 v[26:27], v[26:27], v[54:55], v[38:39]
	v_pk_fma_f32 v[28:29], v[28:29], v[48:49], v[40:41]
	v_pk_fma_f32 v[26:27], v[26:27], s[8:9], v[22:23] op_sel_hi:[1,0,1]
	v_pk_fma_f32 v[28:29], v[28:29], s[8:9], v[24:25] op_sel_hi:[1,0,1]
	ds_read_b128 v[22:25], v229 offset:3600
	v_pk_fma_f32 v[38:39], v[0:1], v[46:47], v[36:37] op_sel_hi:[0,1,0]
	v_pk_fma_f32 v[36:37], v[0:1], v[44:45], v[36:37] op_sel_hi:[0,1,0]
	s_waitcnt lgkmcnt(0)
	v_pk_fma_f32 v[22:23], v[36:37], v[30:31], v[22:23]
	v_pk_fma_f32 v[24:25], v[38:39], v[32:33], v[24:25]
	s_nop 0
	v_pk_fma_f32 v[24:25], v[24:25], s[8:9], v[20:21] op_sel_hi:[1,0,1]
	v_pk_fma_f32 v[20:21], v[22:23], s[8:9], v[18:19] op_sel_hi:[1,0,1]
	v_cvt_pk_bf16_f32 v18, v26, v27
	v_cvt_pk_bf16_f32 v19, v28, v29
	s_nop 0
	v_cvt_pk_bf16_f32 v20, v20, v21
	v_cvt_pk_bf16_f32 v21, v24, v25
	global_store_dwordx4 v[42:43], v[18:21], off offset:256
	v_lshlrev_b32_e32 v0, 16, v18
	v_lshlrev_b32_e32 v22, 16, v19
	v_and_b32_e32 v18, 0xffff0000, v18
	v_and_b32_e32 v19, 0xffff0000, v19
	v_add_f32_e32 v25, v0, v18
	v_mul_f32_e32 v18, v18, v18
	v_fmac_f32_e32 v18, v0, v0
	v_mul_f32_e32 v0, v19, v19
	v_lshlrev_b32_e32 v23, 16, v20
	v_and_b32_e32 v20, 0xffff0000, v20
	v_fmac_f32_e32 v0, v22, v22
	v_add_f32_e32 v0, v18, v0
	v_mul_f32_e32 v18, v20, v20
	v_lshlrev_b32_e32 v24, 16, v21
	v_and_b32_e32 v21, 0xffff0000, v21
	v_add_f32_e32 v26, v22, v19
	v_fmac_f32_e32 v18, v23, v23
	v_add_f32_e32 v25, v25, v26
	v_add_f32_e32 v26, v23, v20
	v_add_f32_e32 v0, v0, v18
	v_mul_f32_e32 v18, v21, v21
	v_add_f32_e32 v25, v25, v26
	v_add_f32_e32 v26, v24, v21
	v_fmac_f32_e32 v18, v24, v24
	v_add_f32_e32 v25, v25, v26
	v_add_f32_e32 v0, v0, v18
	v_add_f32_e32 v25, v56, v25
	v_add_f32_e32 v19, v57, v0
	ds_bpermute_b32 v0, v153, v25
	ds_bpermute_b32 v20, v153, v19
	s_waitcnt lgkmcnt(1)
	v_add_f32_e32 v0, v25, v0
	s_waitcnt lgkmcnt(0)
	v_add_f32_e32 v19, v19, v20
	ds_bpermute_b32 v18, v154, v0
	ds_bpermute_b32 v20, v154, v19
	s_mov_b32 s14, -1
	s_mov_b32 s15, 0
	s_and_saveexec_b64 s[14:15], s[14:15]
	s_cbranch_execz .LBB0_1447
	v_lshl_add_u64 v[22:23], v[34:35], 3, s[34:35]
	s_waitcnt lgkmcnt(1)
	v_add_f32_e32 v0, v0, v18
	s_waitcnt lgkmcnt(0)
	v_add_f32_e32 v18, v19, v20
	v_cndmask_b32_e64 v20, 4, 0, s[10:11]
	v_cndmask_b32_e64 v0, v18, v0, s[10:11]
	v_or_b32_e32 v22, v22, v20
	global_atomic_add_f32 v[22:23], v0, off
; #define PG8_LAS __attribute__((address_space(3)))
; __device__ __forceinline__ float bf_lo(unsigned w) { return __uint_as_float(w << 16); }
; __device__ __forceinline__ float bf_hi(unsigned w) { return __uint_as_float(w & 0xffff0000u); }
; __device__ __forceinline__ void st16_sel(void* p, u32x4 v, bool wt) { if (wt) st16_wt_e(p, v); else *(u32x4*)p = v; }
;     __device__ __forceinline__ void operator()(const f32x4 (&acc)[2][2][4][2], const Unit& u, int wr, int wc, int fr, int fq, int rowmask, const PG8_LAS unsigned char* ev) const {
;     ...
;             for (int m = 0; m < 4; ++m) { if (!((rowmask >> (ai * 4 + m)) & 1)) continue; const int row = row0 + ai * HALF + m * 16; float rA, rB; ln_row_lds(ev, wr * 64 + fr + ai * HALF + m * 16, rA, rB);
;                 float s = 0.f, q = 0.f;
; #pragma unroll
;                 for (int bj = 0; bj < 2; ++bj) { const u32x4 zr = zpre[ai][m][bj];
;                     f32x4 x0 = {bf_lo(zr.x), bf_hi(zr.x), bf_lo(zr.y), bf_hi(zr.y)}, x1 = {bf_lo(zr.z), bf_hi(zr.z), bf_lo(zr.w), bf_hi(zr.w)};
;                     const PG8_LAS f32x4* kp = (const PG8_LAS f32x4*)(ev + 2048 + (wc * 32 + 8 * fq + bj * HALF) * 4);
;                     f32x4 z0 = ((x0 * rA + rB) * kp[0] + kp[64]) * ALPHA_ + acc[ai][bj][m][0], z1 = ((x1 * rA + rB) * kp[1] + kp[65]) * ALPHA_ + acc[ai][bj][m][1];
;                     if (F32OUT) { if (row < MP_ + NSMP_) { float* p = Fout + (size_t)row * 1024 + gcol0 + bj * HALF; *(f32x4*)p = z0; *(f32x4*)(p + 4) = z1; } }
;                     else { const u32x4 w = pack8(z0, z1); st16_sel(Zout + (size_t)row * 1024 + gcol0 + bj * HALF, w, (rowmask & 0x200) != 0);
;                         z0 = (f32x4){bf_lo(w.x), bf_hi(w.x), bf_lo(w.y), bf_hi(w.y)}; z1 = (f32x4){bf_lo(w.z), bf_hi(w.z), bf_lo(w.w), bf_hi(w.w)}; }
;                     s += (z0[0] + z0[1]) + (z0[2] + z0[3]) + (z1[0] + z1[1]) + (z1[2] + z1[3]);
;                     q += (z0[0] * z0[0] + z0[1] * z0[1]) + (z0[2] * z0[2] + z0[3] * z0[3]) + (z1[0] * z1[0] + z1[1] * z1[1]) + (z1[2] * z1[2] + z1[3] * z1[3]); }
;                 s += __shfl_xor(s, 16); s += __shfl_xor(s, 32); q += __shfl_xor(q, 16); q += __shfl_xor(q, 32);
;                 if (fq == 0) { atomicAdd(stats_out + 2 * (size_t)row, s); atomicAdd(stats_out + 2 * (size_t)row + 1, q); } } }
.LBB0_1447:
	s_or_b64 exec, exec, s[14:15]
	s_waitcnt lgkmcnt(0)
	ds_read_b64 v[20:21], v230 offset:1408
	s_waitcnt vmcnt(15)
	v_lshlrev_b32_e32 v22, 16, v62
	v_and_b32_e32 v23, 0xffff0000, v62
	v_lshlrev_b32_e32 v24, 16, v63
	v_and_b32_e32 v25, 0xffff0000, v63
	s_waitcnt lgkmcnt(0)
	v_pk_mul_f32 v[20:21], v[20:21], s[6:7] op_sel_hi:[1,0]
	v_add_u32_e32 v18, 0xb0, v212
	v_fma_f32 v0, -v20, v20, v21
	v_max_f32_e32 v0, 0, v0
	v_add_f32_e32 v0, 0x3727c5ac, v0
	v_rsq_f32_e32 v0, v0
	v_lshlrev_b32_e32 v36, 16, v64
	v_and_b32_e32 v37, 0xffff0000, v64
	v_lshlrev_b32_e32 v38, 16, v65
	v_mul_f32_e64 v20, v20, -v0
	v_pk_fma_f32 v[40:41], v[0:1], v[24:25], v[20:21] op_sel_hi:[0,1,0]
	v_pk_fma_f32 v[42:43], v[0:1], v[22:23], v[20:21] op_sel_hi:[0,1,0]
	ds_read_b128 v[22:25], v229 offset:2048
	ds_read_b128 v[26:29], v229 offset:2064
	ds_read_b128 v[30:33], v229 offset:3072
	v_and_b32_e32 v39, 0xffff0000, v65
	v_ashrrev_i32_e32 v19, 31, v18
	v_lshlrev_b64 v[34:35], 11, v[18:19]
	s_waitcnt lgkmcnt(0)
	v_pk_fma_f32 v[22:23], v[22:23], v[42:43], v[30:31]
	v_pk_fma_f32 v[24:25], v[24:25], v[40:41], v[32:33]
	v_pk_fma_f32 v[22:23], v[22:23], s[8:9], v[14:15] op_sel_hi:[1,0,1]
	v_pk_fma_f32 v[24:25], v[24:25], s[8:9], v[16:17] op_sel_hi:[1,0,1]
	ds_read_b128 v[14:17], v229 offset:3088
	v_pk_fma_f32 v[30:31], v[0:1], v[38:39], v[20:21] op_sel_hi:[0,1,0]
	v_pk_fma_f32 v[32:33], v[0:1], v[36:37], v[20:21] op_sel_hi:[0,1,0]
	s_waitcnt lgkmcnt(0)
	v_pk_fma_f32 v[14:15], v[26:27], v[32:33], v[14:15]
	v_pk_fma_f32 v[16:17], v[28:29], v[30:31], v[16:17]
	s_waitcnt vmcnt(14)
	v_lshlrev_b32_e32 v28, 16, v52
	v_pk_fma_f32 v[16:17], v[16:17], s[8:9], v[12:13] op_sel_hi:[1,0,1]
	v_pk_fma_f32 v[12:13], v[14:15], s[8:9], v[10:11] op_sel_hi:[1,0,1]
	v_lshl_add_u64 v[14:15], s[70:71], 0, v[34:35]
	v_cvt_pk_bf16_f32 v10, v22, v23
	v_cvt_pk_bf16_f32 v11, v24, v25
	v_lshl_add_u64 v[26:27], v[210:211], 1, v[14:15]
	v_cvt_pk_bf16_f32 v12, v12, v13
	v_cvt_pk_bf16_f32 v13, v16, v17
	global_store_dwordx4 v[26:27], v[10:13], off
	v_lshlrev_b32_e32 v14, 16, v10
	v_lshlrev_b32_e32 v15, 16, v11
	v_and_b32_e32 v10, 0xffff0000, v10
	v_and_b32_e32 v11, 0xffff0000, v11
	v_add_f32_e32 v21, v14, v10
	v_add_f32_e32 v22, v15, v11
	v_mul_f32_e32 v10, v10, v10
	v_mul_f32_e32 v11, v11, v11
	v_lshlrev_b32_e32 v16, 16, v12
	v_and_b32_e32 v12, 0xffff0000, v12
	v_fmac_f32_e32 v10, v14, v14
	v_fmac_f32_e32 v11, v15, v15
	v_add_f32_e32 v10, v10, v11
	v_mul_f32_e32 v11, v12, v12
	v_lshlrev_b32_e32 v17, 16, v13
	v_and_b32_e32 v13, 0xffff0000, v13
	v_fmac_f32_e32 v11, v16, v16
	v_add_f32_e32 v21, v21, v22
	v_add_f32_e32 v22, v16, v12
	v_add_f32_e32 v10, v10, v11
	v_mul_f32_e32 v11, v13, v13
	v_add_f32_e32 v21, v21, v22
	v_add_f32_e32 v22, v17, v13
	v_fmac_f32_e32 v11, v17, v17
	v_add_f32_e32 v21, v21, v22
	v_add_f32_e32 v37, v10, v11
	v_lshlrev_b32_e32 v10, 16, v50
	v_and_b32_e32 v11, 0xffff0000, v50
	v_lshlrev_b32_e32 v12, 16, v51
	v_and_b32_e32 v13, 0xffff0000, v51
	v_pk_fma_f32 v[32:33], v[0:1], v[12:13], v[20:21] op_sel_hi:[0,1,0]
	v_pk_fma_f32 v[34:35], v[0:1], v[10:11], v[20:21] op_sel_hi:[0,1,0]
	ds_read_b128 v[10:13], v229 offset:2560
	ds_read_b128 v[14:17], v229 offset:2576
	ds_read_b128 v[22:25], v229 offset:3584
	v_and_b32_e32 v29, 0xffff0000, v52
	v_lshlrev_b32_e32 v30, 16, v53
	v_and_b32_e32 v31, 0xffff0000, v53
	v_add_f32_e32 v36, 0, v21
	s_waitcnt lgkmcnt(0)
	v_pk_fma_f32 v[10:11], v[10:11], v[34:35], v[22:23]
	v_pk_fma_f32 v[12:13], v[12:13], v[32:33], v[24:25]
	v_pk_fma_f32 v[10:11], v[10:11], s[8:9], v[6:7] op_sel_hi:[1,0,1]
	v_pk_fma_f32 v[12:13], v[12:13], s[8:9], v[8:9] op_sel_hi:[1,0,1]
	ds_read_b128 v[6:9], v229 offset:3600
	v_pk_fma_f32 v[22:23], v[0:1], v[30:31], v[20:21] op_sel_hi:[0,1,0]
	v_pk_fma_f32 v[20:21], v[0:1], v[28:29], v[20:21] op_sel_hi:[0,1,0]
	s_waitcnt lgkmcnt(0)
	v_pk_fma_f32 v[6:7], v[20:21], v[14:15], v[6:7]
	v_pk_fma_f32 v[8:9], v[22:23], v[16:17], v[8:9]
	s_nop 0
	v_pk_fma_f32 v[8:9], v[8:9], s[8:9], v[4:5] op_sel_hi:[1,0,1]
	v_pk_fma_f32 v[4:5], v[6:7], s[8:9], v[2:3] op_sel_hi:[1,0,1]
	v_cvt_pk_bf16_f32 v2, v10, v11
	v_cvt_pk_bf16_f32 v3, v12, v13
	s_nop 0
	v_cvt_pk_bf16_f32 v4, v4, v5
	v_cvt_pk_bf16_f32 v5, v8, v9
	global_store_dwordx4 v[26:27], v[2:5], off offset:256
	v_lshlrev_b32_e32 v0, 16, v2
	v_lshlrev_b32_e32 v6, 16, v3
	v_and_b32_e32 v2, 0xffff0000, v2
	v_and_b32_e32 v3, 0xffff0000, v3
	v_add_f32_e32 v9, v0, v2
	v_mul_f32_e32 v2, v2, v2
	v_fmac_f32_e32 v2, v0, v0
	v_mul_f32_e32 v0, v3, v3
	v_lshlrev_b32_e32 v7, 16, v4
	v_and_b32_e32 v4, 0xffff0000, v4
	v_fmac_f32_e32 v0, v6, v6
	v_add_f32_e32 v0, v2, v0
	v_mul_f32_e32 v2, v4, v4
	v_lshlrev_b32_e32 v8, 16, v5
	v_and_b32_e32 v5, 0xffff0000, v5
	v_add_f32_e32 v10, v6, v3
	v_fmac_f32_e32 v2, v7, v7
	v_add_f32_e32 v9, v9, v10
	v_add_f32_e32 v10, v7, v4
	v_add_f32_e32 v0, v0, v2
	v_mul_f32_e32 v2, v5, v5
	v_add_f32_e32 v9, v9, v10
	v_add_f32_e32 v10, v8, v5
	v_fmac_f32_e32 v2, v8, v8
	v_add_f32_e32 v9, v9, v10
	v_add_f32_e32 v0, v0, v2
	v_add_f32_e32 v9, v36, v9
	v_add_f32_e32 v3, v37, v0
	ds_bpermute_b32 v0, v153, v9
	ds_bpermute_b32 v4, v153, v3
	s_waitcnt lgkmcnt(1)
	v_add_f32_e32 v0, v9, v0
	s_waitcnt lgkmcnt(0)
	v_add_f32_e32 v3, v3, v4
	ds_bpermute_b32 v2, v154, v0
	ds_bpermute_b32 v4, v154, v3
	s_mov_b32 s14, -1
	s_mov_b32 s15, 0
	s_and_saveexec_b64 s[14:15], s[14:15]
	s_cbranch_execz .LBB0_1449
	v_lshl_add_u64 v[6:7], v[18:19], 3, s[34:35]
	s_waitcnt lgkmcnt(1)
	v_add_f32_e32 v0, v0, v2
	s_waitcnt lgkmcnt(0)
	v_add_f32_e32 v2, v3, v4
	v_cndmask_b32_e64 v4, 4, 0, s[10:11]
	v_cndmask_b32_e64 v0, v2, v0, s[10:11]
	v_or_b32_e32 v6, v6, v4
	global_atomic_add_f32 v[6:7], v0, off
